# GEMM main loops: s_setprio 1 issued before the pre-burst barrier and s_setprio 0 after the post-burst barrier (off the compute group's critical path)
# speedup vs baseline: 1.0181x; 1.0002x over previous
.LBB0_139:
	v_or_b32_e32 v140, 0x10000, v146
	v_add_u32_e32 v150, 0x10400, v146
	v_add_u32_e32 v154, 0x10800, v146
	v_add_u32_e32 v158, 0x10c00, v146
	ds_read_b128 v[140:143], v140
	ds_read_b128 v[150:153], v150
	ds_read_b128 v[154:157], v154
	ds_read_b128 v[158:161], v158
	s_add_u32 s10, s6, 0xfff80080
	s_addc_u32 s11, s7, -1
	s_cmp_eq_u32 s41, 28
	s_cselect_b32 s11, s63, s11
	s_cselect_b32 s10, s62, s10
	s_cselect_b32 s53, s61, s29
	s_cselect_b32 s52, s60, s28
	s_mov_b32 m0, s12
	v_lshl_add_u64 v[206:207], s[6:7], 0, v[136:137]
	ds_read_b128 v[162:165], v145
	ds_read_b128 v[166:169], v145 offset:1024
	ds_read_b128 v[170:173], v145 offset:2048
	ds_read_b128 v[174:177], v145 offset:3072
	ds_read_b128 v[178:181], v145 offset:4096
	ds_read_b128 v[182:185], v145 offset:5120
	ds_read_b128 v[186:189], v145 offset:6144
	ds_read_b128 v[190:193], v145 offset:7168
	global_load_lds_dwordx4 v[206:207], off
	v_lshl_add_u64 v[206:207], s[6:7], 0, v[138:139]
	s_mov_b32 m0, s78
	s_nop 0
	global_load_lds_dwordx4 v[206:207], off
	s_waitcnt lgkmcnt(8)
	s_setprio 1
	s_barrier
	s_waitcnt lgkmcnt(0)
	v_mfma_f32_16x16x32_bf16 v[126:129], v[140:143], v[162:165], v[126:129]
	v_mfma_f32_16x16x32_bf16 v[122:125], v[154:157], v[162:165], v[122:125]
	v_mfma_f32_16x16x32_bf16 v[118:121], v[140:143], v[170:173], v[118:121]
	v_mfma_f32_16x16x32_bf16 v[110:113], v[154:157], v[170:173], v[110:113]
	v_mfma_f32_16x16x32_bf16 v[102:105], v[140:143], v[178:181], v[102:105]
	v_mfma_f32_16x16x32_bf16 v[94:97], v[154:157], v[178:181], v[94:97]
	v_mfma_f32_16x16x32_bf16 v[86:89], v[140:143], v[186:189], v[86:89]
	v_mfma_f32_16x16x32_bf16 v[78:81], v[154:157], v[186:189], v[78:81]
	v_mfma_f32_16x16x32_bf16 v[126:129], v[150:153], v[166:169], v[126:129]
	v_mfma_f32_16x16x32_bf16 v[122:125], v[158:161], v[166:169], v[122:125]
	v_mfma_f32_16x16x32_bf16 v[118:121], v[150:153], v[174:177], v[118:121]
	v_mfma_f32_16x16x32_bf16 v[110:113], v[158:161], v[174:177], v[110:113]
	v_mfma_f32_16x16x32_bf16 v[102:105], v[150:153], v[182:185], v[102:105]
	v_mfma_f32_16x16x32_bf16 v[94:97], v[158:161], v[182:185], v[94:97]
	v_mfma_f32_16x16x32_bf16 v[86:89], v[150:153], v[190:193], v[86:89]
	v_mfma_f32_16x16x32_bf16 v[78:81], v[158:161], v[190:193], v[78:81]
	s_barrier
	s_setprio 0
	v_or_b32_e32 v197, 0x14000, v146
	s_mov_b32 m0, s83
	v_add_u32_e32 v199, 0x14400, v146
	ds_read_b128 v[206:209], v197
	ds_read_b128 v[210:213], v199
	v_add_u32_e32 v197, 0x14800, v146
	v_lshl_add_u64 v[222:223], s[52:53], 0, v[194:195]
	v_add_u32_e32 v199, 0x14c00, v146
	ds_read_b128 v[214:217], v197
	ds_read_b128 v[218:221], v199
	global_load_lds_dwordx4 v[222:223], off
	v_lshl_add_u64 v[224:225], s[52:53], 0, v[134:135]
	s_mov_b32 m0, s54
	s_nop 0
	global_load_lds_dwordx4 v[224:225], off
	s_setprio 1
	s_barrier
	s_waitcnt lgkmcnt(0)
	v_mfma_f32_16x16x32_bf16 v[114:117], v[206:209], v[162:165], v[114:117]
	v_mfma_f32_16x16x32_bf16 v[106:109], v[214:217], v[162:165], v[106:109]
	v_mfma_f32_16x16x32_bf16 v[98:101], v[206:209], v[170:173], v[98:101]
	v_mfma_f32_16x16x32_bf16 v[90:93], v[214:217], v[170:173], v[90:93]
	v_mfma_f32_16x16x32_bf16 v[82:85], v[206:209], v[178:181], v[82:85]
	v_mfma_f32_16x16x32_bf16 v[74:77], v[214:217], v[178:181], v[74:77]
	v_mfma_f32_16x16x32_bf16 v[70:73], v[206:209], v[186:189], v[70:73]
	v_mfma_f32_16x16x32_bf16 v[66:69], v[214:217], v[186:189], v[66:69]
	v_mfma_f32_16x16x32_bf16 v[114:117], v[210:213], v[166:169], v[114:117]
	v_mfma_f32_16x16x32_bf16 v[106:109], v[218:221], v[166:169], v[106:109]
	v_mfma_f32_16x16x32_bf16 v[98:101], v[210:213], v[174:177], v[98:101]
	v_mfma_f32_16x16x32_bf16 v[90:93], v[218:221], v[174:177], v[90:93]
	v_mfma_f32_16x16x32_bf16 v[82:85], v[210:213], v[182:185], v[82:85]
	v_mfma_f32_16x16x32_bf16 v[74:77], v[218:221], v[182:185], v[74:77]
	s_mov_b32 m0, s55
	v_mfma_f32_16x16x32_bf16 v[70:73], v[210:213], v[190:193], v[70:73]
	v_lshl_add_u64 v[226:227], s[10:11], 0, v[130:131]
	v_mfma_f32_16x16x32_bf16 v[66:69], v[218:221], v[190:193], v[66:69]
	s_barrier
	s_setprio 0
	ds_read_b128 v[162:165], v145 offset:16384
	ds_read_b128 v[166:169], v145 offset:17408
	ds_read_b128 v[170:173], v145 offset:18432
	ds_read_b128 v[174:177], v145 offset:19456
	ds_read_b128 v[178:181], v145 offset:20480
	ds_read_b128 v[182:185], v145 offset:21504
	ds_read_b128 v[186:189], v145 offset:22528
	ds_read_b128 v[190:193], v145 offset:23552
	global_load_lds_dwordx4 v[226:227], off
	v_lshl_add_u64 v[228:229], s[10:11], 0, v[132:133]
	s_mov_b32 m0, s34
	s_nop 0
	global_load_lds_dwordx4 v[228:229], off
	s_setprio 1
	s_barrier
	s_waitcnt lgkmcnt(0)
	v_mfma_f32_16x16x32_bf16 v[62:65], v[140:143], v[162:165], v[62:65]
	v_mfma_f32_16x16x32_bf16 v[58:61], v[154:157], v[162:165], v[58:61]
	v_mfma_f32_16x16x32_bf16 v[54:57], v[140:143], v[170:173], v[54:57]
	v_mfma_f32_16x16x32_bf16 v[46:49], v[154:157], v[170:173], v[46:49]
	v_mfma_f32_16x16x32_bf16 v[38:41], v[140:143], v[178:181], v[38:41]
	v_mfma_f32_16x16x32_bf16 v[30:33], v[154:157], v[178:181], v[30:33]
	v_mfma_f32_16x16x32_bf16 v[22:25], v[140:143], v[186:189], v[22:25]
	v_mfma_f32_16x16x32_bf16 v[14:17], v[154:157], v[186:189], v[14:17]
	v_mfma_f32_16x16x32_bf16 v[62:65], v[150:153], v[166:169], v[62:65]
	v_mfma_f32_16x16x32_bf16 v[58:61], v[158:161], v[166:169], v[58:61]
	v_mfma_f32_16x16x32_bf16 v[54:57], v[150:153], v[174:177], v[54:57]
	v_mfma_f32_16x16x32_bf16 v[46:49], v[158:161], v[174:177], v[46:49]
	v_mfma_f32_16x16x32_bf16 v[38:41], v[150:153], v[182:185], v[38:41]
	v_mfma_f32_16x16x32_bf16 v[30:33], v[158:161], v[182:185], v[30:33]
	v_mfma_f32_16x16x32_bf16 v[22:25], v[150:153], v[190:193], v[22:25]
	v_mfma_f32_16x16x32_bf16 v[14:17], v[158:161], v[190:193], v[14:17]
	s_barrier
	s_setprio 0
	s_add_u32 s58, s52, 0x80000
	s_addc_u32 s59, s53, 0
	s_mov_b32 m0, s4
	v_lshl_add_u64 v[140:141], s[58:59], 0, v[194:195]
	global_load_lds_dwordx4 v[140:141], off
	v_lshl_add_u64 v[140:141], s[58:59], 0, v[134:135]
	s_mov_b32 m0, s5
	s_nop 0
	global_load_lds_dwordx4 v[140:141], off
	s_waitcnt vmcnt(6)
	s_setprio 1
	s_barrier
	v_mfma_f32_16x16x32_bf16 v[50:53], v[206:209], v[162:165], v[50:53]
	v_mfma_f32_16x16x32_bf16 v[42:45], v[214:217], v[162:165], v[42:45]
	v_mfma_f32_16x16x32_bf16 v[34:37], v[206:209], v[170:173], v[34:37]
	v_mfma_f32_16x16x32_bf16 v[26:29], v[214:217], v[170:173], v[26:29]
	v_mfma_f32_16x16x32_bf16 v[18:21], v[206:209], v[178:181], v[18:21]
	v_mfma_f32_16x16x32_bf16 v[10:13], v[214:217], v[178:181], v[10:13]
	v_mfma_f32_16x16x32_bf16 v[6:9], v[206:209], v[186:189], v[6:9]
	v_mfma_f32_16x16x32_bf16 v[2:5], v[214:217], v[186:189], v[2:5]
	v_mfma_f32_16x16x32_bf16 v[50:53], v[210:213], v[166:169], v[50:53]
	v_mfma_f32_16x16x32_bf16 v[42:45], v[218:221], v[166:169], v[42:45]
	v_mfma_f32_16x16x32_bf16 v[34:37], v[210:213], v[174:177], v[34:37]
	v_mfma_f32_16x16x32_bf16 v[26:29], v[218:221], v[174:177], v[26:29]
	v_or_b32_e32 v140, 0x18000, v146
	v_mfma_f32_16x16x32_bf16 v[18:21], v[210:213], v[182:185], v[18:21]
	v_add_u32_e32 v150, 0x18400, v146
	v_mfma_f32_16x16x32_bf16 v[10:13], v[218:221], v[182:185], v[10:13]
	v_add_u32_e32 v154, 0x18800, v146
	v_mfma_f32_16x16x32_bf16 v[6:9], v[210:213], v[190:193], v[6:9]
	v_add_u32_e32 v158, 0x18c00, v146
	v_mfma_f32_16x16x32_bf16 v[2:5], v[218:221], v[190:193], v[2:5]
	s_barrier
	s_setprio 0
	ds_read_b128 v[140:143], v140
	ds_read_b128 v[150:153], v150
	ds_read_b128 v[154:157], v154
	ds_read_b128 v[158:161], v158
	s_add_u32 s10, s10, 0x80000
	s_addc_u32 s11, s11, 0
	s_mov_b32 m0, s56
	v_lshl_add_u64 v[206:207], s[10:11], 0, v[130:131]
	ds_read_b128 v[162:165], v145 offset:32768
	ds_read_b128 v[166:169], v145 offset:33792
	ds_read_b128 v[170:173], v145 offset:34816
	ds_read_b128 v[174:177], v145 offset:35840
	ds_read_b128 v[178:181], v145 offset:36864
	ds_read_b128 v[182:185], v145 offset:37888
	ds_read_b128 v[186:189], v145 offset:38912
	ds_read_b128 v[190:193], v145 offset:39936
	global_load_lds_dwordx4 v[206:207], off
	v_lshl_add_u64 v[206:207], s[10:11], 0, v[132:133]
	s_mov_b32 m0, s57
	s_nop 0
	global_load_lds_dwordx4 v[206:207], off
	s_waitcnt lgkmcnt(8)
	s_setprio 1
	s_barrier
	s_waitcnt lgkmcnt(0)
	v_mfma_f32_16x16x32_bf16 v[126:129], v[140:143], v[162:165], v[126:129]
	v_mfma_f32_16x16x32_bf16 v[122:125], v[154:157], v[162:165], v[122:125]
	v_mfma_f32_16x16x32_bf16 v[118:121], v[140:143], v[170:173], v[118:121]
	v_mfma_f32_16x16x32_bf16 v[110:113], v[154:157], v[170:173], v[110:113]
	v_mfma_f32_16x16x32_bf16 v[102:105], v[140:143], v[178:181], v[102:105]
	v_mfma_f32_16x16x32_bf16 v[94:97], v[154:157], v[178:181], v[94:97]
	v_mfma_f32_16x16x32_bf16 v[86:89], v[140:143], v[186:189], v[86:89]
	v_mfma_f32_16x16x32_bf16 v[78:81], v[154:157], v[186:189], v[78:81]
	v_mfma_f32_16x16x32_bf16 v[126:129], v[150:153], v[166:169], v[126:129]
	v_mfma_f32_16x16x32_bf16 v[122:125], v[158:161], v[166:169], v[122:125]
	v_mfma_f32_16x16x32_bf16 v[118:121], v[150:153], v[174:177], v[118:121]
	v_mfma_f32_16x16x32_bf16 v[110:113], v[158:161], v[174:177], v[110:113]
	v_mfma_f32_16x16x32_bf16 v[102:105], v[150:153], v[182:185], v[102:105]
	v_mfma_f32_16x16x32_bf16 v[94:97], v[158:161], v[182:185], v[94:97]
	v_mfma_f32_16x16x32_bf16 v[86:89], v[150:153], v[190:193], v[86:89]
	v_mfma_f32_16x16x32_bf16 v[78:81], v[158:161], v[190:193], v[78:81]
	s_barrier
	s_setprio 0
	v_or_b32_e32 v197, 0x1c000, v146
	s_mov_b32 m0, s70
	v_add_u32_e32 v199, 0x1c400, v146
	ds_read_b128 v[206:209], v197
	ds_read_b128 v[210:213], v199
	v_add_u32_e32 v197, 0x1c800, v146
	v_lshl_add_u64 v[222:223], v[222:223], 0, s[76:77]
	v_add_u32_e32 v199, 0x1cc00, v146
	ds_read_b128 v[214:217], v197
	ds_read_b128 v[218:221], v199
	global_load_lds_dwordx4 v[222:223], off
	v_lshl_add_u64 v[222:223], v[224:225], 0, s[76:77]
	s_mov_b32 m0, s71
	s_nop 0
	global_load_lds_dwordx4 v[222:223], off
	s_setprio 1
	s_barrier
	s_waitcnt lgkmcnt(0)
	v_mfma_f32_16x16x32_bf16 v[114:117], v[206:209], v[162:165], v[114:117]
	v_mfma_f32_16x16x32_bf16 v[106:109], v[214:217], v[162:165], v[106:109]
	v_mfma_f32_16x16x32_bf16 v[98:101], v[206:209], v[170:173], v[98:101]
	v_mfma_f32_16x16x32_bf16 v[90:93], v[214:217], v[170:173], v[90:93]
	v_mfma_f32_16x16x32_bf16 v[82:85], v[206:209], v[178:181], v[82:85]
	v_mfma_f32_16x16x32_bf16 v[74:77], v[214:217], v[178:181], v[74:77]
	v_mfma_f32_16x16x32_bf16 v[70:73], v[206:209], v[186:189], v[70:73]
	v_mfma_f32_16x16x32_bf16 v[66:69], v[214:217], v[186:189], v[66:69]
	v_mfma_f32_16x16x32_bf16 v[114:117], v[210:213], v[166:169], v[114:117]
	v_mfma_f32_16x16x32_bf16 v[106:109], v[218:221], v[166:169], v[106:109]
	v_mfma_f32_16x16x32_bf16 v[98:101], v[210:213], v[174:177], v[98:101]
	v_mfma_f32_16x16x32_bf16 v[90:93], v[218:221], v[174:177], v[90:93]
	v_mfma_f32_16x16x32_bf16 v[82:85], v[210:213], v[182:185], v[82:85]
	v_mfma_f32_16x16x32_bf16 v[74:77], v[218:221], v[182:185], v[74:77]
	s_mov_b32 m0, s33
	v_mfma_f32_16x16x32_bf16 v[70:73], v[210:213], v[190:193], v[70:73]
	v_lshl_add_u64 v[222:223], v[226:227], 0, s[76:77]
	v_mfma_f32_16x16x32_bf16 v[66:69], v[218:221], v[190:193], v[66:69]
	s_barrier
	s_setprio 0
	ds_read_b128 v[162:165], v145 offset:49152
	ds_read_b128 v[166:169], v145 offset:50176
	ds_read_b128 v[170:173], v145 offset:51200
	ds_read_b128 v[174:177], v145 offset:52224
	ds_read_b128 v[178:181], v145 offset:53248
	ds_read_b128 v[182:185], v145 offset:54272
	ds_read_b128 v[186:189], v145 offset:55296
	ds_read_b128 v[190:193], v145 offset:56320
	global_load_lds_dwordx4 v[222:223], off
	v_lshl_add_u64 v[222:223], v[228:229], 0, s[76:77]
	s_mov_b32 m0, s35
	s_nop 0
	global_load_lds_dwordx4 v[222:223], off
	s_setprio 1
	s_barrier
	s_waitcnt lgkmcnt(0)
	v_mfma_f32_16x16x32_bf16 v[62:65], v[140:143], v[162:165], v[62:65]
	v_mfma_f32_16x16x32_bf16 v[58:61], v[154:157], v[162:165], v[58:61]
	v_mfma_f32_16x16x32_bf16 v[54:57], v[140:143], v[170:173], v[54:57]
	v_mfma_f32_16x16x32_bf16 v[46:49], v[154:157], v[170:173], v[46:49]
	v_mfma_f32_16x16x32_bf16 v[38:41], v[140:143], v[178:181], v[38:41]
	v_mfma_f32_16x16x32_bf16 v[30:33], v[154:157], v[178:181], v[30:33]
	v_mfma_f32_16x16x32_bf16 v[22:25], v[140:143], v[186:189], v[22:25]
	v_mfma_f32_16x16x32_bf16 v[14:17], v[154:157], v[186:189], v[14:17]
	v_mfma_f32_16x16x32_bf16 v[62:65], v[150:153], v[166:169], v[62:65]
	v_mfma_f32_16x16x32_bf16 v[58:61], v[158:161], v[166:169], v[58:61]
	v_mfma_f32_16x16x32_bf16 v[54:57], v[150:153], v[174:177], v[54:57]
	v_mfma_f32_16x16x32_bf16 v[46:49], v[158:161], v[174:177], v[46:49]
	v_mfma_f32_16x16x32_bf16 v[38:41], v[150:153], v[182:185], v[38:41]
	v_mfma_f32_16x16x32_bf16 v[30:33], v[158:161], v[182:185], v[30:33]
	v_mfma_f32_16x16x32_bf16 v[22:25], v[150:153], v[190:193], v[22:25]
	v_mfma_f32_16x16x32_bf16 v[14:17], v[158:161], v[190:193], v[14:17]
	s_barrier
	s_setprio 0
	s_add_u32 s10, s52, 0x80080
	s_addc_u32 s11, s53, 0
	s_mov_b32 m0, s67
	v_lshl_add_u64 v[140:141], s[10:11], 0, v[194:195]
	global_load_lds_dwordx4 v[140:141], off
	v_lshl_add_u64 v[140:141], s[10:11], 0, v[134:135]
	s_mov_b32 m0, s17
	s_nop 0
	global_load_lds_dwordx4 v[140:141], off
	s_waitcnt vmcnt(6)
	s_setprio 1
	s_barrier
	v_mfma_f32_16x16x32_bf16 v[50:53], v[206:209], v[162:165], v[50:53]
	v_mfma_f32_16x16x32_bf16 v[42:45], v[214:217], v[162:165], v[42:45]
	v_mfma_f32_16x16x32_bf16 v[34:37], v[206:209], v[170:173], v[34:37]
	v_mfma_f32_16x16x32_bf16 v[26:29], v[214:217], v[170:173], v[26:29]
	v_mfma_f32_16x16x32_bf16 v[18:21], v[206:209], v[178:181], v[18:21]
	v_mfma_f32_16x16x32_bf16 v[10:13], v[214:217], v[178:181], v[10:13]
	v_mfma_f32_16x16x32_bf16 v[6:9], v[206:209], v[186:189], v[6:9]
	v_mfma_f32_16x16x32_bf16 v[2:5], v[214:217], v[186:189], v[2:5]
	v_mfma_f32_16x16x32_bf16 v[50:53], v[210:213], v[166:169], v[50:53]
	v_mfma_f32_16x16x32_bf16 v[42:45], v[218:221], v[166:169], v[42:45]
	v_mfma_f32_16x16x32_bf16 v[34:37], v[210:213], v[174:177], v[34:37]
	v_mfma_f32_16x16x32_bf16 v[26:29], v[218:221], v[174:177], v[26:29]
	v_mfma_f32_16x16x32_bf16 v[18:21], v[210:213], v[182:185], v[18:21]
	v_mfma_f32_16x16x32_bf16 v[10:13], v[218:221], v[182:185], v[10:13]
	v_mfma_f32_16x16x32_bf16 v[6:9], v[210:213], v[190:193], v[6:9]
	v_mfma_f32_16x16x32_bf16 v[2:5], v[218:221], v[190:193], v[2:5]
	s_setprio 0
	s_add_i32 s41, s41, 2
	s_add_u32 s6, s6, 0x100
	s_addc_u32 s7, s7, 0
	s_add_u32 s28, s28, 0x100
	s_addc_u32 s29, s29, 0
	s_cmp_gt_u32 s41, 29
	s_barrier
	s_cbranch_scc0 .LBB0_139
	s_cmp_gt_i32 s79, 3
	s_mov_b64 s[6:7], -1
	s_cbranch_scc0 .LBB0_146
	s_lshl_b32 s10, s82, 8
	v_lshl_or_b32 v140, s80, 8, v149
	s_cmp_lg_u32 s79, 4
	v_ashrrev_i32_e32 v141, 31, v140
	s_cbranch_scc0 .LBB0_143
	v_readlane_b32 s6, v252, 55
	v_readlane_b32 s7, v252, 56
	v_add_u32_e32 v150, s10, v147
	s_nop 0
	v_mov_b64_e32 v[142:143], s[6:7]
	s_mov_b32 s6, 0x9000
	v_mad_i64_i32 v[142:143], s[6:7], v150, s6, v[142:143]
	v_lshl_add_u64 v[142:143], v[140:141], 1, v[142:143]
	v_cvt_pk_bf16_f32 v150, v126, v127
	v_cvt_pk_bf16_f32 v151, v128, v129
	v_cvt_pk_bf16_f32 v152, v122, v123
	v_cvt_pk_bf16_f32 v153, v124, v125
	global_store_dwordx4 v[142:143], v[150:153], off
	v_add_co_u32_e32 v154, vcc, s44, v142
	s_nop 0
	v_cvt_pk_bf16_f32 v150, v114, v115
	v_cvt_pk_bf16_f32 v151, v116, v117
	v_cvt_pk_bf16_f32 v152, v106, v107
	v_cvt_pk_bf16_f32 v153, v108, v109
	global_store_dwordx4 v[142:143], v[150:153], off offset:256
	v_addc_co_u32_e32 v155, vcc, 0, v143, vcc
	s_nop 0
	v_cvt_pk_bf16_f32 v150, v118, v119
	v_cvt_pk_bf16_f32 v151, v120, v121
	v_cvt_pk_bf16_f32 v152, v110, v111
	v_cvt_pk_bf16_f32 v153, v112, v113
	global_store_dwordx4 v[154:155], v[150:153], off
	s_mov_b64 s[6:7], 0
	s_nop 0
	v_cvt_pk_bf16_f32 v150, v98, v99
	v_cvt_pk_bf16_f32 v151, v100, v101
	v_cvt_pk_bf16_f32 v152, v90, v91
	v_cvt_pk_bf16_f32 v153, v92, v93
	global_store_dwordx4 v[154:155], v[150:153], off offset:256
	v_add_co_u32_e32 v154, vcc, s45, v142
	s_nop 0
	v_cvt_pk_bf16_f32 v150, v102, v103
	v_cvt_pk_bf16_f32 v151, v104, v105
	v_cvt_pk_bf16_f32 v152, v94, v95
	v_cvt_pk_bf16_f32 v153, v96, v97
	s_nop 0
	v_addc_co_u32_e32 v155, vcc, 0, v143, vcc
	global_store_dwordx4 v[154:155], v[150:153], off
	s_nop 1
	v_cvt_pk_bf16_f32 v150, v82, v83
	v_cvt_pk_bf16_f32 v151, v84, v85
	v_cvt_pk_bf16_f32 v152, v74, v75
	v_cvt_pk_bf16_f32 v153, v76, v77
	global_store_dwordx4 v[154:155], v[150:153], off offset:256
	v_add_co_u32_e32 v154, vcc, s90, v142
	s_nop 0
	v_cvt_pk_bf16_f32 v150, v86, v87
	v_cvt_pk_bf16_f32 v151, v88, v89
	v_cvt_pk_bf16_f32 v152, v78, v79
	v_cvt_pk_bf16_f32 v153, v80, v81
	s_nop 0
	v_addc_co_u32_e32 v155, vcc, 0, v143, vcc
	global_store_dwordx4 v[154:155], v[150:153], off
	s_nop 1
	v_cvt_pk_bf16_f32 v150, v70, v71
	v_cvt_pk_bf16_f32 v151, v72, v73
	v_cvt_pk_bf16_f32 v152, v66, v67
	v_cvt_pk_bf16_f32 v153, v68, v69
	global_store_dwordx4 v[154:155], v[150:153], off offset:256
	v_add_co_u32_e32 v154, vcc, s20, v142
	s_nop 0
	v_cvt_pk_bf16_f32 v150, v62, v63
	v_cvt_pk_bf16_f32 v151, v64, v65
	v_cvt_pk_bf16_f32 v152, v58, v59
	v_cvt_pk_bf16_f32 v153, v60, v61
	s_nop 0
	v_addc_co_u32_e32 v155, vcc, 0, v143, vcc
	global_store_dwordx4 v[154:155], v[150:153], off
	s_nop 1
	v_cvt_pk_bf16_f32 v150, v50, v51
	v_cvt_pk_bf16_f32 v151, v52, v53
	v_cvt_pk_bf16_f32 v152, v42, v43
	v_cvt_pk_bf16_f32 v153, v44, v45
	global_store_dwordx4 v[154:155], v[150:153], off offset:256
	v_add_co_u32_e32 v154, vcc, s21, v142
	s_nop 0
	v_cvt_pk_bf16_f32 v150, v54, v55
	v_cvt_pk_bf16_f32 v151, v56, v57
	v_cvt_pk_bf16_f32 v152, v46, v47
	v_cvt_pk_bf16_f32 v153, v48, v49
	s_nop 0
	v_addc_co_u32_e32 v155, vcc, 0, v143, vcc
	global_store_dwordx4 v[154:155], v[150:153], off
	s_nop 1
	v_cvt_pk_bf16_f32 v150, v34, v35
	v_cvt_pk_bf16_f32 v151, v36, v37
	v_cvt_pk_bf16_f32 v152, v26, v27
	v_cvt_pk_bf16_f32 v153, v28, v29
	global_store_dwordx4 v[154:155], v[150:153], off offset:256
	v_add_co_u32_e32 v154, vcc, s22, v142
	s_nop 0
	v_cvt_pk_bf16_f32 v150, v38, v39
	v_cvt_pk_bf16_f32 v151, v40, v41
	v_cvt_pk_bf16_f32 v152, v30, v31
	v_cvt_pk_bf16_f32 v153, v32, v33
	s_nop 0
	v_addc_co_u32_e32 v155, vcc, 0, v143, vcc
	global_store_dwordx4 v[154:155], v[150:153], off
	v_add_co_u32_e32 v142, vcc, s23, v142
	s_nop 0
	v_cvt_pk_bf16_f32 v150, v18, v19
	v_cvt_pk_bf16_f32 v151, v20, v21
	v_cvt_pk_bf16_f32 v152, v10, v11
	v_cvt_pk_bf16_f32 v153, v12, v13
	global_store_dwordx4 v[154:155], v[150:153], off offset:256
	v_addc_co_u32_e32 v143, vcc, 0, v143, vcc
	s_nop 0
	v_cvt_pk_bf16_f32 v150, v22, v23
	v_cvt_pk_bf16_f32 v151, v24, v25
	v_cvt_pk_bf16_f32 v152, v14, v15
	v_cvt_pk_bf16_f32 v153, v16, v17
	global_store_dwordx4 v[142:143], v[150:153], off
	s_nop 1
	v_cvt_pk_bf16_f32 v150, v6, v7
	v_cvt_pk_bf16_f32 v151, v8, v9
	v_cvt_pk_bf16_f32 v152, v2, v3
	v_cvt_pk_bf16_f32 v153, v4, v5
	global_store_dwordx4 v[142:143], v[150:153], off offset:256

.LBB0_204:
	s_add_u32 s80, s54, s62
	s_addc_u32 s81, s55, s63
	s_add_u32 s82, s80, 0x100
	s_addc_u32 s83, s81, 0
	s_and_b64 s[10:11], s[8:9], exec
	s_cselect_b32 s83, s1, s83
	s_cselect_b32 s82, s0, s82
	s_add_u32 s10, s52, s62
	s_addc_u32 s11, s53, s63
	s_add_u32 s10, s10, 0x100
	s_addc_u32 s11, s11, 0
	s_and_b64 s[8:9], s[8:9], exec
	s_cselect_b32 vcc_hi, s7, s11
	s_cselect_b32 vcc_lo, s6, s10
	s_add_u32 s10, s80, 0x10080
	v_or_b32_e32 v138, 0x10000, v142
	s_addc_u32 s11, s81, 0
	s_add_i32 m0, s5, 0xc000
	s_add_i32 s87, s5, 0xe000
	ds_read_b128 v[144:147], v138
	v_add_u32_e32 v138, 0x10400, v142
	s_add_u32 s80, vcc_lo, 0x340000
	ds_read_b128 v[148:151], v138
	v_add_u32_e32 v138, 0x10800, v142
	s_addc_u32 s81, vcc_hi, 0
	ds_read_b128 v[152:155], v138
	v_add_u32_e32 v138, 0x10c00, v142
	s_add_u32 s62, s82, 0x10000
	ds_read_b128 v[156:159], v138
	s_addc_u32 s63, s83, 0
	s_add_u32 s8, vcc_lo, 0x340080
	s_addc_u32 s9, vcc_hi, 0
	v_lshl_add_u64 v[138:139], s[10:11], 0, v[136:137]
	ds_read_b128 v[160:163], v141
	ds_read_b128 v[164:167], v141 offset:1024
	ds_read_b128 v[168:171], v141 offset:2048
	ds_read_b128 v[172:175], v141 offset:3072
	ds_read_b128 v[176:179], v141 offset:4096
	ds_read_b128 v[180:183], v141 offset:5120
	ds_read_b128 v[184:187], v141 offset:6144
	ds_read_b128 v[188:191], v141 offset:7168
	global_load_lds_dwordx4 v[138:139], off
	v_lshl_add_u64 v[138:139], s[10:11], 0, v[132:133]
	s_mov_b32 m0, s87
	s_nop 0
	global_load_lds_dwordx4 v[138:139], off
	s_waitcnt lgkmcnt(8)
	s_setprio 1
	s_barrier
	s_waitcnt lgkmcnt(0)
	v_mfma_f32_16x16x32_bf16 v[126:129], v[144:147], v[160:163], v[126:129]
	v_mfma_f32_16x16x32_bf16 v[122:125], v[152:155], v[160:163], v[122:125]
	v_mfma_f32_16x16x32_bf16 v[118:121], v[144:147], v[168:171], v[118:121]
	v_mfma_f32_16x16x32_bf16 v[110:113], v[152:155], v[168:171], v[110:113]
	v_mfma_f32_16x16x32_bf16 v[102:105], v[144:147], v[176:179], v[102:105]
	v_mfma_f32_16x16x32_bf16 v[94:97], v[152:155], v[176:179], v[94:97]
	v_mfma_f32_16x16x32_bf16 v[86:89], v[144:147], v[184:187], v[86:89]
	v_mfma_f32_16x16x32_bf16 v[78:81], v[152:155], v[184:187], v[78:81]
	v_mfma_f32_16x16x32_bf16 v[126:129], v[148:151], v[164:167], v[126:129]
	v_mfma_f32_16x16x32_bf16 v[122:125], v[156:159], v[164:167], v[122:125]
	v_mfma_f32_16x16x32_bf16 v[118:121], v[148:151], v[172:175], v[118:121]
	v_mfma_f32_16x16x32_bf16 v[110:113], v[156:159], v[172:175], v[110:113]
	v_mfma_f32_16x16x32_bf16 v[102:105], v[148:151], v[180:183], v[102:105]
	v_mfma_f32_16x16x32_bf16 v[94:97], v[156:159], v[180:183], v[94:97]
	v_mfma_f32_16x16x32_bf16 v[86:89], v[148:151], v[188:191], v[86:89]
	v_mfma_f32_16x16x32_bf16 v[78:81], v[156:159], v[188:191], v[78:81]
	s_barrier
	s_setprio 0
	v_or_b32_e32 v138, 0x14000, v142
	v_add_u32_e32 v139, 0x14400, v142
	ds_read_b128 v[206:209], v138
	ds_read_b128 v[210:213], v139
	v_add_u32_e32 v138, 0x14800, v142
	v_add_u32_e32 v139, 0x14c00, v142
	s_mov_b32 m0, s12
	ds_read_b128 v[214:217], v138
	ds_read_b128 v[218:221], v139
	v_lshl_add_u64 v[138:139], vcc, 0, v[134:135]
	global_load_lds_dwordx4 v[138:139], off
	v_lshl_add_u64 v[192:193], vcc, 0, v[130:131]
	s_mov_b32 m0, s17
	s_nop 0
	global_load_lds_dwordx4 v[192:193], off
	s_setprio 1
	s_barrier
	s_waitcnt lgkmcnt(0)
	v_mfma_f32_16x16x32_bf16 v[114:117], v[206:209], v[160:163], v[114:117]
	v_mfma_f32_16x16x32_bf16 v[106:109], v[214:217], v[160:163], v[106:109]
	v_mfma_f32_16x16x32_bf16 v[98:101], v[206:209], v[168:171], v[98:101]
	v_mfma_f32_16x16x32_bf16 v[90:93], v[214:217], v[168:171], v[90:93]
	v_mfma_f32_16x16x32_bf16 v[82:85], v[206:209], v[176:179], v[82:85]
	v_mfma_f32_16x16x32_bf16 v[74:77], v[214:217], v[176:179], v[74:77]
	v_mfma_f32_16x16x32_bf16 v[70:73], v[206:209], v[184:187], v[70:73]
	v_mfma_f32_16x16x32_bf16 v[66:69], v[214:217], v[184:187], v[66:69]
	v_mfma_f32_16x16x32_bf16 v[114:117], v[210:213], v[164:167], v[114:117]
	v_mfma_f32_16x16x32_bf16 v[106:109], v[218:221], v[164:167], v[106:109]
	v_mfma_f32_16x16x32_bf16 v[98:101], v[210:213], v[172:175], v[98:101]
	v_mfma_f32_16x16x32_bf16 v[90:93], v[218:221], v[172:175], v[90:93]
	v_mfma_f32_16x16x32_bf16 v[82:85], v[210:213], v[180:183], v[82:85]
	v_mfma_f32_16x16x32_bf16 v[74:77], v[218:221], v[180:183], v[74:77]
	s_mov_b32 m0, s5
	v_mfma_f32_16x16x32_bf16 v[70:73], v[210:213], v[188:191], v[70:73]
	v_lshl_add_u64 v[222:223], s[82:83], 0, v[136:137]
	v_mfma_f32_16x16x32_bf16 v[66:69], v[218:221], v[188:191], v[66:69]
	s_barrier
	s_setprio 0
	ds_read_b128 v[160:163], v141 offset:16384
	ds_read_b128 v[164:167], v141 offset:17408
	ds_read_b128 v[168:171], v141 offset:18432
	ds_read_b128 v[172:175], v141 offset:19456
	ds_read_b128 v[176:179], v141 offset:20480
	ds_read_b128 v[180:183], v141 offset:21504
	ds_read_b128 v[184:187], v141 offset:22528
	ds_read_b128 v[188:191], v141 offset:23552
	global_load_lds_dwordx4 v[222:223], off
	v_lshl_add_u64 v[224:225], s[82:83], 0, v[132:133]
	s_mov_b32 m0, s26
	s_nop 0
	global_load_lds_dwordx4 v[224:225], off
	s_setprio 1
	s_barrier
	s_waitcnt lgkmcnt(0)
	v_mfma_f32_16x16x32_bf16 v[62:65], v[144:147], v[160:163], v[62:65]
	v_mfma_f32_16x16x32_bf16 v[58:61], v[152:155], v[160:163], v[58:61]
	v_mfma_f32_16x16x32_bf16 v[54:57], v[144:147], v[168:171], v[54:57]
	v_mfma_f32_16x16x32_bf16 v[46:49], v[152:155], v[168:171], v[46:49]
	v_mfma_f32_16x16x32_bf16 v[38:41], v[144:147], v[176:179], v[38:41]
	v_mfma_f32_16x16x32_bf16 v[30:33], v[152:155], v[176:179], v[30:33]
	v_mfma_f32_16x16x32_bf16 v[22:25], v[144:147], v[184:187], v[22:25]
	v_mfma_f32_16x16x32_bf16 v[14:17], v[152:155], v[184:187], v[14:17]
	v_mfma_f32_16x16x32_bf16 v[62:65], v[148:151], v[164:167], v[62:65]
	v_mfma_f32_16x16x32_bf16 v[58:61], v[156:159], v[164:167], v[58:61]
	v_mfma_f32_16x16x32_bf16 v[54:57], v[148:151], v[172:175], v[54:57]
	v_mfma_f32_16x16x32_bf16 v[46:49], v[156:159], v[172:175], v[46:49]
	v_mfma_f32_16x16x32_bf16 v[38:41], v[148:151], v[180:183], v[38:41]
	v_mfma_f32_16x16x32_bf16 v[30:33], v[156:159], v[180:183], v[30:33]
	v_mfma_f32_16x16x32_bf16 v[22:25], v[148:151], v[188:191], v[22:25]
	v_mfma_f32_16x16x32_bf16 v[14:17], v[156:159], v[188:191], v[14:17]
	s_barrier
	s_setprio 0
	s_mov_b32 m0, s34
	v_lshl_add_u64 v[144:145], s[80:81], 0, v[134:135]
	global_load_lds_dwordx4 v[144:145], off
	v_lshl_add_u64 v[144:145], s[80:81], 0, v[130:131]
	s_mov_b32 m0, s35
	s_nop 0
	global_load_lds_dwordx4 v[144:145], off
	s_waitcnt vmcnt(6)
	s_setprio 1
	s_barrier
	v_mfma_f32_16x16x32_bf16 v[50:53], v[206:209], v[160:163], v[50:53]
	v_mfma_f32_16x16x32_bf16 v[42:45], v[214:217], v[160:163], v[42:45]
	v_mfma_f32_16x16x32_bf16 v[34:37], v[206:209], v[168:171], v[34:37]
	v_mfma_f32_16x16x32_bf16 v[26:29], v[214:217], v[168:171], v[26:29]
	v_mfma_f32_16x16x32_bf16 v[18:21], v[206:209], v[176:179], v[18:21]
	v_mfma_f32_16x16x32_bf16 v[10:13], v[214:217], v[176:179], v[10:13]
	v_mfma_f32_16x16x32_bf16 v[6:9], v[206:209], v[184:187], v[6:9]
	v_mfma_f32_16x16x32_bf16 v[2:5], v[214:217], v[184:187], v[2:5]
	v_mfma_f32_16x16x32_bf16 v[50:53], v[210:213], v[164:167], v[50:53]
	v_mfma_f32_16x16x32_bf16 v[42:45], v[218:221], v[164:167], v[42:45]
	v_mfma_f32_16x16x32_bf16 v[34:37], v[210:213], v[172:175], v[34:37]
	v_mfma_f32_16x16x32_bf16 v[26:29], v[218:221], v[172:175], v[26:29]
	v_or_b32_e32 v144, 0x18000, v142
	v_mfma_f32_16x16x32_bf16 v[18:21], v[210:213], v[180:183], v[18:21]
	v_add_u32_e32 v148, 0x18400, v142
	v_mfma_f32_16x16x32_bf16 v[10:13], v[218:221], v[180:183], v[10:13]
	v_add_u32_e32 v152, 0x18800, v142
	v_mfma_f32_16x16x32_bf16 v[6:9], v[210:213], v[188:191], v[6:9]
	v_add_u32_e32 v156, 0x18c00, v142
	v_mfma_f32_16x16x32_bf16 v[2:5], v[218:221], v[188:191], v[2:5]
	s_barrier
	s_setprio 0
	ds_read_b128 v[144:147], v144
	ds_read_b128 v[148:151], v148
	ds_read_b128 v[152:155], v152
	ds_read_b128 v[156:159], v156
	s_mov_b32 m0, s56
	v_lshl_add_u64 v[206:207], s[62:63], 0, v[136:137]
	ds_read_b128 v[160:163], v141 offset:32768
	ds_read_b128 v[164:167], v141 offset:33792
	ds_read_b128 v[168:171], v141 offset:34816
	ds_read_b128 v[172:175], v141 offset:35840
	ds_read_b128 v[176:179], v141 offset:36864
	ds_read_b128 v[180:183], v141 offset:37888
	ds_read_b128 v[184:187], v141 offset:38912
	ds_read_b128 v[188:191], v141 offset:39936
	global_load_lds_dwordx4 v[206:207], off
	v_lshl_add_u64 v[206:207], s[62:63], 0, v[132:133]
	s_mov_b32 m0, s57
	s_nop 0
	global_load_lds_dwordx4 v[206:207], off
	s_waitcnt lgkmcnt(8)
	s_setprio 1
	s_barrier
	s_waitcnt lgkmcnt(0)
	v_mfma_f32_16x16x32_bf16 v[126:129], v[144:147], v[160:163], v[126:129]
	v_mfma_f32_16x16x32_bf16 v[122:125], v[152:155], v[160:163], v[122:125]
	v_mfma_f32_16x16x32_bf16 v[118:121], v[144:147], v[168:171], v[118:121]
	v_mfma_f32_16x16x32_bf16 v[110:113], v[152:155], v[168:171], v[110:113]
	v_mfma_f32_16x16x32_bf16 v[102:105], v[144:147], v[176:179], v[102:105]
	v_mfma_f32_16x16x32_bf16 v[94:97], v[152:155], v[176:179], v[94:97]
	v_mfma_f32_16x16x32_bf16 v[86:89], v[144:147], v[184:187], v[86:89]
	v_mfma_f32_16x16x32_bf16 v[78:81], v[152:155], v[184:187], v[78:81]
	v_mfma_f32_16x16x32_bf16 v[126:129], v[148:151], v[164:167], v[126:129]
	v_mfma_f32_16x16x32_bf16 v[122:125], v[156:159], v[164:167], v[122:125]
	v_mfma_f32_16x16x32_bf16 v[118:121], v[148:151], v[172:175], v[118:121]
	v_mfma_f32_16x16x32_bf16 v[110:113], v[156:159], v[172:175], v[110:113]
	v_mfma_f32_16x16x32_bf16 v[102:105], v[148:151], v[180:183], v[102:105]
	v_mfma_f32_16x16x32_bf16 v[94:97], v[156:159], v[180:183], v[94:97]
	v_mfma_f32_16x16x32_bf16 v[86:89], v[148:151], v[188:191], v[86:89]
	v_mfma_f32_16x16x32_bf16 v[78:81], v[156:159], v[188:191], v[78:81]
	s_barrier
	s_setprio 0
	v_or_b32_e32 v197, 0x1c000, v142
	s_mov_b32 m0, s58
	v_add_u32_e32 v199, 0x1c400, v142
	ds_read_b128 v[206:209], v197
	ds_read_b128 v[210:213], v199
	v_add_u32_e32 v197, 0x1c800, v142
	v_lshl_add_u64 v[138:139], v[138:139], 0, s[76:77]
	v_add_u32_e32 v199, 0x1cc00, v142
	ds_read_b128 v[214:217], v197
	ds_read_b128 v[218:221], v199
	global_load_lds_dwordx4 v[138:139], off
	v_lshl_add_u64 v[138:139], v[192:193], 0, s[76:77]
	s_mov_b32 m0, s59
	s_nop 0
	global_load_lds_dwordx4 v[138:139], off
	s_setprio 1
	s_barrier
	s_waitcnt lgkmcnt(0)
	v_mfma_f32_16x16x32_bf16 v[114:117], v[206:209], v[160:163], v[114:117]
	v_mfma_f32_16x16x32_bf16 v[106:109], v[214:217], v[160:163], v[106:109]
	v_mfma_f32_16x16x32_bf16 v[98:101], v[206:209], v[168:171], v[98:101]
	v_mfma_f32_16x16x32_bf16 v[90:93], v[214:217], v[168:171], v[90:93]
	v_mfma_f32_16x16x32_bf16 v[82:85], v[206:209], v[176:179], v[82:85]
	v_mfma_f32_16x16x32_bf16 v[74:77], v[214:217], v[176:179], v[74:77]
	v_mfma_f32_16x16x32_bf16 v[70:73], v[206:209], v[184:187], v[70:73]
	v_mfma_f32_16x16x32_bf16 v[66:69], v[214:217], v[184:187], v[66:69]
	v_mfma_f32_16x16x32_bf16 v[114:117], v[210:213], v[164:167], v[114:117]
	v_mfma_f32_16x16x32_bf16 v[106:109], v[218:221], v[164:167], v[106:109]
	v_mfma_f32_16x16x32_bf16 v[98:101], v[210:213], v[172:175], v[98:101]
	v_mfma_f32_16x16x32_bf16 v[90:93], v[218:221], v[172:175], v[90:93]
	v_mfma_f32_16x16x32_bf16 v[82:85], v[210:213], v[180:183], v[82:85]
	v_mfma_f32_16x16x32_bf16 v[74:77], v[218:221], v[180:183], v[74:77]
	s_mov_b32 m0, s67
	v_mfma_f32_16x16x32_bf16 v[70:73], v[210:213], v[188:191], v[70:73]
	v_lshl_add_u64 v[138:139], v[222:223], 0, s[76:77]
	v_mfma_f32_16x16x32_bf16 v[66:69], v[218:221], v[188:191], v[66:69]
	s_barrier
	s_setprio 0
	ds_read_b128 v[160:163], v141 offset:49152
	ds_read_b128 v[164:167], v141 offset:50176
	ds_read_b128 v[168:171], v141 offset:51200
	ds_read_b128 v[172:175], v141 offset:52224
	ds_read_b128 v[176:179], v141 offset:53248
	ds_read_b128 v[180:183], v141 offset:54272
	ds_read_b128 v[184:187], v141 offset:55296
	ds_read_b128 v[188:191], v141 offset:56320
	global_load_lds_dwordx4 v[138:139], off
	v_lshl_add_u64 v[138:139], v[224:225], 0, s[76:77]
	s_mov_b32 m0, s70
	s_nop 0
	global_load_lds_dwordx4 v[138:139], off
	s_setprio 1
	s_barrier
	s_waitcnt lgkmcnt(0)
	v_mfma_f32_16x16x32_bf16 v[62:65], v[144:147], v[160:163], v[62:65]
	v_mfma_f32_16x16x32_bf16 v[58:61], v[152:155], v[160:163], v[58:61]
	v_mfma_f32_16x16x32_bf16 v[54:57], v[144:147], v[168:171], v[54:57]
	v_mfma_f32_16x16x32_bf16 v[46:49], v[152:155], v[168:171], v[46:49]
	v_mfma_f32_16x16x32_bf16 v[38:41], v[144:147], v[176:179], v[38:41]
	v_mfma_f32_16x16x32_bf16 v[30:33], v[152:155], v[176:179], v[30:33]
	v_mfma_f32_16x16x32_bf16 v[22:25], v[144:147], v[184:187], v[22:25]
	v_mfma_f32_16x16x32_bf16 v[14:17], v[152:155], v[184:187], v[14:17]
	v_mfma_f32_16x16x32_bf16 v[62:65], v[148:151], v[164:167], v[62:65]
	v_mfma_f32_16x16x32_bf16 v[58:61], v[156:159], v[164:167], v[58:61]
	v_mfma_f32_16x16x32_bf16 v[54:57], v[148:151], v[172:175], v[54:57]
	v_mfma_f32_16x16x32_bf16 v[46:49], v[156:159], v[172:175], v[46:49]
	v_mfma_f32_16x16x32_bf16 v[38:41], v[148:151], v[180:183], v[38:41]
	v_mfma_f32_16x16x32_bf16 v[30:33], v[156:159], v[180:183], v[30:33]
	v_mfma_f32_16x16x32_bf16 v[22:25], v[148:151], v[188:191], v[22:25]
	v_mfma_f32_16x16x32_bf16 v[14:17], v[156:159], v[188:191], v[14:17]
	s_barrier
	s_setprio 0
	s_mov_b32 m0, s71
	v_lshl_add_u64 v[138:139], s[8:9], 0, v[134:135]
	global_load_lds_dwordx4 v[138:139], off
	v_lshl_add_u64 v[138:139], s[8:9], 0, v[130:131]
	s_mov_b32 m0, s78
	s_nop 0
	global_load_lds_dwordx4 v[138:139], off
	s_waitcnt vmcnt(6)
	s_setprio 1
	s_barrier
	v_mfma_f32_16x16x32_bf16 v[50:53], v[206:209], v[160:163], v[50:53]
	v_mfma_f32_16x16x32_bf16 v[42:45], v[214:217], v[160:163], v[42:45]
	v_mfma_f32_16x16x32_bf16 v[34:37], v[206:209], v[168:171], v[34:37]
	v_mfma_f32_16x16x32_bf16 v[26:29], v[214:217], v[168:171], v[26:29]
	v_mfma_f32_16x16x32_bf16 v[18:21], v[206:209], v[176:179], v[18:21]
	v_mfma_f32_16x16x32_bf16 v[10:13], v[214:217], v[176:179], v[10:13]
	v_mfma_f32_16x16x32_bf16 v[6:9], v[206:209], v[184:187], v[6:9]
	v_mfma_f32_16x16x32_bf16 v[2:5], v[214:217], v[184:187], v[2:5]
	v_mfma_f32_16x16x32_bf16 v[50:53], v[210:213], v[164:167], v[50:53]
	v_mfma_f32_16x16x32_bf16 v[42:45], v[218:221], v[164:167], v[42:45]
	v_mfma_f32_16x16x32_bf16 v[34:37], v[210:213], v[172:175], v[34:37]
	v_mfma_f32_16x16x32_bf16 v[26:29], v[218:221], v[172:175], v[26:29]
	v_mfma_f32_16x16x32_bf16 v[18:21], v[210:213], v[180:183], v[18:21]
	v_mfma_f32_16x16x32_bf16 v[10:13], v[218:221], v[180:183], v[10:13]
	v_mfma_f32_16x16x32_bf16 v[6:9], v[210:213], v[188:191], v[6:9]
	v_mfma_f32_16x16x32_bf16 v[2:5], v[218:221], v[188:191], v[2:5]
	s_setprio 0
	s_andn2_b64 vcc, exec, s[60:61]
	s_mov_b64 s[8:9], -1
	s_mov_b64 s[60:61], 0
	s_mov_b64 s[62:63], 0x100
	s_barrier
	s_cbranch_vccz .LBB0_204
	s_cmp_gt_i32 s29, 63
	s_cbranch_scc0 .LBB0_207
	s_lshl_b32 s8, s29, 10
	s_lshl_b32 s9, s94, 8
	s_add_i32 s9, s9, s8
	v_add_u32_e32 v138, s9, v143
	v_ashrrev_i32_e32 v139, 31, v138
	v_lshlrev_b64 v[138:139], 10, v[138:139]
	s_lshl_b32 s8, s42, 8
	v_lshl_add_u64 v[138:139], s[64:65], 0, v[138:139]
	s_ashr_i32 s9, s8, 31
	v_lshl_add_u64 v[138:139], s[8:9], 1, v[138:139]
	s_mov_b64 s[8:9], 0

.LBB0_255:
	v_or_b32_e32 v130, 0x10000, v182
	v_add_u32_e32 v134, 0x10400, v182
	v_add_u32_e32 v138, 0x10800, v182
	v_add_u32_e32 v142, 0x10c00, v182
	ds_read_b128 v[130:133], v130
	ds_read_b128 v[134:137], v134
	ds_read_b128 v[138:141], v138
	ds_read_b128 v[142:145], v142
	s_add_u32 s8, s6, 0xfff00080
	s_addc_u32 s9, s7, -1
	s_cmp_eq_u32 s79, 60
	s_cselect_b32 s11, s53, s9
	s_cselect_b32 s10, s52, s8
	s_cselect_b32 s9, s61, s78
	s_cselect_b32 s8, s60, s1
	v_lshl_add_u64 v[178:179], s[6:7], 0, v[166:167]
	s_add_i32 m0, s5, 0xc000
	ds_read_b128 v[146:149], v181
	ds_read_b128 v[150:153], v181 offset:1024
	ds_read_b128 v[154:157], v181 offset:2048
	ds_read_b128 v[170:173], v181 offset:3072
	ds_read_b128 v[174:177], v181 offset:4096
	ds_read_b128 v[184:187], v181 offset:5120
	ds_read_b128 v[188:191], v181 offset:6144
	ds_read_b128 v[206:209], v181 offset:7168
	global_load_lds_dwordx4 v[178:179], off
	v_lshl_add_u64 v[178:179], s[6:7], 0, v[168:169]
	s_add_i32 m0, s5, 0xe000
	s_nop 0
	global_load_lds_dwordx4 v[178:179], off
	s_waitcnt lgkmcnt(8)
	s_setprio 1
	s_barrier
	s_waitcnt lgkmcnt(0)
	v_mfma_f32_16x16x32_bf16 v[126:129], v[130:133], v[146:149], v[126:129]
	v_mfma_f32_16x16x32_bf16 v[122:125], v[138:141], v[146:149], v[122:125]
	v_mfma_f32_16x16x32_bf16 v[110:113], v[130:133], v[154:157], v[110:113]
	v_mfma_f32_16x16x32_bf16 v[106:109], v[138:141], v[154:157], v[106:109]
	v_mfma_f32_16x16x32_bf16 v[94:97], v[130:133], v[174:177], v[94:97]
	v_mfma_f32_16x16x32_bf16 v[90:93], v[138:141], v[174:177], v[90:93]
	v_mfma_f32_16x16x32_bf16 v[78:81], v[130:133], v[188:191], v[78:81]
	v_mfma_f32_16x16x32_bf16 v[74:77], v[138:141], v[188:191], v[74:77]
	v_mfma_f32_16x16x32_bf16 v[126:129], v[134:137], v[150:153], v[126:129]
	v_mfma_f32_16x16x32_bf16 v[122:125], v[142:145], v[150:153], v[122:125]
	v_mfma_f32_16x16x32_bf16 v[110:113], v[134:137], v[170:173], v[110:113]
	v_mfma_f32_16x16x32_bf16 v[106:109], v[142:145], v[170:173], v[106:109]
	v_mfma_f32_16x16x32_bf16 v[94:97], v[134:137], v[184:187], v[94:97]
	v_mfma_f32_16x16x32_bf16 v[90:93], v[142:145], v[184:187], v[90:93]
	v_mfma_f32_16x16x32_bf16 v[78:81], v[134:137], v[206:209], v[78:81]
	v_mfma_f32_16x16x32_bf16 v[74:77], v[142:145], v[206:209], v[74:77]
	s_barrier
	s_setprio 0
	v_or_b32_e32 v178, 0x14000, v182
	v_add_u32_e32 v179, 0x14400, v182
	ds_read_b128 v[210:213], v178
	ds_read_b128 v[214:217], v179
	v_add_u32_e32 v178, 0x14800, v182
	v_add_u32_e32 v179, 0x14c00, v182
	s_mov_b32 m0, s12
	ds_read_b128 v[218:221], v178
	ds_read_b128 v[222:225], v179
	v_lshl_add_u64 v[178:179], s[8:9], 0, v[162:163]
	global_load_lds_dwordx4 v[178:179], off
	v_lshl_add_u64 v[192:193], s[8:9], 0, v[158:159]
	s_mov_b32 m0, s17
	s_nop 0
	global_load_lds_dwordx4 v[192:193], off
	s_setprio 1
	s_barrier
	s_waitcnt lgkmcnt(0)
	v_mfma_f32_16x16x32_bf16 v[118:121], v[210:213], v[146:149], v[118:121]
	v_mfma_f32_16x16x32_bf16 v[114:117], v[218:221], v[146:149], v[114:117]
	v_mfma_f32_16x16x32_bf16 v[102:105], v[210:213], v[154:157], v[102:105]
	v_mfma_f32_16x16x32_bf16 v[98:101], v[218:221], v[154:157], v[98:101]
	v_mfma_f32_16x16x32_bf16 v[86:89], v[210:213], v[174:177], v[86:89]
	v_mfma_f32_16x16x32_bf16 v[82:85], v[218:221], v[174:177], v[82:85]
	v_mfma_f32_16x16x32_bf16 v[70:73], v[210:213], v[188:191], v[70:73]
	v_mfma_f32_16x16x32_bf16 v[66:69], v[218:221], v[188:191], v[66:69]
	v_mfma_f32_16x16x32_bf16 v[118:121], v[214:217], v[150:153], v[118:121]
	v_mfma_f32_16x16x32_bf16 v[114:117], v[222:225], v[150:153], v[114:117]
	v_mfma_f32_16x16x32_bf16 v[102:105], v[214:217], v[170:173], v[102:105]
	v_mfma_f32_16x16x32_bf16 v[98:101], v[222:225], v[170:173], v[98:101]
	v_mfma_f32_16x16x32_bf16 v[86:89], v[214:217], v[184:187], v[86:89]
	v_mfma_f32_16x16x32_bf16 v[82:85], v[222:225], v[184:187], v[82:85]
	s_mov_b32 m0, s5
	v_mfma_f32_16x16x32_bf16 v[70:73], v[214:217], v[206:209], v[70:73]
	v_lshl_add_u64 v[226:227], s[10:11], 0, v[164:165]
	v_mfma_f32_16x16x32_bf16 v[66:69], v[222:225], v[206:209], v[66:69]
	s_barrier
	s_setprio 0
	ds_read_b128 v[146:149], v181 offset:16384
	ds_read_b128 v[150:153], v181 offset:17408
	ds_read_b128 v[154:157], v181 offset:18432
	ds_read_b128 v[170:173], v181 offset:19456
	ds_read_b128 v[174:177], v181 offset:20480
	ds_read_b128 v[184:187], v181 offset:21504
	ds_read_b128 v[188:191], v181 offset:22528
	ds_read_b128 v[206:209], v181 offset:23552
	global_load_lds_dwordx4 v[226:227], off
	v_lshl_add_u64 v[228:229], s[10:11], 0, v[160:161]
	s_mov_b32 m0, s26
	s_nop 0
	global_load_lds_dwordx4 v[228:229], off
	s_setprio 1
	s_barrier
	s_waitcnt lgkmcnt(0)
	v_mfma_f32_16x16x32_bf16 v[62:65], v[130:133], v[146:149], v[62:65]
	v_mfma_f32_16x16x32_bf16 v[58:61], v[138:141], v[146:149], v[58:61]
	v_mfma_f32_16x16x32_bf16 v[46:49], v[130:133], v[154:157], v[46:49]
	v_mfma_f32_16x16x32_bf16 v[42:45], v[138:141], v[154:157], v[42:45]
	v_mfma_f32_16x16x32_bf16 v[30:33], v[130:133], v[174:177], v[30:33]
	v_mfma_f32_16x16x32_bf16 v[26:29], v[138:141], v[174:177], v[26:29]
	v_mfma_f32_16x16x32_bf16 v[14:17], v[130:133], v[188:191], v[14:17]
	v_mfma_f32_16x16x32_bf16 v[10:13], v[138:141], v[188:191], v[10:13]
	v_mfma_f32_16x16x32_bf16 v[62:65], v[134:137], v[150:153], v[62:65]
	v_mfma_f32_16x16x32_bf16 v[58:61], v[142:145], v[150:153], v[58:61]
	v_mfma_f32_16x16x32_bf16 v[46:49], v[134:137], v[170:173], v[46:49]
	v_mfma_f32_16x16x32_bf16 v[42:45], v[142:145], v[170:173], v[42:45]
	v_mfma_f32_16x16x32_bf16 v[30:33], v[134:137], v[184:187], v[30:33]
	v_mfma_f32_16x16x32_bf16 v[26:29], v[142:145], v[184:187], v[26:29]
	v_mfma_f32_16x16x32_bf16 v[14:17], v[134:137], v[206:209], v[14:17]
	v_mfma_f32_16x16x32_bf16 v[10:13], v[142:145], v[206:209], v[10:13]
	s_barrier
	s_setprio 0
	s_add_u32 s80, s8, 0x100000
	s_addc_u32 s81, s9, 0
	s_mov_b32 m0, s34
	v_lshl_add_u64 v[130:131], s[80:81], 0, v[162:163]
	global_load_lds_dwordx4 v[130:131], off
	v_lshl_add_u64 v[130:131], s[80:81], 0, v[158:159]
	s_mov_b32 m0, s35
	s_nop 0
	global_load_lds_dwordx4 v[130:131], off
	s_waitcnt vmcnt(6)
	s_setprio 1
	s_barrier
	v_mfma_f32_16x16x32_bf16 v[54:57], v[210:213], v[146:149], v[54:57]
	v_mfma_f32_16x16x32_bf16 v[50:53], v[218:221], v[146:149], v[50:53]
	v_mfma_f32_16x16x32_bf16 v[38:41], v[210:213], v[154:157], v[38:41]
	v_mfma_f32_16x16x32_bf16 v[34:37], v[218:221], v[154:157], v[34:37]
	v_mfma_f32_16x16x32_bf16 v[22:25], v[210:213], v[174:177], v[22:25]
	v_mfma_f32_16x16x32_bf16 v[18:21], v[218:221], v[174:177], v[18:21]
	v_mfma_f32_16x16x32_bf16 v[6:9], v[210:213], v[188:191], v[6:9]
	v_mfma_f32_16x16x32_bf16 v[2:5], v[218:221], v[188:191], v[2:5]
	v_mfma_f32_16x16x32_bf16 v[54:57], v[214:217], v[150:153], v[54:57]
	v_mfma_f32_16x16x32_bf16 v[50:53], v[222:225], v[150:153], v[50:53]
	v_mfma_f32_16x16x32_bf16 v[38:41], v[214:217], v[170:173], v[38:41]
	v_mfma_f32_16x16x32_bf16 v[34:37], v[222:225], v[170:173], v[34:37]
	v_or_b32_e32 v130, 0x18000, v182
	v_mfma_f32_16x16x32_bf16 v[22:25], v[214:217], v[184:187], v[22:25]
	v_add_u32_e32 v134, 0x18400, v182
	v_mfma_f32_16x16x32_bf16 v[18:21], v[222:225], v[184:187], v[18:21]
	v_add_u32_e32 v138, 0x18800, v182
	v_mfma_f32_16x16x32_bf16 v[6:9], v[214:217], v[206:209], v[6:9]
	v_add_u32_e32 v142, 0x18c00, v182
	v_mfma_f32_16x16x32_bf16 v[2:5], v[222:225], v[206:209], v[2:5]
	s_barrier
	s_setprio 0
	ds_read_b128 v[130:133], v130
	ds_read_b128 v[134:137], v134
	ds_read_b128 v[138:141], v138
	ds_read_b128 v[142:145], v142
	s_add_u32 s10, s10, 0x100000
	s_addc_u32 s11, s11, 0
	s_mov_b32 m0, s42
	v_lshl_add_u64 v[210:211], s[10:11], 0, v[164:165]
	ds_read_b128 v[146:149], v181 offset:32768
	ds_read_b128 v[150:153], v181 offset:33792
	ds_read_b128 v[154:157], v181 offset:34816
	ds_read_b128 v[170:173], v181 offset:35840
	ds_read_b128 v[174:177], v181 offset:36864
	ds_read_b128 v[184:187], v181 offset:37888
	ds_read_b128 v[188:191], v181 offset:38912
	ds_read_b128 v[206:209], v181 offset:39936
	global_load_lds_dwordx4 v[210:211], off
	v_lshl_add_u64 v[210:211], s[10:11], 0, v[160:161]
	s_mov_b32 m0, s54
	s_nop 0
	global_load_lds_dwordx4 v[210:211], off
	s_waitcnt lgkmcnt(8)
	s_setprio 1
	s_barrier
	s_waitcnt lgkmcnt(0)
	v_mfma_f32_16x16x32_bf16 v[126:129], v[130:133], v[146:149], v[126:129]
	v_mfma_f32_16x16x32_bf16 v[122:125], v[138:141], v[146:149], v[122:125]
	v_mfma_f32_16x16x32_bf16 v[110:113], v[130:133], v[154:157], v[110:113]
	v_mfma_f32_16x16x32_bf16 v[106:109], v[138:141], v[154:157], v[106:109]
	v_mfma_f32_16x16x32_bf16 v[94:97], v[130:133], v[174:177], v[94:97]
	v_mfma_f32_16x16x32_bf16 v[90:93], v[138:141], v[174:177], v[90:93]
	v_mfma_f32_16x16x32_bf16 v[78:81], v[130:133], v[188:191], v[78:81]
	v_mfma_f32_16x16x32_bf16 v[74:77], v[138:141], v[188:191], v[74:77]
	v_mfma_f32_16x16x32_bf16 v[126:129], v[134:137], v[150:153], v[126:129]
	v_mfma_f32_16x16x32_bf16 v[122:125], v[142:145], v[150:153], v[122:125]
	v_mfma_f32_16x16x32_bf16 v[110:113], v[134:137], v[170:173], v[110:113]
	v_mfma_f32_16x16x32_bf16 v[106:109], v[142:145], v[170:173], v[106:109]
	v_mfma_f32_16x16x32_bf16 v[94:97], v[134:137], v[184:187], v[94:97]
	v_mfma_f32_16x16x32_bf16 v[90:93], v[142:145], v[184:187], v[90:93]
	v_mfma_f32_16x16x32_bf16 v[78:81], v[134:137], v[206:209], v[78:81]
	v_mfma_f32_16x16x32_bf16 v[74:77], v[142:145], v[206:209], v[74:77]
	s_barrier
	s_setprio 0
	v_or_b32_e32 v194, 0x1c000, v182
	s_mov_b32 m0, s55
	v_add_u32_e32 v197, 0x1c400, v182
	ds_read_b128 v[210:213], v194
	ds_read_b128 v[214:217], v197
	v_add_u32_e32 v194, 0x1c800, v182
	v_lshl_add_u64 v[178:179], v[178:179], 0, s[76:77]
	v_add_u32_e32 v197, 0x1cc00, v182
	ds_read_b128 v[218:221], v194
	ds_read_b128 v[222:225], v197
	global_load_lds_dwordx4 v[178:179], off
	v_lshl_add_u64 v[178:179], v[192:193], 0, s[76:77]
	s_mov_b32 m0, s56
	s_nop 0
	global_load_lds_dwordx4 v[178:179], off
	s_setprio 1
	s_barrier
	s_waitcnt lgkmcnt(0)
	v_mfma_f32_16x16x32_bf16 v[118:121], v[210:213], v[146:149], v[118:121]
	v_mfma_f32_16x16x32_bf16 v[114:117], v[218:221], v[146:149], v[114:117]
	v_mfma_f32_16x16x32_bf16 v[102:105], v[210:213], v[154:157], v[102:105]
	v_mfma_f32_16x16x32_bf16 v[98:101], v[218:221], v[154:157], v[98:101]
	v_mfma_f32_16x16x32_bf16 v[86:89], v[210:213], v[174:177], v[86:89]
	v_mfma_f32_16x16x32_bf16 v[82:85], v[218:221], v[174:177], v[82:85]
	v_mfma_f32_16x16x32_bf16 v[70:73], v[210:213], v[188:191], v[70:73]
	v_mfma_f32_16x16x32_bf16 v[66:69], v[218:221], v[188:191], v[66:69]
	v_mfma_f32_16x16x32_bf16 v[118:121], v[214:217], v[150:153], v[118:121]
	v_mfma_f32_16x16x32_bf16 v[114:117], v[222:225], v[150:153], v[114:117]
	v_mfma_f32_16x16x32_bf16 v[102:105], v[214:217], v[170:173], v[102:105]
	v_mfma_f32_16x16x32_bf16 v[98:101], v[222:225], v[170:173], v[98:101]
	v_mfma_f32_16x16x32_bf16 v[86:89], v[214:217], v[184:187], v[86:89]
	v_mfma_f32_16x16x32_bf16 v[82:85], v[222:225], v[184:187], v[82:85]
	s_mov_b32 m0, s57
	v_mfma_f32_16x16x32_bf16 v[70:73], v[214:217], v[206:209], v[70:73]
	v_lshl_add_u64 v[178:179], v[226:227], 0, s[76:77]
	v_mfma_f32_16x16x32_bf16 v[66:69], v[222:225], v[206:209], v[66:69]
	s_barrier
	s_setprio 0
	ds_read_b128 v[146:149], v181 offset:49152
	ds_read_b128 v[150:153], v181 offset:50176
	ds_read_b128 v[154:157], v181 offset:51200
	ds_read_b128 v[170:173], v181 offset:52224
	ds_read_b128 v[174:177], v181 offset:53248
	ds_read_b128 v[184:187], v181 offset:54272
	ds_read_b128 v[188:191], v181 offset:55296
	ds_read_b128 v[206:209], v181 offset:56320
	global_load_lds_dwordx4 v[178:179], off
	v_lshl_add_u64 v[178:179], v[228:229], 0, s[76:77]
	s_mov_b32 m0, s58
	s_nop 0
	global_load_lds_dwordx4 v[178:179], off
	s_setprio 1
	s_barrier
	s_waitcnt lgkmcnt(0)
	v_mfma_f32_16x16x32_bf16 v[62:65], v[130:133], v[146:149], v[62:65]
	v_mfma_f32_16x16x32_bf16 v[58:61], v[138:141], v[146:149], v[58:61]
	v_mfma_f32_16x16x32_bf16 v[46:49], v[130:133], v[154:157], v[46:49]
	v_mfma_f32_16x16x32_bf16 v[42:45], v[138:141], v[154:157], v[42:45]
	v_mfma_f32_16x16x32_bf16 v[30:33], v[130:133], v[174:177], v[30:33]
	v_mfma_f32_16x16x32_bf16 v[26:29], v[138:141], v[174:177], v[26:29]
	v_mfma_f32_16x16x32_bf16 v[14:17], v[130:133], v[188:191], v[14:17]
	v_mfma_f32_16x16x32_bf16 v[10:13], v[138:141], v[188:191], v[10:13]
	v_mfma_f32_16x16x32_bf16 v[62:65], v[134:137], v[150:153], v[62:65]
	v_mfma_f32_16x16x32_bf16 v[58:61], v[142:145], v[150:153], v[58:61]
	v_mfma_f32_16x16x32_bf16 v[46:49], v[134:137], v[170:173], v[46:49]
	v_mfma_f32_16x16x32_bf16 v[42:45], v[142:145], v[170:173], v[42:45]
	v_mfma_f32_16x16x32_bf16 v[30:33], v[134:137], v[184:187], v[30:33]
	v_mfma_f32_16x16x32_bf16 v[26:29], v[142:145], v[184:187], v[26:29]
	v_mfma_f32_16x16x32_bf16 v[14:17], v[134:137], v[206:209], v[14:17]
	v_mfma_f32_16x16x32_bf16 v[10:13], v[142:145], v[206:209], v[10:13]
	s_barrier
	s_setprio 0
	s_add_u32 s8, s8, 0x100080
	s_addc_u32 s9, s9, 0
	s_mov_b32 m0, s59
	v_lshl_add_u64 v[130:131], s[8:9], 0, v[162:163]
	global_load_lds_dwordx4 v[130:131], off
	v_lshl_add_u64 v[130:131], s[8:9], 0, v[158:159]
	s_mov_b32 m0, s67
	s_nop 0
	global_load_lds_dwordx4 v[130:131], off
	s_waitcnt vmcnt(6)
	s_setprio 1
	s_barrier
	v_mfma_f32_16x16x32_bf16 v[54:57], v[210:213], v[146:149], v[54:57]
	v_mfma_f32_16x16x32_bf16 v[50:53], v[218:221], v[146:149], v[50:53]
	v_mfma_f32_16x16x32_bf16 v[38:41], v[210:213], v[154:157], v[38:41]
	v_mfma_f32_16x16x32_bf16 v[34:37], v[218:221], v[154:157], v[34:37]
	v_mfma_f32_16x16x32_bf16 v[22:25], v[210:213], v[174:177], v[22:25]
	v_mfma_f32_16x16x32_bf16 v[18:21], v[218:221], v[174:177], v[18:21]
	v_mfma_f32_16x16x32_bf16 v[6:9], v[210:213], v[188:191], v[6:9]
	v_mfma_f32_16x16x32_bf16 v[2:5], v[218:221], v[188:191], v[2:5]
	v_mfma_f32_16x16x32_bf16 v[54:57], v[214:217], v[150:153], v[54:57]
	v_mfma_f32_16x16x32_bf16 v[50:53], v[222:225], v[150:153], v[50:53]
	v_mfma_f32_16x16x32_bf16 v[38:41], v[214:217], v[170:173], v[38:41]
	v_mfma_f32_16x16x32_bf16 v[34:37], v[222:225], v[170:173], v[34:37]
	v_mfma_f32_16x16x32_bf16 v[22:25], v[214:217], v[184:187], v[22:25]
	v_mfma_f32_16x16x32_bf16 v[18:21], v[222:225], v[184:187], v[18:21]
	v_mfma_f32_16x16x32_bf16 v[6:9], v[214:217], v[206:209], v[6:9]
	v_mfma_f32_16x16x32_bf16 v[2:5], v[222:225], v[206:209], v[2:5]
	s_setprio 0
	s_add_i32 s79, s79, 2
	s_add_u32 s6, s6, 0x100
	s_addc_u32 s7, s7, 0
	s_add_u32 s1, s1, 0x100
	s_addc_u32 s78, s78, 0
	s_cmp_gt_u32 s79, 61
	s_barrier
	s_cbranch_scc0 .LBB0_255
	s_lshl_b32 s1, s28, 9
	s_and_b32 s1, s1, 0xfffff800
	s_lshl_b32 s6, s29, 8
	s_add_i32 s1, s1, s6
	v_add_u32_e32 v172, s1, v180
	s_lshl_b32 s1, s28, 8
	s_and_b32 s1, s1, 0x300
	v_or_b32_e32 v132, s1, v183
	v_mov_b64_e32 v[170:171], s[50:51]
	v_mad_i64_i32 v[130:131], s[6:7], v172, s37, v[170:171]
	v_lshlrev_b32_e32 v194, 1, v132
	v_lshl_add_u64 v[130:131], v[130:131], 0, v[194:195]
	v_lshl_add_u64 v[132:133], v[130:131], 0, s[84:85]
	v_add_co_u32_e32 v130, vcc, s16, v130
	v_or_b32_e32 v178, 16, v172
	s_nop 0
	v_addc_co_u32_e32 v131, vcc, 0, v131, vcc
	global_load_dwordx4 v[184:187], v[130:131], off offset:2048
	global_load_dwordx4 v[154:157], v[132:133], off offset:256
	v_mad_i64_i32 v[130:131], s[6:7], v178, s37, v[170:171]
	v_lshl_add_u64 v[130:131], v[130:131], 0, v[194:195]
	v_lshl_add_u64 v[132:133], v[130:131], 0, s[84:85]
	v_add_co_u32_e32 v130, vcc, s16, v130
	v_or_b32_e32 v176, 32, v172
	s_nop 0
	v_addc_co_u32_e32 v131, vcc, 0, v131, vcc
	global_load_dwordx4 v[150:153], v[130:131], off offset:2048
	global_load_dwordx4 v[146:149], v[132:133], off offset:256
	v_mad_i64_i32 v[130:131], s[6:7], v176, s37, v[170:171]
	v_lshl_add_u64 v[130:131], v[130:131], 0, v[194:195]
	v_lshl_add_u64 v[132:133], v[130:131], 0, s[84:85]
	v_add_co_u32_e32 v130, vcc, s16, v130
	v_or_b32_e32 v174, 48, v172
	s_nop 0
	v_addc_co_u32_e32 v131, vcc, 0, v131, vcc
	global_load_dwordx4 v[142:145], v[130:131], off offset:2048
	global_load_dwordx4 v[138:141], v[132:133], off offset:256
	v_mad_i64_i32 v[130:131], s[6:7], v174, s37, v[170:171]
	v_lshl_add_u64 v[130:131], v[130:131], 0, v[194:195]
	v_lshl_add_u64 v[132:133], v[130:131], 0, s[84:85]
	v_add_co_u32_e32 v130, vcc, s16, v130
	v_pk_mul_f32 v[126:127], v[126:127], s[72:73] op_sel_hi:[1,0]
	s_nop 0
	v_addc_co_u32_e32 v131, vcc, 0, v131, vcc
	global_load_dwordx4 v[134:137], v[130:131], off offset:2048
	s_nop 0
	global_load_dwordx4 v[130:133], v[132:133], off offset:256
	v_pk_mul_f32 v[190:191], v[124:125], s[72:73] op_sel_hi:[1,0]
	v_pk_mul_f32 v[128:129], v[128:129], s[72:73] op_sel_hi:[1,0]
	v_pk_mul_f32 v[122:123], v[122:123], s[72:73] op_sel_hi:[1,0]
	v_ashrrev_i32_e32 v173, 31, v172
	v_lshlrev_b64 v[188:189], 11, v[172:173]
	v_pk_mul_f32 v[118:119], v[118:119], s[72:73] op_sel_hi:[1,0]
	v_pk_mul_f32 v[120:121], v[120:121], s[72:73] op_sel_hi:[1,0]
	v_pk_mul_f32 v[110:111], v[110:111], s[72:73] op_sel_hi:[1,0]
	v_pk_mul_f32 v[112:113], v[112:113], s[72:73] op_sel_hi:[1,0]
	v_ashrrev_i32_e32 v179, 31, v178
	v_pk_mul_f32 v[102:103], v[102:103], s[72:73] op_sel_hi:[1,0]
	v_pk_mul_f32 v[104:105], v[104:105], s[72:73] op_sel_hi:[1,0]
	v_pk_mul_f32 v[94:95], v[94:95], s[72:73] op_sel_hi:[1,0]
	v_pk_mul_f32 v[96:97], v[96:97], s[72:73] op_sel_hi:[1,0]
	v_ashrrev_i32_e32 v177, 31, v176
	v_pk_mul_f32 v[86:87], v[86:87], s[72:73] op_sel_hi:[1,0]
	v_pk_mul_f32 v[88:89], v[88:89], s[72:73] op_sel_hi:[1,0]
	v_pk_mul_f32 v[78:79], v[78:79], s[72:73] op_sel_hi:[1,0]
	v_pk_mul_f32 v[80:81], v[80:81], s[72:73] op_sel_hi:[1,0]
	v_ashrrev_i32_e32 v175, 31, v174
	v_pk_mul_f32 v[70:71], v[70:71], s[72:73] op_sel_hi:[1,0]
	v_pk_mul_f32 v[72:73], v[72:73], s[72:73] op_sel_hi:[1,0]
	s_waitcnt vmcnt(0)
	v_lshlrev_b32_e32 v124, 16, v184
	v_and_b32_e32 v125, 0xffff0000, v184
	v_mul_f32_e32 v124, v126, v124
	v_mul_f32_e32 v125, v127, v125
	v_cvt_pk_bf16_f32 v124, v124, v125
	v_lshlrev_b32_e32 v125, 16, v185
	v_and_b32_e32 v126, 0xffff0000, v185
	v_mul_f32_e32 v125, v128, v125
	v_mul_f32_e32 v126, v129, v126
	v_cvt_pk_bf16_f32 v125, v125, v126
	v_lshlrev_b32_e32 v126, 16, v186
	v_mul_f32_e32 v122, v122, v126
	v_and_b32_e32 v126, 0xffff0000, v186
	v_mul_f32_e32 v123, v123, v126
	v_cvt_pk_bf16_f32 v126, v122, v123
	v_lshlrev_b32_e32 v122, 16, v187
	v_and_b32_e32 v123, 0xffff0000, v187
	v_mul_f32_e32 v122, v190, v122
	v_mul_f32_e32 v123, v191, v123
	v_cvt_pk_bf16_f32 v127, v122, v123
	v_lshl_add_u64 v[122:123], s[74:75], 0, v[188:189]
	v_lshl_add_u64 v[122:123], v[122:123], 0, v[194:195]
	global_store_dwordx4 v[122:123], v[124:127], off
	s_nop 1
	v_pk_mul_f32 v[124:125], v[116:117], s[72:73] op_sel_hi:[1,0]
	v_pk_mul_f32 v[116:117], v[114:115], s[72:73] op_sel_hi:[1,0]
	v_lshlrev_b32_e32 v114, 16, v154
	v_and_b32_e32 v115, 0xffff0000, v154
	v_mul_f32_e32 v114, v118, v114
	v_mul_f32_e32 v115, v119, v115
	v_cvt_pk_bf16_f32 v114, v114, v115
	v_lshlrev_b32_e32 v115, 16, v155
	v_and_b32_e32 v118, 0xffff0000, v155
	v_mul_f32_e32 v115, v120, v115
	v_mul_f32_e32 v118, v121, v118
	v_cvt_pk_bf16_f32 v115, v115, v118
	v_lshlrev_b32_e32 v118, 16, v156
	v_mul_f32_e32 v116, v116, v118
	v_and_b32_e32 v118, 0xffff0000, v156
	v_mul_f32_e32 v117, v117, v118
	v_cvt_pk_bf16_f32 v116, v116, v117
	v_lshlrev_b32_e32 v117, 16, v157
	v_mul_f32_e32 v117, v124, v117
	v_and_b32_e32 v118, 0xffff0000, v157
	v_mul_f32_e32 v118, v125, v118
	v_cvt_pk_bf16_f32 v117, v117, v118
	global_store_dwordx4 v[122:123], v[114:117], off offset:256
	s_nop 1
	v_pk_mul_f32 v[116:117], v[108:109], s[72:73] op_sel_hi:[1,0]
	v_pk_mul_f32 v[108:109], v[106:107], s[72:73] op_sel_hi:[1,0]
	v_lshlrev_b32_e32 v106, 16, v150
	v_and_b32_e32 v107, 0xffff0000, v150
	v_mul_f32_e32 v106, v110, v106
	v_mul_f32_e32 v107, v111, v107
	v_cvt_pk_bf16_f32 v106, v106, v107
	v_lshlrev_b32_e32 v107, 16, v151
	v_and_b32_e32 v110, 0xffff0000, v151
	v_mul_f32_e32 v107, v112, v107
	v_mul_f32_e32 v110, v113, v110
	v_cvt_pk_bf16_f32 v107, v107, v110
	v_lshlrev_b32_e32 v110, 16, v152
	v_mul_f32_e32 v108, v108, v110
	v_and_b32_e32 v110, 0xffff0000, v152
	v_mul_f32_e32 v109, v109, v110
	v_cvt_pk_bf16_f32 v108, v108, v109
	v_lshlrev_b32_e32 v109, 16, v153
	v_and_b32_e32 v110, 0xffff0000, v153
	v_lshlrev_b64 v[114:115], 11, v[178:179]
	v_mul_f32_e32 v109, v116, v109
	v_mul_f32_e32 v110, v117, v110
	v_cvt_pk_bf16_f32 v109, v109, v110
	v_lshl_add_u64 v[110:111], s[74:75], 0, v[114:115]
	v_lshl_add_u64 v[110:111], v[110:111], 0, v[194:195]
	global_store_dwordx4 v[110:111], v[106:109], off
	s_nop 1
	v_pk_mul_f32 v[106:107], v[100:101], s[72:73] op_sel_hi:[1,0]
	v_pk_mul_f32 v[100:101], v[98:99], s[72:73] op_sel_hi:[1,0]
	v_lshlrev_b32_e32 v98, 16, v146
	v_and_b32_e32 v99, 0xffff0000, v146
	v_mul_f32_e32 v98, v102, v98
	v_mul_f32_e32 v99, v103, v99
	v_cvt_pk_bf16_f32 v98, v98, v99
	v_lshlrev_b32_e32 v99, 16, v147
	v_and_b32_e32 v102, 0xffff0000, v147
	v_mul_f32_e32 v99, v104, v99
	v_mul_f32_e32 v102, v105, v102
	v_cvt_pk_bf16_f32 v99, v99, v102
	v_lshlrev_b32_e32 v102, 16, v148
	v_mul_f32_e32 v100, v100, v102
	v_and_b32_e32 v102, 0xffff0000, v148
	v_mul_f32_e32 v101, v101, v102
	v_cvt_pk_bf16_f32 v100, v100, v101
	v_lshlrev_b32_e32 v101, 16, v149
	v_mul_f32_e32 v101, v106, v101
	v_and_b32_e32 v102, 0xffff0000, v149
	v_mul_f32_e32 v102, v107, v102
	v_cvt_pk_bf16_f32 v101, v101, v102
	global_store_dwordx4 v[110:111], v[98:101], off offset:256
	s_nop 1
	v_pk_mul_f32 v[100:101], v[92:93], s[72:73] op_sel_hi:[1,0]
	v_pk_mul_f32 v[92:93], v[90:91], s[72:73] op_sel_hi:[1,0]
	v_lshlrev_b32_e32 v90, 16, v142
	v_and_b32_e32 v91, 0xffff0000, v142
	v_mul_f32_e32 v90, v94, v90
	v_mul_f32_e32 v91, v95, v91
	v_cvt_pk_bf16_f32 v90, v90, v91
	v_lshlrev_b32_e32 v91, 16, v143
	v_and_b32_e32 v94, 0xffff0000, v143
	v_mul_f32_e32 v91, v96, v91
	v_mul_f32_e32 v94, v97, v94
	v_cvt_pk_bf16_f32 v91, v91, v94
	v_lshlrev_b32_e32 v94, 16, v144
	v_mul_f32_e32 v92, v92, v94
	v_and_b32_e32 v94, 0xffff0000, v144
	v_mul_f32_e32 v93, v93, v94
	v_cvt_pk_bf16_f32 v92, v92, v93
	v_lshlrev_b32_e32 v93, 16, v145
	v_and_b32_e32 v94, 0xffff0000, v145
	v_lshlrev_b64 v[98:99], 11, v[176:177]
	v_mul_f32_e32 v93, v100, v93
	v_mul_f32_e32 v94, v101, v94
	v_cvt_pk_bf16_f32 v93, v93, v94
	v_lshl_add_u64 v[94:95], s[74:75], 0, v[98:99]
	v_lshl_add_u64 v[94:95], v[94:95], 0, v[194:195]
	global_store_dwordx4 v[94:95], v[90:93], off
	s_nop 1
	v_pk_mul_f32 v[90:91], v[84:85], s[72:73] op_sel_hi:[1,0]
	v_pk_mul_f32 v[84:85], v[82:83], s[72:73] op_sel_hi:[1,0]
	v_lshlrev_b32_e32 v82, 16, v138
	v_and_b32_e32 v83, 0xffff0000, v138
	v_mul_f32_e32 v82, v86, v82
	v_mul_f32_e32 v83, v87, v83
	v_cvt_pk_bf16_f32 v82, v82, v83
	v_lshlrev_b32_e32 v83, 16, v139
	v_and_b32_e32 v86, 0xffff0000, v139
	v_mul_f32_e32 v83, v88, v83
	v_mul_f32_e32 v86, v89, v86
	v_cvt_pk_bf16_f32 v83, v83, v86
	v_lshlrev_b32_e32 v86, 16, v140
	v_mul_f32_e32 v84, v84, v86
	v_and_b32_e32 v86, 0xffff0000, v140
	v_mul_f32_e32 v85, v85, v86
	v_cvt_pk_bf16_f32 v84, v84, v85
	v_lshlrev_b32_e32 v85, 16, v141
	v_mul_f32_e32 v85, v90, v85
	v_and_b32_e32 v86, 0xffff0000, v141
	v_mul_f32_e32 v86, v91, v86
	v_cvt_pk_bf16_f32 v85, v85, v86
	global_store_dwordx4 v[94:95], v[82:85], off offset:256
	s_nop 1
	v_pk_mul_f32 v[84:85], v[76:77], s[72:73] op_sel_hi:[1,0]
	v_pk_mul_f32 v[76:77], v[74:75], s[72:73] op_sel_hi:[1,0]
	v_lshlrev_b32_e32 v74, 16, v134
	v_and_b32_e32 v75, 0xffff0000, v134
	v_mul_f32_e32 v74, v78, v74
	v_mul_f32_e32 v75, v79, v75
	v_cvt_pk_bf16_f32 v74, v74, v75
	v_lshlrev_b32_e32 v75, 16, v135
	v_and_b32_e32 v78, 0xffff0000, v135
	v_mul_f32_e32 v75, v80, v75
	v_mul_f32_e32 v78, v81, v78
	v_cvt_pk_bf16_f32 v75, v75, v78
	v_lshlrev_b32_e32 v78, 16, v136
	v_mul_f32_e32 v76, v76, v78
	v_and_b32_e32 v78, 0xffff0000, v136
	v_mul_f32_e32 v77, v77, v78
	v_cvt_pk_bf16_f32 v76, v76, v77
	v_lshlrev_b32_e32 v77, 16, v137
	v_and_b32_e32 v78, 0xffff0000, v137
	v_lshlrev_b64 v[82:83], 11, v[174:175]
	v_mul_f32_e32 v77, v84, v77
	v_mul_f32_e32 v78, v85, v78
	v_cvt_pk_bf16_f32 v77, v77, v78
	v_lshl_add_u64 v[78:79], s[74:75], 0, v[82:83]
	v_lshl_add_u64 v[78:79], v[78:79], 0, v[194:195]
	global_store_dwordx4 v[78:79], v[74:77], off
	s_nop 1
	v_pk_mul_f32 v[74:75], v[68:69], s[72:73] op_sel_hi:[1,0]
	v_pk_mul_f32 v[68:69], v[66:67], s[72:73] op_sel_hi:[1,0]
	v_lshlrev_b32_e32 v66, 16, v130
	v_and_b32_e32 v67, 0xffff0000, v130
	v_mul_f32_e32 v66, v70, v66
	v_mul_f32_e32 v67, v71, v67
	v_cvt_pk_bf16_f32 v66, v66, v67
	v_lshlrev_b32_e32 v67, 16, v131
	v_and_b32_e32 v70, 0xffff0000, v131
	v_mul_f32_e32 v67, v72, v67
	v_mul_f32_e32 v70, v73, v70
	v_cvt_pk_bf16_f32 v67, v67, v70
	v_lshlrev_b32_e32 v70, 16, v132
	v_mul_f32_e32 v68, v68, v70
	v_and_b32_e32 v70, 0xffff0000, v132
	v_mul_f32_e32 v69, v69, v70
	v_cvt_pk_bf16_f32 v68, v68, v69
	v_lshlrev_b32_e32 v69, 16, v133
	v_mul_f32_e32 v69, v74, v69
	v_and_b32_e32 v70, 0xffff0000, v133
	v_mul_f32_e32 v70, v75, v70
	v_cvt_pk_bf16_f32 v69, v69, v70
	global_store_dwordx4 v[78:79], v[66:69], off offset:256
	v_add_u32_e32 v78, 0x80, v172
	s_nop 0
	v_mad_i64_i32 v[66:67], s[6:7], v78, s37, v[170:171]
	v_lshl_add_u64 v[66:67], v[66:67], 0, v[194:195]
	v_add_co_u32_e32 v68, vcc, s16, v66
	v_add_u32_e32 v86, 0x90, v172
	s_nop 0
	v_addc_co_u32_e32 v69, vcc, 0, v67, vcc
	global_load_dwordx4 v[70:73], v[68:69], off offset:2048
	v_lshl_add_u64 v[66:67], v[66:67], 0, s[84:85]
	global_load_dwordx4 v[74:77], v[66:67], off offset:256
	v_pk_mul_f32 v[96:97], v[56:57], s[72:73] op_sel_hi:[1,0]
	v_mad_i64_i32 v[56:57], s[6:7], v86, s37, v[170:171]
	v_lshl_add_u64 v[56:57], v[56:57], 0, v[194:195]
	v_pk_mul_f32 v[94:95], v[58:59], s[72:73] op_sel_hi:[1,0]
	v_add_co_u32_e32 v58, vcc, s16, v56
	v_pk_mul_f32 v[92:93], v[60:61], s[72:73] op_sel_hi:[1,0]
	s_nop 0
	v_addc_co_u32_e32 v59, vcc, 0, v57, vcc
	global_load_dwordx4 v[58:61], v[58:59], off offset:2048
	v_add_u32_e32 v68, 0xa0, v172
	v_pk_mul_f32 v[102:103], v[50:51], s[72:73] op_sel_hi:[1,0]
	v_mad_i64_i32 v[50:51], s[6:7], v68, s37, v[170:171]
	v_add_u32_e32 v66, 0xb0, v172
	v_lshl_add_u64 v[50:51], v[50:51], 0, v[194:195]
	v_pk_mul_f32 v[100:101], v[52:53], s[72:73] op_sel_hi:[1,0]
	v_mad_i64_i32 v[52:53], s[6:7], v66, s37, v[170:171]
	v_lshl_add_u64 v[82:83], v[50:51], 0, s[84:85]
	v_add_co_u32_e32 v50, vcc, s16, v50
	v_lshl_add_u64 v[52:53], v[52:53], 0, v[194:195]
	s_nop 0
	v_addc_co_u32_e32 v51, vcc, 0, v51, vcc
	v_ashrrev_i32_e32 v79, 31, v78
	v_lshl_add_u64 v[104:105], v[52:53], 0, s[84:85]
	v_add_co_u32_e32 v52, vcc, s16, v52
	v_pk_mul_f32 v[98:99], v[54:55], s[72:73] op_sel_hi:[1,0]
	v_lshlrev_b64 v[54:55], 11, v[78:79]
	v_lshl_add_u64 v[56:57], v[56:57], 0, s[84:85]
	v_addc_co_u32_e32 v53, vcc, 0, v53, vcc
	v_pk_mul_f32 v[88:89], v[64:65], s[72:73] op_sel_hi:[1,0]
	v_pk_mul_f32 v[90:91], v[62:63], s[72:73] op_sel_hi:[1,0]
	v_lshl_add_u64 v[106:107], s[74:75], 0, v[54:55]
	global_load_dwordx4 v[62:65], v[56:57], off offset:256
	global_load_dwordx4 v[78:81], v[50:51], off offset:2048
	s_nop 0
	global_load_dwordx4 v[82:85], v[82:83], off offset:256
	s_nop 0
	global_load_dwordx4 v[54:57], v[52:53], off offset:2048
	s_nop 0
	global_load_dwordx4 v[50:53], v[104:105], off offset:256
	v_lshl_add_u64 v[104:105], v[106:107], 0, v[194:195]
	v_pk_mul_f32 v[46:47], v[46:47], s[72:73] op_sel_hi:[1,0]
	v_pk_mul_f32 v[48:49], v[48:49], s[72:73] op_sel_hi:[1,0]
	v_ashrrev_i32_e32 v87, 31, v86
	v_pk_mul_f32 v[38:39], v[38:39], s[72:73] op_sel_hi:[1,0]
	v_pk_mul_f32 v[40:41], v[40:41], s[72:73] op_sel_hi:[1,0]
	v_pk_mul_f32 v[30:31], v[30:31], s[72:73] op_sel_hi:[1,0]
	v_pk_mul_f32 v[32:33], v[32:33], s[72:73] op_sel_hi:[1,0]
	v_ashrrev_i32_e32 v69, 31, v68
	v_pk_mul_f32 v[22:23], v[22:23], s[72:73] op_sel_hi:[1,0]
	v_pk_mul_f32 v[24:25], v[24:25], s[72:73] op_sel_hi:[1,0]
	v_pk_mul_f32 v[14:15], v[14:15], s[72:73] op_sel_hi:[1,0]
	v_pk_mul_f32 v[16:17], v[16:17], s[72:73] op_sel_hi:[1,0]
	v_ashrrev_i32_e32 v67, 31, v66
	v_pk_mul_f32 v[6:7], v[6:7], s[72:73] op_sel_hi:[1,0]
	v_pk_mul_f32 v[8:9], v[8:9], s[72:73] op_sel_hi:[1,0]
	s_waitcnt vmcnt(0)
	v_lshlrev_b32_e32 v106, 16, v70
	v_and_b32_e32 v70, 0xffff0000, v70
	v_lshlrev_b32_e32 v107, 16, v71
	v_and_b32_e32 v71, 0xffff0000, v71
	v_lshlrev_b32_e32 v108, 16, v72
	v_and_b32_e32 v72, 0xffff0000, v72
	v_lshlrev_b32_e32 v109, 16, v73
	v_and_b32_e32 v73, 0xffff0000, v73
	v_mul_f32_e32 v70, v91, v70
	v_mul_f32_e32 v71, v89, v71
	v_mul_f32_e32 v72, v95, v72
	v_mul_f32_e32 v73, v93, v73
	v_mul_f32_e32 v90, v90, v106
	v_mul_f32_e32 v88, v88, v107
	v_mul_f32_e32 v89, v94, v108
	v_mul_f32_e32 v91, v92, v109
	v_cvt_pk_bf16_f32 v70, v90, v70
	v_cvt_pk_bf16_f32 v71, v88, v71
	v_cvt_pk_bf16_f32 v72, v89, v72
	v_cvt_pk_bf16_f32 v73, v91, v73
	v_lshlrev_b32_e32 v111, 16, v75
	v_and_b32_e32 v75, 0xffff0000, v75
	global_store_dwordx4 v[104:105], v[70:73], off
	v_lshlrev_b32_e32 v110, 16, v74
	v_and_b32_e32 v74, 0xffff0000, v74
	v_lshlrev_b32_e32 v72, 16, v76
	v_and_b32_e32 v73, 0xffff0000, v76
	v_mul_f32_e32 v71, v97, v75
	v_mul_f32_e32 v72, v102, v72
	v_mul_f32_e32 v73, v103, v73
	v_mul_f32_e32 v92, v98, v110
	v_mul_f32_e32 v74, v99, v74
	v_mul_f32_e32 v93, v96, v111
	v_cvt_pk_bf16_f32 v70, v92, v74
	v_cvt_pk_bf16_f32 v71, v93, v71
	v_cvt_pk_bf16_f32 v72, v72, v73
	v_lshlrev_b32_e32 v73, 16, v77
	v_mul_f32_e32 v73, v100, v73
	v_and_b32_e32 v74, 0xffff0000, v77
	v_mul_f32_e32 v74, v101, v74
	v_cvt_pk_bf16_f32 v73, v73, v74
	global_store_dwordx4 v[104:105], v[70:73], off offset:256
	s_nop 1
	v_pk_mul_f32 v[72:73], v[44:45], s[72:73] op_sel_hi:[1,0]
	v_pk_mul_f32 v[44:45], v[42:43], s[72:73] op_sel_hi:[1,0]
	v_lshlrev_b32_e32 v42, 16, v58
	v_and_b32_e32 v43, 0xffff0000, v58
	v_mul_f32_e32 v42, v46, v42
	v_mul_f32_e32 v43, v47, v43
	v_cvt_pk_bf16_f32 v42, v42, v43
	v_lshlrev_b32_e32 v43, 16, v59
	v_and_b32_e32 v46, 0xffff0000, v59
	v_mul_f32_e32 v43, v48, v43
	v_mul_f32_e32 v46, v49, v46
	v_cvt_pk_bf16_f32 v43, v43, v46
	v_lshlrev_b32_e32 v46, 16, v60
	v_mul_f32_e32 v44, v44, v46
	v_and_b32_e32 v46, 0xffff0000, v60
	v_mul_f32_e32 v45, v45, v46
	v_cvt_pk_bf16_f32 v44, v44, v45
	v_lshlrev_b32_e32 v45, 16, v61
	v_and_b32_e32 v46, 0xffff0000, v61
	v_lshlrev_b64 v[70:71], 11, v[86:87]
	v_mul_f32_e32 v45, v72, v45
	v_mul_f32_e32 v46, v73, v46
	v_cvt_pk_bf16_f32 v45, v45, v46
	v_lshl_add_u64 v[46:47], s[74:75], 0, v[70:71]
	v_lshl_add_u64 v[46:47], v[46:47], 0, v[194:195]
	global_store_dwordx4 v[46:47], v[42:45], off
	s_nop 1
	v_pk_mul_f32 v[42:43], v[36:37], s[72:73] op_sel_hi:[1,0]
	v_pk_mul_f32 v[36:37], v[34:35], s[72:73] op_sel_hi:[1,0]
	v_lshlrev_b32_e32 v34, 16, v62
	v_and_b32_e32 v35, 0xffff0000, v62
	v_mul_f32_e32 v34, v38, v34
	v_mul_f32_e32 v35, v39, v35
	v_cvt_pk_bf16_f32 v34, v34, v35
	v_lshlrev_b32_e32 v35, 16, v63
	v_and_b32_e32 v38, 0xffff0000, v63
	v_mul_f32_e32 v35, v40, v35
	v_mul_f32_e32 v38, v41, v38
	v_cvt_pk_bf16_f32 v35, v35, v38
	v_lshlrev_b32_e32 v38, 16, v64
	v_mul_f32_e32 v36, v36, v38
	v_and_b32_e32 v38, 0xffff0000, v64
	v_mul_f32_e32 v37, v37, v38
	v_cvt_pk_bf16_f32 v36, v36, v37
	v_lshlrev_b32_e32 v37, 16, v65
	v_mul_f32_e32 v37, v42, v37
	v_and_b32_e32 v38, 0xffff0000, v65
	v_mul_f32_e32 v38, v43, v38
	v_cvt_pk_bf16_f32 v37, v37, v38
	global_store_dwordx4 v[46:47], v[34:37], off offset:256
	s_nop 1
	v_pk_mul_f32 v[36:37], v[28:29], s[72:73] op_sel_hi:[1,0]
	v_pk_mul_f32 v[28:29], v[26:27], s[72:73] op_sel_hi:[1,0]
	v_lshlrev_b32_e32 v26, 16, v78
	v_and_b32_e32 v27, 0xffff0000, v78
	v_mul_f32_e32 v26, v30, v26
	v_mul_f32_e32 v27, v31, v27
	v_cvt_pk_bf16_f32 v26, v26, v27
	v_lshlrev_b32_e32 v27, 16, v79
	v_and_b32_e32 v30, 0xffff0000, v79
	v_mul_f32_e32 v27, v32, v27
	v_mul_f32_e32 v30, v33, v30
	v_cvt_pk_bf16_f32 v27, v27, v30
	v_lshlrev_b32_e32 v30, 16, v80
	v_mul_f32_e32 v28, v28, v30
	v_and_b32_e32 v30, 0xffff0000, v80
	v_mul_f32_e32 v29, v29, v30
	v_cvt_pk_bf16_f32 v28, v28, v29
	v_lshlrev_b32_e32 v29, 16, v81
	v_and_b32_e32 v30, 0xffff0000, v81
	v_lshlrev_b64 v[34:35], 11, v[68:69]
	v_mul_f32_e32 v29, v36, v29
	v_mul_f32_e32 v30, v37, v30
	v_cvt_pk_bf16_f32 v29, v29, v30
	v_lshl_add_u64 v[30:31], s[74:75], 0, v[34:35]
	v_lshl_add_u64 v[30:31], v[30:31], 0, v[194:195]
	global_store_dwordx4 v[30:31], v[26:29], off
	s_nop 1
	v_pk_mul_f32 v[26:27], v[20:21], s[72:73] op_sel_hi:[1,0]
	v_pk_mul_f32 v[20:21], v[18:19], s[72:73] op_sel_hi:[1,0]
	v_lshlrev_b32_e32 v18, 16, v82
	v_and_b32_e32 v19, 0xffff0000, v82
	v_mul_f32_e32 v18, v22, v18
	v_mul_f32_e32 v19, v23, v19
	v_cvt_pk_bf16_f32 v18, v18, v19
	v_lshlrev_b32_e32 v19, 16, v83
	v_and_b32_e32 v22, 0xffff0000, v83
	v_mul_f32_e32 v19, v24, v19
	v_mul_f32_e32 v22, v25, v22
	v_cvt_pk_bf16_f32 v19, v19, v22
	v_lshlrev_b32_e32 v22, 16, v84
	v_mul_f32_e32 v20, v20, v22
	v_and_b32_e32 v22, 0xffff0000, v84
	v_mul_f32_e32 v21, v21, v22
	v_cvt_pk_bf16_f32 v20, v20, v21
	v_lshlrev_b32_e32 v21, 16, v85
	v_mul_f32_e32 v21, v26, v21
	v_and_b32_e32 v22, 0xffff0000, v85
	v_mul_f32_e32 v22, v27, v22
	v_cvt_pk_bf16_f32 v21, v21, v22
	global_store_dwordx4 v[30:31], v[18:21], off offset:256
	s_nop 1
	v_pk_mul_f32 v[20:21], v[12:13], s[72:73] op_sel_hi:[1,0]
	v_pk_mul_f32 v[12:13], v[10:11], s[72:73] op_sel_hi:[1,0]
	v_lshlrev_b32_e32 v10, 16, v54
	v_and_b32_e32 v11, 0xffff0000, v54
	v_mul_f32_e32 v10, v14, v10
	v_mul_f32_e32 v11, v15, v11
	v_cvt_pk_bf16_f32 v10, v10, v11
	v_lshlrev_b32_e32 v11, 16, v55
	v_and_b32_e32 v14, 0xffff0000, v55
	v_mul_f32_e32 v11, v16, v11
	v_mul_f32_e32 v14, v17, v14
	v_cvt_pk_bf16_f32 v11, v11, v14
	v_lshlrev_b32_e32 v14, 16, v56
	v_mul_f32_e32 v12, v12, v14
	v_and_b32_e32 v14, 0xffff0000, v56
	v_mul_f32_e32 v13, v13, v14
	v_cvt_pk_bf16_f32 v12, v12, v13
	v_lshlrev_b32_e32 v13, 16, v57
	v_and_b32_e32 v14, 0xffff0000, v57
	v_lshlrev_b64 v[18:19], 11, v[66:67]
	v_mul_f32_e32 v13, v20, v13
	v_mul_f32_e32 v14, v21, v14
	v_cvt_pk_bf16_f32 v13, v13, v14
	v_lshl_add_u64 v[14:15], s[74:75], 0, v[18:19]
	v_lshl_add_u64 v[14:15], v[14:15], 0, v[194:195]
	global_store_dwordx4 v[14:15], v[10:13], off
	s_nop 1
	v_pk_mul_f32 v[10:11], v[4:5], s[72:73] op_sel_hi:[1,0]
	v_pk_mul_f32 v[4:5], v[2:3], s[72:73] op_sel_hi:[1,0]
	v_lshlrev_b32_e32 v2, 16, v50
	v_and_b32_e32 v3, 0xffff0000, v50
	v_mul_f32_e32 v2, v6, v2
	v_mul_f32_e32 v3, v7, v3
	v_cvt_pk_bf16_f32 v2, v2, v3
	v_lshlrev_b32_e32 v3, 16, v51
	v_and_b32_e32 v6, 0xffff0000, v51
	v_mul_f32_e32 v3, v8, v3
	v_mul_f32_e32 v6, v9, v6
	v_cvt_pk_bf16_f32 v3, v3, v6
	v_lshlrev_b32_e32 v6, 16, v52
	v_mul_f32_e32 v4, v4, v6
	v_and_b32_e32 v6, 0xffff0000, v52
	v_mul_f32_e32 v5, v5, v6
	v_cvt_pk_bf16_f32 v4, v4, v5
	v_lshlrev_b32_e32 v5, 16, v53
	v_mul_f32_e32 v5, v10, v5
	v_and_b32_e32 v6, 0xffff0000, v53
	v_mul_f32_e32 v6, v11, v6
	v_cvt_pk_bf16_f32 v5, v5, v6
	global_store_dwordx4 v[14:15], v[2:5], off offset:256
	s_and_b64 vcc, exec, s[62:63]
	s_mov_b32 s29, s71
	s_mov_b32 s28, s0
	s_mov_b64 s[8:9], s[60:61]
	s_mov_b64 s[6:7], s[52:53]
	s_cbranch_vccz .LBB0_252
	s_waitcnt vmcnt(0)
	v_readlane_b32 s28, v250, 12
	s_cmpk_gt_u32 s4, 0xff
	v_readlane_b32 s29, v250, 13
	s_mov_b32 s70, 0x800000
	s_cbranch_scc1 .LBB0_259
	s_barrier

.LBB0_266:
	s_add_u32 s8, s6, 0x100
	s_addc_u32 s9, s7, 0
	v_or_b32_e32 v142, 0x10000, v147
	v_add_u32_e32 v150, 0x10400, v147
	v_add_u32_e32 v154, 0x10800, v147
	v_add_u32_e32 v158, 0x10c00, v147
	s_add_u32 s10, s71, s6
	ds_read_b128 v[142:145], v142
	ds_read_b128 v[150:153], v150
	ds_read_b128 v[154:157], v154
	ds_read_b128 v[158:161], v158
	s_addc_u32 s11, s78, s7
	s_cmp_eq_u32 s79, 4
	s_cselect_b32 s81, 0, s8
	s_cselect_b32 s80, 0, s9
	s_cselect_b32 s54, s29, s10
	s_cselect_b32 s55, s5, s11
	s_add_u32 s10, s18, s81
	s_addc_u32 s11, s19, s80
	v_lshl_add_u64 v[206:207], v[138:139], 0, s[6:7]
	s_add_i32 m0, s17, 0xc000
	ds_read_b128 v[162:165], v146
	ds_read_b128 v[166:169], v146 offset:1024
	ds_read_b128 v[170:173], v146 offset:2048
	ds_read_b128 v[174:177], v146 offset:3072
	ds_read_b128 v[178:181], v146 offset:4096
	ds_read_b128 v[182:185], v146 offset:5120
	ds_read_b128 v[186:189], v146 offset:6144
	ds_read_b128 v[190:193], v146 offset:7168
	global_load_lds_dwordx4 v[206:207], off
	v_lshl_add_u64 v[206:207], v[140:141], 0, s[6:7]
	s_add_i32 m0, s17, 0xe000
	s_nop 0
	global_load_lds_dwordx4 v[206:207], off
	s_waitcnt lgkmcnt(8)
	s_setprio 1
	s_barrier
	s_waitcnt lgkmcnt(0)
	v_mfma_f32_16x16x32_bf16 v[126:129], v[142:145], v[162:165], v[126:129]
	v_mfma_f32_16x16x32_bf16 v[122:125], v[154:157], v[162:165], v[122:125]
	v_mfma_f32_16x16x32_bf16 v[110:113], v[142:145], v[170:173], v[110:113]
	v_mfma_f32_16x16x32_bf16 v[106:109], v[154:157], v[170:173], v[106:109]
	v_mfma_f32_16x16x32_bf16 v[94:97], v[142:145], v[178:181], v[94:97]
	v_mfma_f32_16x16x32_bf16 v[90:93], v[154:157], v[178:181], v[90:93]
	v_mfma_f32_16x16x32_bf16 v[78:81], v[142:145], v[186:189], v[78:81]
	v_mfma_f32_16x16x32_bf16 v[74:77], v[154:157], v[186:189], v[74:77]
	v_mfma_f32_16x16x32_bf16 v[126:129], v[150:153], v[166:169], v[126:129]
	v_mfma_f32_16x16x32_bf16 v[122:125], v[158:161], v[166:169], v[122:125]
	v_mfma_f32_16x16x32_bf16 v[110:113], v[150:153], v[174:177], v[110:113]
	v_mfma_f32_16x16x32_bf16 v[106:109], v[158:161], v[174:177], v[106:109]
	v_mfma_f32_16x16x32_bf16 v[94:97], v[150:153], v[182:185], v[94:97]
	v_mfma_f32_16x16x32_bf16 v[90:93], v[158:161], v[182:185], v[90:93]
	v_mfma_f32_16x16x32_bf16 v[78:81], v[150:153], v[190:193], v[78:81]
	v_mfma_f32_16x16x32_bf16 v[74:77], v[158:161], v[190:193], v[74:77]
	s_barrier
	s_setprio 0
	v_or_b32_e32 v194, 0x14000, v147
	s_mov_b32 m0, s26
	v_add_u32_e32 v197, 0x14400, v147
	ds_read_b128 v[206:209], v194
	ds_read_b128 v[210:213], v197
	v_add_u32_e32 v194, 0x14800, v147
	v_lshl_add_u64 v[222:223], s[54:55], 0, v[134:135]
	v_add_u32_e32 v197, 0x14c00, v147
	ds_read_b128 v[214:217], v194
	ds_read_b128 v[218:221], v197
	global_load_lds_dwordx4 v[222:223], off
	v_lshl_add_u64 v[224:225], s[54:55], 0, v[130:131]
	s_mov_b32 m0, s34
	s_nop 0
	global_load_lds_dwordx4 v[224:225], off
	s_setprio 1
	s_barrier
	s_waitcnt lgkmcnt(0)
	v_mfma_f32_16x16x32_bf16 v[118:121], v[206:209], v[162:165], v[118:121]
	v_mfma_f32_16x16x32_bf16 v[114:117], v[214:217], v[162:165], v[114:117]
	v_mfma_f32_16x16x32_bf16 v[102:105], v[206:209], v[170:173], v[102:105]
	v_mfma_f32_16x16x32_bf16 v[98:101], v[214:217], v[170:173], v[98:101]
	v_mfma_f32_16x16x32_bf16 v[86:89], v[206:209], v[178:181], v[86:89]
	v_mfma_f32_16x16x32_bf16 v[82:85], v[214:217], v[178:181], v[82:85]
	v_mfma_f32_16x16x32_bf16 v[70:73], v[206:209], v[186:189], v[70:73]
	v_mfma_f32_16x16x32_bf16 v[66:69], v[214:217], v[186:189], v[66:69]
	v_mfma_f32_16x16x32_bf16 v[118:121], v[210:213], v[166:169], v[118:121]
	v_mfma_f32_16x16x32_bf16 v[114:117], v[218:221], v[166:169], v[114:117]
	v_mfma_f32_16x16x32_bf16 v[102:105], v[210:213], v[174:177], v[102:105]
	v_mfma_f32_16x16x32_bf16 v[98:101], v[218:221], v[174:177], v[98:101]
	v_mfma_f32_16x16x32_bf16 v[86:89], v[210:213], v[182:185], v[86:89]
	v_mfma_f32_16x16x32_bf16 v[82:85], v[218:221], v[182:185], v[82:85]
	s_mov_b32 m0, s17
	v_mfma_f32_16x16x32_bf16 v[70:73], v[210:213], v[190:193], v[70:73]
	v_lshl_add_u64 v[226:227], s[10:11], 0, v[136:137]
	v_mfma_f32_16x16x32_bf16 v[66:69], v[218:221], v[190:193], v[66:69]
	s_barrier
	s_setprio 0
	ds_read_b128 v[162:165], v146 offset:16384
	ds_read_b128 v[166:169], v146 offset:17408
	ds_read_b128 v[170:173], v146 offset:18432
	ds_read_b128 v[174:177], v146 offset:19456
	ds_read_b128 v[178:181], v146 offset:20480
	ds_read_b128 v[182:185], v146 offset:21504
	ds_read_b128 v[186:189], v146 offset:22528
	ds_read_b128 v[190:193], v146 offset:23552
	global_load_lds_dwordx4 v[226:227], off
	v_lshl_add_u64 v[228:229], s[10:11], 0, v[132:133]
	s_mov_b32 m0, s35
	s_nop 0
	global_load_lds_dwordx4 v[228:229], off
	s_setprio 1
	s_barrier
	s_waitcnt lgkmcnt(0)
	v_mfma_f32_16x16x32_bf16 v[62:65], v[142:145], v[162:165], v[62:65]
	v_mfma_f32_16x16x32_bf16 v[58:61], v[154:157], v[162:165], v[58:61]
	v_mfma_f32_16x16x32_bf16 v[46:49], v[142:145], v[170:173], v[46:49]
	v_mfma_f32_16x16x32_bf16 v[42:45], v[154:157], v[170:173], v[42:45]
	v_mfma_f32_16x16x32_bf16 v[30:33], v[142:145], v[178:181], v[30:33]
	v_mfma_f32_16x16x32_bf16 v[26:29], v[154:157], v[178:181], v[26:29]
	v_mfma_f32_16x16x32_bf16 v[14:17], v[142:145], v[186:189], v[14:17]
	v_mfma_f32_16x16x32_bf16 v[10:13], v[154:157], v[186:189], v[10:13]
	v_mfma_f32_16x16x32_bf16 v[62:65], v[150:153], v[166:169], v[62:65]
	v_mfma_f32_16x16x32_bf16 v[58:61], v[158:161], v[166:169], v[58:61]
	v_mfma_f32_16x16x32_bf16 v[46:49], v[150:153], v[174:177], v[46:49]
	v_mfma_f32_16x16x32_bf16 v[42:45], v[158:161], v[174:177], v[42:45]
	v_mfma_f32_16x16x32_bf16 v[30:33], v[150:153], v[182:185], v[30:33]
	v_mfma_f32_16x16x32_bf16 v[26:29], v[158:161], v[182:185], v[26:29]
	v_mfma_f32_16x16x32_bf16 v[14:17], v[150:153], v[190:193], v[14:17]
	v_mfma_f32_16x16x32_bf16 v[10:13], v[158:161], v[190:193], v[10:13]
	s_barrier
	s_setprio 0
	s_add_u32 s6, s54, 0x20000
	s_addc_u32 s7, s55, 0
	s_mov_b32 m0, s42
	v_lshl_add_u64 v[142:143], s[6:7], 0, v[134:135]
	global_load_lds_dwordx4 v[142:143], off
	v_lshl_add_u64 v[142:143], s[6:7], 0, v[130:131]
	s_mov_b32 m0, s56
	s_nop 0
	global_load_lds_dwordx4 v[142:143], off
	s_waitcnt vmcnt(6)
	s_setprio 1
	s_barrier
	v_mfma_f32_16x16x32_bf16 v[54:57], v[206:209], v[162:165], v[54:57]
	v_mfma_f32_16x16x32_bf16 v[50:53], v[214:217], v[162:165], v[50:53]
	v_mfma_f32_16x16x32_bf16 v[38:41], v[206:209], v[170:173], v[38:41]
	v_mfma_f32_16x16x32_bf16 v[34:37], v[214:217], v[170:173], v[34:37]
	v_mfma_f32_16x16x32_bf16 v[22:25], v[206:209], v[178:181], v[22:25]
	v_mfma_f32_16x16x32_bf16 v[18:21], v[214:217], v[178:181], v[18:21]
	v_mfma_f32_16x16x32_bf16 v[6:9], v[206:209], v[186:189], v[6:9]
	v_mfma_f32_16x16x32_bf16 v[2:5], v[214:217], v[186:189], v[2:5]
	v_mfma_f32_16x16x32_bf16 v[54:57], v[210:213], v[166:169], v[54:57]
	v_mfma_f32_16x16x32_bf16 v[50:53], v[218:221], v[166:169], v[50:53]
	v_mfma_f32_16x16x32_bf16 v[38:41], v[210:213], v[174:177], v[38:41]
	v_mfma_f32_16x16x32_bf16 v[34:37], v[218:221], v[174:177], v[34:37]
	v_or_b32_e32 v142, 0x18000, v147
	v_mfma_f32_16x16x32_bf16 v[22:25], v[210:213], v[182:185], v[22:25]
	v_add_u32_e32 v150, 0x18400, v147
	v_mfma_f32_16x16x32_bf16 v[18:21], v[218:221], v[182:185], v[18:21]
	v_add_u32_e32 v154, 0x18800, v147
	v_mfma_f32_16x16x32_bf16 v[6:9], v[210:213], v[190:193], v[6:9]
	v_add_u32_e32 v158, 0x18c00, v147
	v_mfma_f32_16x16x32_bf16 v[2:5], v[218:221], v[190:193], v[2:5]
	s_barrier
	s_setprio 0
	ds_read_b128 v[142:145], v142
	ds_read_b128 v[150:153], v150
	ds_read_b128 v[154:157], v154
	ds_read_b128 v[158:161], v158
	s_add_u32 s6, s10, 0x20000
	s_addc_u32 s7, s11, 0
	s_mov_b32 m0, s57
	v_lshl_add_u64 v[206:207], s[6:7], 0, v[136:137]
	ds_read_b128 v[162:165], v146 offset:32768
	ds_read_b128 v[166:169], v146 offset:33792
	ds_read_b128 v[170:173], v146 offset:34816
	ds_read_b128 v[174:177], v146 offset:35840
	ds_read_b128 v[178:181], v146 offset:36864
	ds_read_b128 v[182:185], v146 offset:37888
	ds_read_b128 v[186:189], v146 offset:38912
	ds_read_b128 v[190:193], v146 offset:39936
	global_load_lds_dwordx4 v[206:207], off
	v_lshl_add_u64 v[206:207], s[6:7], 0, v[132:133]
	s_mov_b32 m0, s58
	s_nop 0
	global_load_lds_dwordx4 v[206:207], off
	s_waitcnt lgkmcnt(8)
	s_setprio 1
	s_barrier
	s_waitcnt lgkmcnt(0)
	v_mfma_f32_16x16x32_bf16 v[126:129], v[142:145], v[162:165], v[126:129]
	v_mfma_f32_16x16x32_bf16 v[122:125], v[154:157], v[162:165], v[122:125]
	v_mfma_f32_16x16x32_bf16 v[110:113], v[142:145], v[170:173], v[110:113]
	v_mfma_f32_16x16x32_bf16 v[106:109], v[154:157], v[170:173], v[106:109]
	v_mfma_f32_16x16x32_bf16 v[94:97], v[142:145], v[178:181], v[94:97]
	v_mfma_f32_16x16x32_bf16 v[90:93], v[154:157], v[178:181], v[90:93]
	v_mfma_f32_16x16x32_bf16 v[78:81], v[142:145], v[186:189], v[78:81]
	v_mfma_f32_16x16x32_bf16 v[74:77], v[154:157], v[186:189], v[74:77]
	v_mfma_f32_16x16x32_bf16 v[126:129], v[150:153], v[166:169], v[126:129]
	v_mfma_f32_16x16x32_bf16 v[122:125], v[158:161], v[166:169], v[122:125]
	v_mfma_f32_16x16x32_bf16 v[110:113], v[150:153], v[174:177], v[110:113]
	v_mfma_f32_16x16x32_bf16 v[106:109], v[158:161], v[174:177], v[106:109]
	v_mfma_f32_16x16x32_bf16 v[94:97], v[150:153], v[182:185], v[94:97]
	v_mfma_f32_16x16x32_bf16 v[90:93], v[158:161], v[182:185], v[90:93]
	v_mfma_f32_16x16x32_bf16 v[78:81], v[150:153], v[190:193], v[78:81]
	v_mfma_f32_16x16x32_bf16 v[74:77], v[158:161], v[190:193], v[74:77]
	s_barrier
	s_setprio 0
	v_or_b32_e32 v194, 0x1c000, v147
	s_mov_b32 m0, s59
	v_add_u32_e32 v197, 0x1c400, v147
	ds_read_b128 v[206:209], v194
	ds_read_b128 v[210:213], v197
	v_add_u32_e32 v194, 0x1c800, v147
	v_lshl_add_u64 v[222:223], v[222:223], 0, s[76:77]
	v_add_u32_e32 v197, 0x1cc00, v147
	ds_read_b128 v[214:217], v194
	ds_read_b128 v[218:221], v197
	global_load_lds_dwordx4 v[222:223], off
	v_lshl_add_u64 v[222:223], v[224:225], 0, s[76:77]
	s_mov_b32 m0, s60
	s_nop 0
	global_load_lds_dwordx4 v[222:223], off
	s_setprio 1
	s_barrier
	s_waitcnt lgkmcnt(0)
	v_mfma_f32_16x16x32_bf16 v[118:121], v[206:209], v[162:165], v[118:121]
	v_mfma_f32_16x16x32_bf16 v[114:117], v[214:217], v[162:165], v[114:117]
	v_mfma_f32_16x16x32_bf16 v[102:105], v[206:209], v[170:173], v[102:105]
	v_mfma_f32_16x16x32_bf16 v[98:101], v[214:217], v[170:173], v[98:101]
	v_mfma_f32_16x16x32_bf16 v[86:89], v[206:209], v[178:181], v[86:89]
	v_mfma_f32_16x16x32_bf16 v[82:85], v[214:217], v[178:181], v[82:85]
	v_mfma_f32_16x16x32_bf16 v[70:73], v[206:209], v[186:189], v[70:73]
	v_mfma_f32_16x16x32_bf16 v[66:69], v[214:217], v[186:189], v[66:69]
	v_mfma_f32_16x16x32_bf16 v[118:121], v[210:213], v[166:169], v[118:121]
	v_mfma_f32_16x16x32_bf16 v[114:117], v[218:221], v[166:169], v[114:117]
	v_mfma_f32_16x16x32_bf16 v[102:105], v[210:213], v[174:177], v[102:105]
	v_mfma_f32_16x16x32_bf16 v[98:101], v[218:221], v[174:177], v[98:101]
	v_mfma_f32_16x16x32_bf16 v[86:89], v[210:213], v[182:185], v[86:89]
	v_mfma_f32_16x16x32_bf16 v[82:85], v[218:221], v[182:185], v[82:85]
	s_mov_b32 m0, s61
	v_mfma_f32_16x16x32_bf16 v[70:73], v[210:213], v[190:193], v[70:73]
	v_lshl_add_u64 v[222:223], v[226:227], 0, s[76:77]
	v_mfma_f32_16x16x32_bf16 v[66:69], v[218:221], v[190:193], v[66:69]
	s_barrier
	s_setprio 0
	ds_read_b128 v[162:165], v146 offset:49152
	ds_read_b128 v[166:169], v146 offset:50176
	ds_read_b128 v[170:173], v146 offset:51200
	ds_read_b128 v[174:177], v146 offset:52224
	ds_read_b128 v[178:181], v146 offset:53248
	ds_read_b128 v[182:185], v146 offset:54272
	ds_read_b128 v[186:189], v146 offset:55296
	ds_read_b128 v[190:193], v146 offset:56320
	global_load_lds_dwordx4 v[222:223], off
	v_lshl_add_u64 v[222:223], v[228:229], 0, s[76:77]
	s_mov_b32 m0, s62
	s_nop 0
	global_load_lds_dwordx4 v[222:223], off
	s_setprio 1
	s_barrier
	s_waitcnt lgkmcnt(0)
	v_mfma_f32_16x16x32_bf16 v[62:65], v[142:145], v[162:165], v[62:65]
	v_mfma_f32_16x16x32_bf16 v[58:61], v[154:157], v[162:165], v[58:61]
	v_mfma_f32_16x16x32_bf16 v[46:49], v[142:145], v[170:173], v[46:49]
	v_mfma_f32_16x16x32_bf16 v[42:45], v[154:157], v[170:173], v[42:45]
	v_mfma_f32_16x16x32_bf16 v[30:33], v[142:145], v[178:181], v[30:33]
	v_mfma_f32_16x16x32_bf16 v[26:29], v[154:157], v[178:181], v[26:29]
	v_mfma_f32_16x16x32_bf16 v[14:17], v[142:145], v[186:189], v[14:17]
	v_mfma_f32_16x16x32_bf16 v[10:13], v[154:157], v[186:189], v[10:13]
	v_mfma_f32_16x16x32_bf16 v[62:65], v[150:153], v[166:169], v[62:65]
	v_mfma_f32_16x16x32_bf16 v[58:61], v[158:161], v[166:169], v[58:61]
	v_mfma_f32_16x16x32_bf16 v[46:49], v[150:153], v[174:177], v[46:49]
	v_mfma_f32_16x16x32_bf16 v[42:45], v[158:161], v[174:177], v[42:45]
	v_mfma_f32_16x16x32_bf16 v[30:33], v[150:153], v[182:185], v[30:33]
	v_mfma_f32_16x16x32_bf16 v[26:29], v[158:161], v[182:185], v[26:29]
	v_mfma_f32_16x16x32_bf16 v[14:17], v[150:153], v[190:193], v[14:17]
	v_mfma_f32_16x16x32_bf16 v[10:13], v[158:161], v[190:193], v[10:13]
	s_barrier
	s_setprio 0
	s_add_u32 s6, s54, 0x20080
	s_addc_u32 s7, s55, 0
	s_mov_b32 m0, s63
	v_lshl_add_u64 v[142:143], s[6:7], 0, v[134:135]
	global_load_lds_dwordx4 v[142:143], off
	v_lshl_add_u64 v[142:143], s[6:7], 0, v[130:131]
	s_mov_b32 m0, s67
	s_nop 0
	global_load_lds_dwordx4 v[142:143], off
	s_waitcnt vmcnt(6)
	s_setprio 1
	s_barrier
	v_mfma_f32_16x16x32_bf16 v[54:57], v[206:209], v[162:165], v[54:57]
	v_mfma_f32_16x16x32_bf16 v[50:53], v[214:217], v[162:165], v[50:53]
	v_mfma_f32_16x16x32_bf16 v[38:41], v[206:209], v[170:173], v[38:41]
	v_mfma_f32_16x16x32_bf16 v[34:37], v[214:217], v[170:173], v[34:37]
	v_mfma_f32_16x16x32_bf16 v[22:25], v[206:209], v[178:181], v[22:25]
	v_mfma_f32_16x16x32_bf16 v[18:21], v[214:217], v[178:181], v[18:21]
	v_mfma_f32_16x16x32_bf16 v[6:9], v[206:209], v[186:189], v[6:9]
	v_mfma_f32_16x16x32_bf16 v[2:5], v[214:217], v[186:189], v[2:5]
	v_mfma_f32_16x16x32_bf16 v[54:57], v[210:213], v[166:169], v[54:57]
	v_mfma_f32_16x16x32_bf16 v[50:53], v[218:221], v[166:169], v[50:53]
	v_mfma_f32_16x16x32_bf16 v[38:41], v[210:213], v[174:177], v[38:41]
	v_mfma_f32_16x16x32_bf16 v[34:37], v[218:221], v[174:177], v[34:37]
	v_mfma_f32_16x16x32_bf16 v[22:25], v[210:213], v[182:185], v[22:25]
	v_mfma_f32_16x16x32_bf16 v[18:21], v[218:221], v[182:185], v[18:21]
	v_mfma_f32_16x16x32_bf16 v[6:9], v[210:213], v[190:193], v[6:9]
	v_mfma_f32_16x16x32_bf16 v[2:5], v[218:221], v[190:193], v[2:5]
	s_setprio 0
	s_add_i32 s79, s79, 2
	s_cmp_gt_u32 s79, 5
	s_mov_b64 s[6:7], s[8:9]
	s_barrier
	s_cbranch_scc0 .LBB0_266
	s_lshl_b32 s5, s28, 6
	s_and_b32 s5, s5, 0xffffff00
	v_add_u32_e32 v144, s5, v148
	s_lshl_b32 s5, s28, 8
	s_and_b32 s5, s5, 0x300
	v_or_b32_e32 v145, s5, v149
	v_mov_b64_e32 v[142:143], s[50:51]
	v_mad_i64_i32 v[150:151], s[6:7], v144, s37, v[142:143]
	v_lshlrev_b32_e32 v194, 1, v145
	v_lshl_add_u64 v[154:155], v[150:151], 0, v[194:195]
	v_add_co_u32_e32 v150, vcc, 0x1000, v154
	v_or_b32_e32 v184, 16, v144
	s_nop 0
	v_addc_co_u32_e32 v151, vcc, 0, v155, vcc
	global_load_dwordx4 v[150:153], v[150:151], off offset:2048
	v_lshl_add_u64 v[154:155], v[154:155], 0, s[84:85]
	global_load_dwordx4 v[154:157], v[154:155], off offset:256
	v_pk_mul_f32 v[182:183], v[114:115], s[36:37] op_sel_hi:[1,0]
	v_mad_i64_i32 v[114:115], s[6:7], v184, s37, v[142:143]
	v_lshl_add_u64 v[114:115], v[114:115], 0, v[194:195]
	v_pk_mul_f32 v[180:181], v[116:117], s[36:37] op_sel_hi:[1,0]
	v_add_co_u32_e32 v116, vcc, 0x1000, v114
	v_pk_mul_f32 v[170:171], v[126:127], s[36:37] op_sel_hi:[1,0]
	s_nop 0
	v_addc_co_u32_e32 v117, vcc, 0, v115, vcc
	v_pk_mul_f32 v[172:173], v[124:125], s[36:37] op_sel_hi:[1,0]
	global_load_dwordx4 v[124:127], v[116:117], off offset:2048
	v_lshl_add_u64 v[114:115], v[114:115], 0, s[84:85]
	global_load_dwordx4 v[158:161], v[114:115], off offset:256
	v_or_b32_e32 v186, 32, v144
	v_mad_i64_i32 v[116:117], s[6:7], v186, s37, v[142:143]
	v_lshl_add_u64 v[116:117], v[116:117], 0, v[194:195]
	v_lshl_add_u64 v[166:167], v[116:117], 0, s[84:85]
	v_add_co_u32_e32 v116, vcc, 0x1000, v116
	v_pk_mul_f32 v[174:175], v[122:123], s[36:37] op_sel_hi:[1,0]
	s_nop 0
	v_addc_co_u32_e32 v117, vcc, 0, v117, vcc
	global_load_dwordx4 v[162:165], v[116:117], off offset:2048
	s_nop 0
	global_load_dwordx4 v[166:169], v[166:167], off offset:256
	v_or_b32_e32 v122, 48, v144
	v_pk_mul_f32 v[178:179], v[118:119], s[36:37] op_sel_hi:[1,0]
	v_mad_i64_i32 v[118:119], s[6:7], v122, s37, v[142:143]
	v_ashrrev_i32_e32 v145, 31, v144
	v_lshl_add_u64 v[118:119], v[118:119], 0, v[194:195]
	v_pk_mul_f32 v[176:177], v[120:121], s[36:37] op_sel_hi:[1,0]
	v_lshlrev_b64 v[120:121], 11, v[144:145]
	v_add_co_u32_e32 v114, vcc, 0x1000, v118
	v_lshl_add_u64 v[120:121], s[74:75], 0, v[120:121]
	s_nop 0
	v_addc_co_u32_e32 v115, vcc, 0, v119, vcc
	v_lshl_add_u64 v[188:189], v[118:119], 0, s[84:85]
	v_lshl_add_u64 v[190:191], v[120:121], 0, v[194:195]
	global_load_dwordx4 v[118:121], v[114:115], off offset:2048
	s_nop 0
	global_load_dwordx4 v[114:117], v[188:189], off offset:256
	v_pk_mul_f32 v[128:129], v[128:129], s[36:37] op_sel_hi:[1,0]
	v_pk_mul_f32 v[110:111], v[110:111], s[36:37] op_sel_hi:[1,0]
	v_pk_mul_f32 v[112:113], v[112:113], s[36:37] op_sel_hi:[1,0]
	v_ashrrev_i32_e32 v185, 31, v184
	v_pk_mul_f32 v[102:103], v[102:103], s[36:37] op_sel_hi:[1,0]
	v_pk_mul_f32 v[104:105], v[104:105], s[36:37] op_sel_hi:[1,0]
	v_pk_mul_f32 v[94:95], v[94:95], s[36:37] op_sel_hi:[1,0]
	v_pk_mul_f32 v[96:97], v[96:97], s[36:37] op_sel_hi:[1,0]
	v_ashrrev_i32_e32 v187, 31, v186
	v_pk_mul_f32 v[86:87], v[86:87], s[36:37] op_sel_hi:[1,0]
	v_pk_mul_f32 v[88:89], v[88:89], s[36:37] op_sel_hi:[1,0]
	v_pk_mul_f32 v[78:79], v[78:79], s[36:37] op_sel_hi:[1,0]
	v_pk_mul_f32 v[80:81], v[80:81], s[36:37] op_sel_hi:[1,0]
	v_ashrrev_i32_e32 v123, 31, v122
	v_pk_mul_f32 v[70:71], v[70:71], s[36:37] op_sel_hi:[1,0]
	v_pk_mul_f32 v[72:73], v[72:73], s[36:37] op_sel_hi:[1,0]
	s_waitcnt vmcnt(0)
	v_lshlrev_b32_e32 v145, 16, v150
	v_and_b32_e32 v150, 0xffff0000, v150
	v_lshlrev_b32_e32 v188, 16, v151
	v_and_b32_e32 v151, 0xffff0000, v151
	v_mul_f32_e32 v150, v171, v150
	v_mul_f32_e32 v128, v128, v188
	v_mul_f32_e32 v129, v129, v151
	v_lshlrev_b32_e32 v189, 16, v152
	v_and_b32_e32 v152, 0xffff0000, v152
	v_lshlrev_b32_e32 v192, 16, v153
	v_and_b32_e32 v153, 0xffff0000, v153
	v_mul_f32_e32 v145, v170, v145
	v_cvt_pk_bf16_f32 v150, v145, v150
	v_cvt_pk_bf16_f32 v151, v128, v129
	v_lshlrev_b32_e32 v128, 16, v154
	v_and_b32_e32 v129, 0xffff0000, v154
	v_mul_f32_e32 v152, v175, v152
	v_mul_f32_e32 v153, v173, v153
	v_mul_f32_e32 v128, v178, v128
	v_mul_f32_e32 v129, v179, v129
	v_mul_f32_e32 v170, v174, v189
	v_mul_f32_e32 v171, v172, v192
	v_cvt_pk_bf16_f32 v152, v170, v152
	v_cvt_pk_bf16_f32 v153, v171, v153
	global_store_dwordx4 v[190:191], v[150:153], off
	s_nop 1
	v_cvt_pk_bf16_f32 v150, v128, v129
	v_lshlrev_b32_e32 v128, 16, v155
	v_and_b32_e32 v129, 0xffff0000, v155
	v_mul_f32_e32 v128, v176, v128
	v_mul_f32_e32 v129, v177, v129
	v_cvt_pk_bf16_f32 v151, v128, v129
	v_lshlrev_b32_e32 v128, 16, v156
	v_and_b32_e32 v129, 0xffff0000, v156
	v_mul_f32_e32 v128, v182, v128
	v_mul_f32_e32 v129, v183, v129
	v_cvt_pk_bf16_f32 v152, v128, v129
	v_lshlrev_b32_e32 v128, 16, v157
	v_and_b32_e32 v129, 0xffff0000, v157
	v_mul_f32_e32 v128, v180, v128
	v_mul_f32_e32 v129, v181, v129
	v_cvt_pk_bf16_f32 v153, v128, v129
	global_store_dwordx4 v[190:191], v[150:153], off offset:256
	v_lshlrev_b64 v[128:129], 11, v[184:185]
	s_nop 0
	v_pk_mul_f32 v[150:151], v[108:109], s[36:37] op_sel_hi:[1,0]
	v_pk_mul_f32 v[108:109], v[106:107], s[36:37] op_sel_hi:[1,0]
	v_lshlrev_b32_e32 v106, 16, v124
	v_and_b32_e32 v107, 0xffff0000, v124
	v_mul_f32_e32 v106, v110, v106
	v_mul_f32_e32 v107, v111, v107
	v_cvt_pk_bf16_f32 v106, v106, v107
	v_lshlrev_b32_e32 v107, 16, v125
	v_and_b32_e32 v110, 0xffff0000, v125
	v_mul_f32_e32 v107, v112, v107
	v_mul_f32_e32 v110, v113, v110
	v_cvt_pk_bf16_f32 v107, v107, v110
	v_lshlrev_b32_e32 v110, 16, v126
	v_mul_f32_e32 v108, v108, v110
	v_and_b32_e32 v110, 0xffff0000, v126
	v_mul_f32_e32 v109, v109, v110
	v_cvt_pk_bf16_f32 v108, v108, v109
	v_lshlrev_b32_e32 v109, 16, v127
	v_and_b32_e32 v110, 0xffff0000, v127
	v_mul_f32_e32 v109, v150, v109
	v_mul_f32_e32 v110, v151, v110
	v_cvt_pk_bf16_f32 v109, v109, v110
	v_lshl_add_u64 v[110:111], s[74:75], 0, v[128:129]
	v_lshl_add_u64 v[110:111], v[110:111], 0, v[194:195]
	global_store_dwordx4 v[110:111], v[106:109], off
	s_nop 1
	v_pk_mul_f32 v[106:107], v[100:101], s[36:37] op_sel_hi:[1,0]
	v_pk_mul_f32 v[100:101], v[98:99], s[36:37] op_sel_hi:[1,0]
	v_lshlrev_b32_e32 v98, 16, v158
	v_and_b32_e32 v99, 0xffff0000, v158
	v_mul_f32_e32 v98, v102, v98
	v_mul_f32_e32 v99, v103, v99
	v_cvt_pk_bf16_f32 v98, v98, v99
	v_lshlrev_b32_e32 v99, 16, v159
	v_and_b32_e32 v102, 0xffff0000, v159
	v_mul_f32_e32 v99, v104, v99
	v_mul_f32_e32 v102, v105, v102
	v_cvt_pk_bf16_f32 v99, v99, v102
	v_lshlrev_b32_e32 v102, 16, v160
	v_mul_f32_e32 v100, v100, v102
	v_and_b32_e32 v102, 0xffff0000, v160
	v_mul_f32_e32 v101, v101, v102
	v_cvt_pk_bf16_f32 v100, v100, v101
	v_lshlrev_b32_e32 v101, 16, v161
	v_mul_f32_e32 v101, v106, v101
	v_and_b32_e32 v102, 0xffff0000, v161
	v_mul_f32_e32 v102, v107, v102
	v_cvt_pk_bf16_f32 v101, v101, v102
	global_store_dwordx4 v[110:111], v[98:101], off offset:256
	s_nop 1
	v_pk_mul_f32 v[100:101], v[92:93], s[36:37] op_sel_hi:[1,0]
	v_pk_mul_f32 v[92:93], v[90:91], s[36:37] op_sel_hi:[1,0]
	v_lshlrev_b32_e32 v90, 16, v162
	v_and_b32_e32 v91, 0xffff0000, v162
	v_mul_f32_e32 v90, v94, v90
	v_mul_f32_e32 v91, v95, v91
	v_cvt_pk_bf16_f32 v90, v90, v91
	v_lshlrev_b32_e32 v91, 16, v163
	v_and_b32_e32 v94, 0xffff0000, v163
	v_mul_f32_e32 v91, v96, v91
	v_mul_f32_e32 v94, v97, v94
	v_cvt_pk_bf16_f32 v91, v91, v94
	v_lshlrev_b32_e32 v94, 16, v164
	v_mul_f32_e32 v92, v92, v94
	v_and_b32_e32 v94, 0xffff0000, v164
	v_mul_f32_e32 v93, v93, v94
	v_cvt_pk_bf16_f32 v92, v92, v93
	v_lshlrev_b32_e32 v93, 16, v165
	v_and_b32_e32 v94, 0xffff0000, v165
	v_lshlrev_b64 v[98:99], 11, v[186:187]
	v_mul_f32_e32 v93, v100, v93
	v_mul_f32_e32 v94, v101, v94
	v_cvt_pk_bf16_f32 v93, v93, v94
	v_lshl_add_u64 v[94:95], s[74:75], 0, v[98:99]
	v_lshl_add_u64 v[94:95], v[94:95], 0, v[194:195]
	global_store_dwordx4 v[94:95], v[90:93], off
	s_nop 1
	v_pk_mul_f32 v[90:91], v[84:85], s[36:37] op_sel_hi:[1,0]
	v_pk_mul_f32 v[84:85], v[82:83], s[36:37] op_sel_hi:[1,0]
	v_lshlrev_b32_e32 v82, 16, v166
	v_and_b32_e32 v83, 0xffff0000, v166
	v_mul_f32_e32 v82, v86, v82
	v_mul_f32_e32 v83, v87, v83
	v_cvt_pk_bf16_f32 v82, v82, v83
	v_lshlrev_b32_e32 v83, 16, v167
	v_and_b32_e32 v86, 0xffff0000, v167
	v_mul_f32_e32 v83, v88, v83
	v_mul_f32_e32 v86, v89, v86
	v_cvt_pk_bf16_f32 v83, v83, v86
	v_lshlrev_b32_e32 v86, 16, v168
	v_mul_f32_e32 v84, v84, v86
	v_and_b32_e32 v86, 0xffff0000, v168
	v_mul_f32_e32 v85, v85, v86
	v_cvt_pk_bf16_f32 v84, v84, v85
	v_lshlrev_b32_e32 v85, 16, v169
	v_mul_f32_e32 v85, v90, v85
	v_and_b32_e32 v86, 0xffff0000, v169
	v_mul_f32_e32 v86, v91, v86
	v_cvt_pk_bf16_f32 v85, v85, v86
	global_store_dwordx4 v[94:95], v[82:85], off offset:256
	s_nop 1
	v_pk_mul_f32 v[84:85], v[76:77], s[36:37] op_sel_hi:[1,0]
	v_pk_mul_f32 v[76:77], v[74:75], s[36:37] op_sel_hi:[1,0]
	v_lshlrev_b32_e32 v74, 16, v118
	v_and_b32_e32 v75, 0xffff0000, v118
	v_mul_f32_e32 v74, v78, v74
	v_mul_f32_e32 v75, v79, v75
	v_cvt_pk_bf16_f32 v74, v74, v75
	v_lshlrev_b32_e32 v75, 16, v119
	v_and_b32_e32 v78, 0xffff0000, v119
	v_mul_f32_e32 v75, v80, v75
	v_mul_f32_e32 v78, v81, v78
	v_cvt_pk_bf16_f32 v75, v75, v78
	v_lshlrev_b32_e32 v78, 16, v120
	v_mul_f32_e32 v76, v76, v78
	v_and_b32_e32 v78, 0xffff0000, v120
	v_mul_f32_e32 v77, v77, v78
	v_cvt_pk_bf16_f32 v76, v76, v77
	v_lshlrev_b32_e32 v77, 16, v121
	v_and_b32_e32 v78, 0xffff0000, v121
	v_lshlrev_b64 v[82:83], 11, v[122:123]
	v_mul_f32_e32 v77, v84, v77
	v_mul_f32_e32 v78, v85, v78
	v_cvt_pk_bf16_f32 v77, v77, v78
	v_lshl_add_u64 v[78:79], s[74:75], 0, v[82:83]
	v_lshl_add_u64 v[78:79], v[78:79], 0, v[194:195]
	global_store_dwordx4 v[78:79], v[74:77], off
	s_nop 1
	v_pk_mul_f32 v[74:75], v[68:69], s[36:37] op_sel_hi:[1,0]
	v_pk_mul_f32 v[68:69], v[66:67], s[36:37] op_sel_hi:[1,0]
	v_lshlrev_b32_e32 v66, 16, v114
	v_and_b32_e32 v67, 0xffff0000, v114
	v_mul_f32_e32 v66, v70, v66
	v_mul_f32_e32 v67, v71, v67
	v_cvt_pk_bf16_f32 v66, v66, v67
	v_lshlrev_b32_e32 v67, 16, v115
	v_and_b32_e32 v70, 0xffff0000, v115
	v_mul_f32_e32 v67, v72, v67
	v_mul_f32_e32 v70, v73, v70
	v_cvt_pk_bf16_f32 v67, v67, v70
	v_lshlrev_b32_e32 v70, 16, v116
	v_mul_f32_e32 v68, v68, v70
	v_and_b32_e32 v70, 0xffff0000, v116
	v_mul_f32_e32 v69, v69, v70
	v_cvt_pk_bf16_f32 v68, v68, v69
	v_lshlrev_b32_e32 v69, 16, v117
	v_mul_f32_e32 v69, v74, v69
	v_and_b32_e32 v70, 0xffff0000, v117
	v_mul_f32_e32 v70, v75, v70
	v_cvt_pk_bf16_f32 v69, v69, v70
	global_store_dwordx4 v[78:79], v[66:69], off offset:256
	v_add_u32_e32 v78, 0x80, v144
	s_nop 0
	v_mad_i64_i32 v[66:67], s[6:7], v78, s37, v[142:143]
	v_lshl_add_u64 v[66:67], v[66:67], 0, v[194:195]
	v_add_co_u32_e32 v68, vcc, s16, v66
	v_add_u32_e32 v86, 0x90, v144
	s_nop 0
	v_addc_co_u32_e32 v69, vcc, 0, v67, vcc
	global_load_dwordx4 v[70:73], v[68:69], off offset:2048
	v_lshl_add_u64 v[66:67], v[66:67], 0, s[84:85]
	global_load_dwordx4 v[74:77], v[66:67], off offset:256
	v_pk_mul_f32 v[96:97], v[56:57], s[36:37] op_sel_hi:[1,0]
	v_mad_i64_i32 v[56:57], s[6:7], v86, s37, v[142:143]
	v_lshl_add_u64 v[56:57], v[56:57], 0, v[194:195]
	v_pk_mul_f32 v[94:95], v[58:59], s[36:37] op_sel_hi:[1,0]
	v_add_co_u32_e32 v58, vcc, s16, v56
	v_pk_mul_f32 v[92:93], v[60:61], s[36:37] op_sel_hi:[1,0]
	s_nop 0
	v_addc_co_u32_e32 v59, vcc, 0, v57, vcc
	global_load_dwordx4 v[58:61], v[58:59], off offset:2048
	v_add_u32_e32 v68, 0xa0, v144
	v_pk_mul_f32 v[102:103], v[50:51], s[36:37] op_sel_hi:[1,0]
	v_mad_i64_i32 v[50:51], s[6:7], v68, s37, v[142:143]
	v_add_u32_e32 v66, 0xb0, v144
	v_lshl_add_u64 v[50:51], v[50:51], 0, v[194:195]
	v_pk_mul_f32 v[100:101], v[52:53], s[36:37] op_sel_hi:[1,0]
	v_mad_i64_i32 v[52:53], s[6:7], v66, s37, v[142:143]
	v_lshl_add_u64 v[82:83], v[50:51], 0, s[84:85]
	v_add_co_u32_e32 v50, vcc, s16, v50
	v_lshl_add_u64 v[52:53], v[52:53], 0, v[194:195]
	s_nop 0
	v_addc_co_u32_e32 v51, vcc, 0, v51, vcc
	v_ashrrev_i32_e32 v79, 31, v78
	v_lshl_add_u64 v[104:105], v[52:53], 0, s[84:85]
	v_add_co_u32_e32 v52, vcc, s16, v52
	v_pk_mul_f32 v[98:99], v[54:55], s[36:37] op_sel_hi:[1,0]
	v_lshlrev_b64 v[54:55], 11, v[78:79]
	v_lshl_add_u64 v[56:57], v[56:57], 0, s[84:85]
	v_addc_co_u32_e32 v53, vcc, 0, v53, vcc
	v_pk_mul_f32 v[88:89], v[64:65], s[36:37] op_sel_hi:[1,0]
	v_pk_mul_f32 v[90:91], v[62:63], s[36:37] op_sel_hi:[1,0]
	v_lshl_add_u64 v[106:107], s[74:75], 0, v[54:55]
	global_load_dwordx4 v[62:65], v[56:57], off offset:256
	global_load_dwordx4 v[78:81], v[50:51], off offset:2048
	s_nop 0
	global_load_dwordx4 v[82:85], v[82:83], off offset:256
	s_nop 0
	global_load_dwordx4 v[54:57], v[52:53], off offset:2048
	s_nop 0
	global_load_dwordx4 v[50:53], v[104:105], off offset:256
	v_lshl_add_u64 v[104:105], v[106:107], 0, v[194:195]
	v_pk_mul_f32 v[46:47], v[46:47], s[36:37] op_sel_hi:[1,0]
	v_pk_mul_f32 v[48:49], v[48:49], s[36:37] op_sel_hi:[1,0]
	v_ashrrev_i32_e32 v87, 31, v86
	v_pk_mul_f32 v[38:39], v[38:39], s[36:37] op_sel_hi:[1,0]
	v_pk_mul_f32 v[40:41], v[40:41], s[36:37] op_sel_hi:[1,0]
	v_pk_mul_f32 v[30:31], v[30:31], s[36:37] op_sel_hi:[1,0]
	v_pk_mul_f32 v[32:33], v[32:33], s[36:37] op_sel_hi:[1,0]
	v_ashrrev_i32_e32 v69, 31, v68
	v_pk_mul_f32 v[22:23], v[22:23], s[36:37] op_sel_hi:[1,0]
	v_pk_mul_f32 v[24:25], v[24:25], s[36:37] op_sel_hi:[1,0]
	v_pk_mul_f32 v[14:15], v[14:15], s[36:37] op_sel_hi:[1,0]
	v_pk_mul_f32 v[16:17], v[16:17], s[36:37] op_sel_hi:[1,0]
	v_ashrrev_i32_e32 v67, 31, v66
	v_pk_mul_f32 v[6:7], v[6:7], s[36:37] op_sel_hi:[1,0]
	v_pk_mul_f32 v[8:9], v[8:9], s[36:37] op_sel_hi:[1,0]
	s_waitcnt vmcnt(0)
	v_lshlrev_b32_e32 v106, 16, v70
	v_and_b32_e32 v70, 0xffff0000, v70
	v_lshlrev_b32_e32 v107, 16, v71
	v_and_b32_e32 v71, 0xffff0000, v71
	v_lshlrev_b32_e32 v108, 16, v72
	v_and_b32_e32 v72, 0xffff0000, v72
	v_lshlrev_b32_e32 v109, 16, v73
	v_and_b32_e32 v73, 0xffff0000, v73
	v_mul_f32_e32 v70, v91, v70
	v_mul_f32_e32 v71, v89, v71
	v_mul_f32_e32 v72, v95, v72
	v_mul_f32_e32 v73, v93, v73
	v_mul_f32_e32 v90, v90, v106
	v_mul_f32_e32 v88, v88, v107
	v_mul_f32_e32 v89, v94, v108
	v_mul_f32_e32 v91, v92, v109
	v_cvt_pk_bf16_f32 v70, v90, v70
	v_cvt_pk_bf16_f32 v71, v88, v71
	v_cvt_pk_bf16_f32 v72, v89, v72
	v_cvt_pk_bf16_f32 v73, v91, v73
	v_lshlrev_b32_e32 v111, 16, v75
	v_and_b32_e32 v75, 0xffff0000, v75
	global_store_dwordx4 v[104:105], v[70:73], off
	v_lshlrev_b32_e32 v110, 16, v74
	v_and_b32_e32 v74, 0xffff0000, v74
	v_lshlrev_b32_e32 v72, 16, v76
	v_and_b32_e32 v73, 0xffff0000, v76
	v_mul_f32_e32 v71, v97, v75
	v_mul_f32_e32 v72, v102, v72
	v_mul_f32_e32 v73, v103, v73
	v_mul_f32_e32 v92, v98, v110
	v_mul_f32_e32 v74, v99, v74
	v_mul_f32_e32 v93, v96, v111
	v_cvt_pk_bf16_f32 v70, v92, v74
	v_cvt_pk_bf16_f32 v71, v93, v71
	v_cvt_pk_bf16_f32 v72, v72, v73
	v_lshlrev_b32_e32 v73, 16, v77
	v_mul_f32_e32 v73, v100, v73
	v_and_b32_e32 v74, 0xffff0000, v77
	v_mul_f32_e32 v74, v101, v74
	v_cvt_pk_bf16_f32 v73, v73, v74
	global_store_dwordx4 v[104:105], v[70:73], off offset:256
	s_nop 1
	v_pk_mul_f32 v[72:73], v[44:45], s[36:37] op_sel_hi:[1,0]
	v_pk_mul_f32 v[44:45], v[42:43], s[36:37] op_sel_hi:[1,0]
	v_lshlrev_b32_e32 v42, 16, v58
	v_and_b32_e32 v43, 0xffff0000, v58
	v_mul_f32_e32 v42, v46, v42
	v_mul_f32_e32 v43, v47, v43
	v_cvt_pk_bf16_f32 v42, v42, v43
	v_lshlrev_b32_e32 v43, 16, v59
	v_and_b32_e32 v46, 0xffff0000, v59
	v_mul_f32_e32 v43, v48, v43
	v_mul_f32_e32 v46, v49, v46
	v_cvt_pk_bf16_f32 v43, v43, v46
	v_lshlrev_b32_e32 v46, 16, v60
	v_mul_f32_e32 v44, v44, v46
	v_and_b32_e32 v46, 0xffff0000, v60
	v_mul_f32_e32 v45, v45, v46
	v_cvt_pk_bf16_f32 v44, v44, v45
	v_lshlrev_b32_e32 v45, 16, v61
	v_and_b32_e32 v46, 0xffff0000, v61
	v_lshlrev_b64 v[70:71], 11, v[86:87]
	v_mul_f32_e32 v45, v72, v45
	v_mul_f32_e32 v46, v73, v46
	v_cvt_pk_bf16_f32 v45, v45, v46
	v_lshl_add_u64 v[46:47], s[74:75], 0, v[70:71]
	v_lshl_add_u64 v[46:47], v[46:47], 0, v[194:195]
	global_store_dwordx4 v[46:47], v[42:45], off
	s_nop 1
	v_pk_mul_f32 v[42:43], v[36:37], s[36:37] op_sel_hi:[1,0]
	v_pk_mul_f32 v[36:37], v[34:35], s[36:37] op_sel_hi:[1,0]
	v_lshlrev_b32_e32 v34, 16, v62
	v_and_b32_e32 v35, 0xffff0000, v62
	v_mul_f32_e32 v34, v38, v34
	v_mul_f32_e32 v35, v39, v35
	v_cvt_pk_bf16_f32 v34, v34, v35
	v_lshlrev_b32_e32 v35, 16, v63
	v_and_b32_e32 v38, 0xffff0000, v63
	v_mul_f32_e32 v35, v40, v35
	v_mul_f32_e32 v38, v41, v38
	v_cvt_pk_bf16_f32 v35, v35, v38
	v_lshlrev_b32_e32 v38, 16, v64
	v_mul_f32_e32 v36, v36, v38
	v_and_b32_e32 v38, 0xffff0000, v64
	v_mul_f32_e32 v37, v37, v38
	v_cvt_pk_bf16_f32 v36, v36, v37
	v_lshlrev_b32_e32 v37, 16, v65
	v_mul_f32_e32 v37, v42, v37
	v_and_b32_e32 v38, 0xffff0000, v65
	v_mul_f32_e32 v38, v43, v38
	v_cvt_pk_bf16_f32 v37, v37, v38
	global_store_dwordx4 v[46:47], v[34:37], off offset:256
	s_nop 1
	v_pk_mul_f32 v[36:37], v[28:29], s[36:37] op_sel_hi:[1,0]
	v_pk_mul_f32 v[28:29], v[26:27], s[36:37] op_sel_hi:[1,0]
	v_lshlrev_b32_e32 v26, 16, v78
	v_and_b32_e32 v27, 0xffff0000, v78
	v_mul_f32_e32 v26, v30, v26
	v_mul_f32_e32 v27, v31, v27
	v_cvt_pk_bf16_f32 v26, v26, v27
	v_lshlrev_b32_e32 v27, 16, v79
	v_and_b32_e32 v30, 0xffff0000, v79
	v_mul_f32_e32 v27, v32, v27
	v_mul_f32_e32 v30, v33, v30
	v_cvt_pk_bf16_f32 v27, v27, v30
	v_lshlrev_b32_e32 v30, 16, v80
	v_mul_f32_e32 v28, v28, v30
	v_and_b32_e32 v30, 0xffff0000, v80
	v_mul_f32_e32 v29, v29, v30
	v_cvt_pk_bf16_f32 v28, v28, v29
	v_lshlrev_b32_e32 v29, 16, v81
	v_and_b32_e32 v30, 0xffff0000, v81
	v_lshlrev_b64 v[34:35], 11, v[68:69]
	v_mul_f32_e32 v29, v36, v29
	v_mul_f32_e32 v30, v37, v30
	v_cvt_pk_bf16_f32 v29, v29, v30
	v_lshl_add_u64 v[30:31], s[74:75], 0, v[34:35]
	v_lshl_add_u64 v[30:31], v[30:31], 0, v[194:195]
	global_store_dwordx4 v[30:31], v[26:29], off
	s_nop 1
	v_pk_mul_f32 v[26:27], v[20:21], s[36:37] op_sel_hi:[1,0]
	v_pk_mul_f32 v[20:21], v[18:19], s[36:37] op_sel_hi:[1,0]
	v_lshlrev_b32_e32 v18, 16, v82
	v_and_b32_e32 v19, 0xffff0000, v82
	v_mul_f32_e32 v18, v22, v18
	v_mul_f32_e32 v19, v23, v19
	v_cvt_pk_bf16_f32 v18, v18, v19
	v_lshlrev_b32_e32 v19, 16, v83
	v_and_b32_e32 v22, 0xffff0000, v83
	v_mul_f32_e32 v19, v24, v19
	v_mul_f32_e32 v22, v25, v22
	v_cvt_pk_bf16_f32 v19, v19, v22
	v_lshlrev_b32_e32 v22, 16, v84
	v_mul_f32_e32 v20, v20, v22
	v_and_b32_e32 v22, 0xffff0000, v84
	v_mul_f32_e32 v21, v21, v22
	v_cvt_pk_bf16_f32 v20, v20, v21
	v_lshlrev_b32_e32 v21, 16, v85
	v_mul_f32_e32 v21, v26, v21
	v_and_b32_e32 v22, 0xffff0000, v85
	v_mul_f32_e32 v22, v27, v22
	v_cvt_pk_bf16_f32 v21, v21, v22
	global_store_dwordx4 v[30:31], v[18:21], off offset:256
	s_nop 1
	v_pk_mul_f32 v[20:21], v[12:13], s[36:37] op_sel_hi:[1,0]
	v_pk_mul_f32 v[12:13], v[10:11], s[36:37] op_sel_hi:[1,0]
	v_lshlrev_b32_e32 v10, 16, v54
	v_and_b32_e32 v11, 0xffff0000, v54
	v_mul_f32_e32 v10, v14, v10
	v_mul_f32_e32 v11, v15, v11
	v_cvt_pk_bf16_f32 v10, v10, v11
	v_lshlrev_b32_e32 v11, 16, v55
	v_and_b32_e32 v14, 0xffff0000, v55
	v_mul_f32_e32 v11, v16, v11
	v_mul_f32_e32 v14, v17, v14
	v_cvt_pk_bf16_f32 v11, v11, v14
	v_lshlrev_b32_e32 v14, 16, v56
	v_mul_f32_e32 v12, v12, v14
	v_and_b32_e32 v14, 0xffff0000, v56
	v_mul_f32_e32 v13, v13, v14
	v_cvt_pk_bf16_f32 v12, v12, v13
	v_lshlrev_b32_e32 v13, 16, v57
	v_and_b32_e32 v14, 0xffff0000, v57
	v_lshlrev_b64 v[18:19], 11, v[66:67]
	v_mul_f32_e32 v13, v20, v13
	v_mul_f32_e32 v14, v21, v14
	v_cvt_pk_bf16_f32 v13, v13, v14
	v_lshl_add_u64 v[14:15], s[74:75], 0, v[18:19]
	v_lshl_add_u64 v[14:15], v[14:15], 0, v[194:195]
	global_store_dwordx4 v[14:15], v[10:13], off
	s_nop 1
	v_pk_mul_f32 v[10:11], v[4:5], s[36:37] op_sel_hi:[1,0]
	v_pk_mul_f32 v[4:5], v[2:3], s[36:37] op_sel_hi:[1,0]
	v_lshlrev_b32_e32 v2, 16, v50
	v_and_b32_e32 v3, 0xffff0000, v50
	v_mul_f32_e32 v2, v6, v2
	v_mul_f32_e32 v3, v7, v3
	v_cvt_pk_bf16_f32 v2, v2, v3
	v_lshlrev_b32_e32 v3, 16, v51
	v_and_b32_e32 v6, 0xffff0000, v51
	v_mul_f32_e32 v3, v8, v3
	v_mul_f32_e32 v6, v9, v6
	v_cvt_pk_bf16_f32 v3, v3, v6
	v_lshlrev_b32_e32 v6, 16, v52
	v_mul_f32_e32 v4, v4, v6
	v_and_b32_e32 v6, 0xffff0000, v52
	v_mul_f32_e32 v5, v5, v6
	v_cvt_pk_bf16_f32 v4, v4, v5
	v_lshlrev_b32_e32 v5, 16, v53
	v_mul_f32_e32 v5, v10, v5
	v_and_b32_e32 v6, 0xffff0000, v53
	v_mul_f32_e32 v6, v11, v6
	v_cvt_pk_bf16_f32 v5, v5, v6
	global_store_dwordx4 v[14:15], v[2:5], off offset:256
	s_and_b64 vcc, exec, s[52:53]
	s_mov_b32 s28, s4
	s_cbranch_vccz .LBB0_265
	s_waitcnt vmcnt(0)
	v_readlane_b32 s28, v250, 12
	s_cmpk_gt_u32 s12, 0xff
	v_readlane_b32 s29, v250, 13
	s_mov_b32 s70, 0x800000
	s_cbranch_scc1 .LBB0_270
	s_barrier

.LBB0_368:
	v_or_b32_e32 v130, 0x10000, v201
	v_add_u32_e32 v134, 0x10400, v201
	v_add_u32_e32 v138, 0x10800, v201
	v_add_u32_e32 v142, 0x10c00, v201
	ds_read_b128 v[130:133], v130
	ds_read_b128 v[134:137], v134
	ds_read_b128 v[138:141], v138
	ds_read_b128 v[142:145], v142
	s_add_u32 s10, s8, 0xfffc0080
	s_addc_u32 s11, s9, -1
	s_cmp_eq_u32 s29, 12
	s_cselect_b32 s11, s81, s11
	s_cselect_b32 s10, s80, s10
	s_cselect_b32 s53, s83, s28
	s_cselect_b32 s52, s82, s7
	v_lshl_add_u64 v[178:179], s[8:9], 0, v[212:213]
	s_add_i32 m0, s34, 0xc000
	ds_read_b128 v[146:149], v199
	ds_read_b128 v[150:153], v199 offset:1024
	ds_read_b128 v[154:157], v199 offset:2048
	ds_read_b128 v[158:161], v199 offset:3072
	ds_read_b128 v[162:165], v199 offset:4096
	ds_read_b128 v[166:169], v199 offset:5120
	ds_read_b128 v[170:173], v199 offset:6144
	ds_read_b128 v[174:177], v199 offset:7168
	global_load_lds_dwordx4 v[178:179], off
	v_lshl_add_u64 v[178:179], s[8:9], 0, v[214:215]
	s_add_i32 m0, s34, 0xe000
	s_nop 0
	global_load_lds_dwordx4 v[178:179], off
	s_waitcnt lgkmcnt(8)
	s_setprio 1
	s_barrier
	s_waitcnt lgkmcnt(0)
	v_mfma_f32_16x16x32_bf16 v[126:129], v[130:133], v[146:149], v[126:129]
	v_mfma_f32_16x16x32_bf16 v[122:125], v[138:141], v[146:149], v[122:125]
	v_mfma_f32_16x16x32_bf16 v[118:121], v[130:133], v[154:157], v[118:121]
	v_mfma_f32_16x16x32_bf16 v[114:117], v[138:141], v[154:157], v[114:117]
	v_mfma_f32_16x16x32_bf16 v[110:113], v[130:133], v[162:165], v[110:113]
	v_mfma_f32_16x16x32_bf16 v[106:109], v[138:141], v[162:165], v[106:109]
	v_mfma_f32_16x16x32_bf16 v[102:105], v[130:133], v[170:173], v[102:105]
	v_mfma_f32_16x16x32_bf16 v[98:101], v[138:141], v[170:173], v[98:101]
	v_mfma_f32_16x16x32_bf16 v[126:129], v[134:137], v[150:153], v[126:129]
	v_mfma_f32_16x16x32_bf16 v[122:125], v[142:145], v[150:153], v[122:125]
	v_mfma_f32_16x16x32_bf16 v[118:121], v[134:137], v[158:161], v[118:121]
	v_mfma_f32_16x16x32_bf16 v[114:117], v[142:145], v[158:161], v[114:117]
	v_mfma_f32_16x16x32_bf16 v[110:113], v[134:137], v[166:169], v[110:113]
	v_mfma_f32_16x16x32_bf16 v[106:109], v[142:145], v[166:169], v[106:109]
	v_mfma_f32_16x16x32_bf16 v[102:105], v[134:137], v[174:177], v[102:105]
	v_mfma_f32_16x16x32_bf16 v[98:101], v[142:145], v[174:177], v[98:101]
	s_barrier
	s_setprio 0
	s_mov_b32 m0, s35
	v_or_b32_e32 v178, 0x14000, v201
	v_add_u32_e32 v182, 0x14400, v201
	v_add_u32_e32 v186, 0x14800, v201
	v_add_u32_e32 v190, 0x14c00, v201
	v_lshl_add_u64 v[216:217], s[52:53], 0, v[194:195]
	ds_read_b128 v[178:181], v178
	ds_read_b128 v[182:185], v182
	ds_read_b128 v[186:189], v186
	ds_read_b128 v[190:193], v190
	global_load_lds_dwordx4 v[216:217], off
	v_lshl_add_u64 v[218:219], s[52:53], 0, v[210:211]
	s_mov_b32 m0, s42
	s_nop 0
	global_load_lds_dwordx4 v[218:219], off
	s_setprio 1
	s_barrier
	s_waitcnt lgkmcnt(0)
	v_mfma_f32_16x16x32_bf16 v[94:97], v[178:181], v[146:149], v[94:97]
	v_mfma_f32_16x16x32_bf16 v[90:93], v[186:189], v[146:149], v[90:93]
	v_mfma_f32_16x16x32_bf16 v[86:89], v[178:181], v[154:157], v[86:89]
	v_mfma_f32_16x16x32_bf16 v[82:85], v[186:189], v[154:157], v[82:85]
	v_mfma_f32_16x16x32_bf16 v[78:81], v[178:181], v[162:165], v[78:81]
	v_mfma_f32_16x16x32_bf16 v[74:77], v[186:189], v[162:165], v[74:77]
	v_mfma_f32_16x16x32_bf16 v[70:73], v[178:181], v[170:173], v[70:73]
	v_mfma_f32_16x16x32_bf16 v[66:69], v[186:189], v[170:173], v[66:69]
	v_mfma_f32_16x16x32_bf16 v[94:97], v[182:185], v[150:153], v[94:97]
	v_mfma_f32_16x16x32_bf16 v[90:93], v[190:193], v[150:153], v[90:93]
	v_mfma_f32_16x16x32_bf16 v[86:89], v[182:185], v[158:161], v[86:89]
	v_mfma_f32_16x16x32_bf16 v[82:85], v[190:193], v[158:161], v[82:85]
	v_mfma_f32_16x16x32_bf16 v[78:81], v[182:185], v[166:169], v[78:81]
	v_mfma_f32_16x16x32_bf16 v[74:77], v[190:193], v[166:169], v[74:77]
	s_mov_b32 m0, s34
	v_mfma_f32_16x16x32_bf16 v[70:73], v[182:185], v[174:177], v[70:73]
	v_lshl_add_u64 v[220:221], s[10:11], 0, v[206:207]
	v_mfma_f32_16x16x32_bf16 v[66:69], v[190:193], v[174:177], v[66:69]
	s_barrier
	s_setprio 0
	ds_read_b128 v[146:149], v199 offset:16384
	ds_read_b128 v[150:153], v199 offset:17408
	ds_read_b128 v[154:157], v199 offset:18432
	ds_read_b128 v[158:161], v199 offset:19456
	ds_read_b128 v[162:165], v199 offset:20480
	ds_read_b128 v[166:169], v199 offset:21504
	ds_read_b128 v[170:173], v199 offset:22528
	ds_read_b128 v[174:177], v199 offset:23552
	global_load_lds_dwordx4 v[220:221], off
	v_lshl_add_u64 v[222:223], s[10:11], 0, v[208:209]
	s_mov_b32 m0, s56
	s_nop 0
	global_load_lds_dwordx4 v[222:223], off
	s_setprio 1
	s_barrier
	s_waitcnt lgkmcnt(0)
	v_mfma_f32_16x16x32_bf16 v[62:65], v[130:133], v[146:149], v[62:65]
	v_mfma_f32_16x16x32_bf16 v[58:61], v[138:141], v[146:149], v[58:61]
	v_mfma_f32_16x16x32_bf16 v[54:57], v[130:133], v[154:157], v[54:57]
	v_mfma_f32_16x16x32_bf16 v[50:53], v[138:141], v[154:157], v[50:53]
	v_mfma_f32_16x16x32_bf16 v[46:49], v[130:133], v[162:165], v[46:49]
	v_mfma_f32_16x16x32_bf16 v[42:45], v[138:141], v[162:165], v[42:45]
	v_mfma_f32_16x16x32_bf16 v[38:41], v[130:133], v[170:173], v[38:41]
	v_mfma_f32_16x16x32_bf16 v[34:37], v[138:141], v[170:173], v[34:37]
	v_mfma_f32_16x16x32_bf16 v[62:65], v[134:137], v[150:153], v[62:65]
	v_mfma_f32_16x16x32_bf16 v[58:61], v[142:145], v[150:153], v[58:61]
	v_mfma_f32_16x16x32_bf16 v[54:57], v[134:137], v[158:161], v[54:57]
	v_mfma_f32_16x16x32_bf16 v[50:53], v[142:145], v[158:161], v[50:53]
	v_mfma_f32_16x16x32_bf16 v[46:49], v[134:137], v[166:169], v[46:49]
	v_mfma_f32_16x16x32_bf16 v[42:45], v[142:145], v[166:169], v[42:45]
	v_mfma_f32_16x16x32_bf16 v[38:41], v[134:137], v[174:177], v[38:41]
	v_mfma_f32_16x16x32_bf16 v[34:37], v[142:145], v[174:177], v[34:37]
	s_barrier
	s_setprio 0
	s_add_u32 s86, s52, 0x40000
	s_addc_u32 s87, s53, 0
	s_mov_b32 m0, s57
	v_lshl_add_u64 v[130:131], s[86:87], 0, v[194:195]
	global_load_lds_dwordx4 v[130:131], off
	v_lshl_add_u64 v[130:131], s[86:87], 0, v[210:211]
	s_mov_b32 m0, s67
	s_nop 0
	global_load_lds_dwordx4 v[130:131], off
	s_waitcnt vmcnt(6)
	s_setprio 1
	s_barrier
	v_mfma_f32_16x16x32_bf16 v[30:33], v[178:181], v[146:149], v[30:33]
	v_mfma_f32_16x16x32_bf16 v[26:29], v[186:189], v[146:149], v[26:29]
	v_mfma_f32_16x16x32_bf16 v[22:25], v[178:181], v[154:157], v[22:25]
	v_mfma_f32_16x16x32_bf16 v[18:21], v[186:189], v[154:157], v[18:21]
	v_mfma_f32_16x16x32_bf16 v[14:17], v[178:181], v[162:165], v[14:17]
	v_mfma_f32_16x16x32_bf16 v[10:13], v[186:189], v[162:165], v[10:13]
	v_mfma_f32_16x16x32_bf16 v[6:9], v[178:181], v[170:173], v[6:9]
	v_mfma_f32_16x16x32_bf16 v[2:5], v[186:189], v[170:173], v[2:5]
	v_mfma_f32_16x16x32_bf16 v[30:33], v[182:185], v[150:153], v[30:33]
	v_mfma_f32_16x16x32_bf16 v[26:29], v[190:193], v[150:153], v[26:29]
	v_mfma_f32_16x16x32_bf16 v[22:25], v[182:185], v[158:161], v[22:25]
	v_mfma_f32_16x16x32_bf16 v[18:21], v[190:193], v[158:161], v[18:21]
	v_or_b32_e32 v130, 0x18000, v201
	v_mfma_f32_16x16x32_bf16 v[14:17], v[182:185], v[166:169], v[14:17]
	v_add_u32_e32 v134, 0x18400, v201
	v_mfma_f32_16x16x32_bf16 v[10:13], v[190:193], v[166:169], v[10:13]
	v_add_u32_e32 v138, 0x18800, v201
	v_mfma_f32_16x16x32_bf16 v[6:9], v[182:185], v[174:177], v[6:9]
	v_add_u32_e32 v142, 0x18c00, v201
	v_mfma_f32_16x16x32_bf16 v[2:5], v[190:193], v[174:177], v[2:5]
	s_barrier
	s_setprio 0
	ds_read_b128 v[130:133], v130
	ds_read_b128 v[134:137], v134
	ds_read_b128 v[138:141], v138
	ds_read_b128 v[142:145], v142
	s_add_u32 s10, s10, 0x40000
	s_addc_u32 s11, s11, 0
	s_mov_b32 m0, s70
	v_lshl_add_u64 v[178:179], s[10:11], 0, v[206:207]
	ds_read_b128 v[146:149], v199 offset:32768
	ds_read_b128 v[150:153], v199 offset:33792
	ds_read_b128 v[154:157], v199 offset:34816
	ds_read_b128 v[158:161], v199 offset:35840
	ds_read_b128 v[162:165], v199 offset:36864
	ds_read_b128 v[166:169], v199 offset:37888
	ds_read_b128 v[170:173], v199 offset:38912
	ds_read_b128 v[174:177], v199 offset:39936
	global_load_lds_dwordx4 v[178:179], off
	v_lshl_add_u64 v[178:179], s[10:11], 0, v[208:209]
	s_mov_b32 m0, s71
	s_nop 0
	global_load_lds_dwordx4 v[178:179], off
	s_waitcnt lgkmcnt(8)
	s_setprio 1
	s_barrier
	s_waitcnt lgkmcnt(0)
	v_mfma_f32_16x16x32_bf16 v[126:129], v[130:133], v[146:149], v[126:129]
	v_mfma_f32_16x16x32_bf16 v[122:125], v[138:141], v[146:149], v[122:125]
	v_mfma_f32_16x16x32_bf16 v[118:121], v[130:133], v[154:157], v[118:121]
	v_mfma_f32_16x16x32_bf16 v[114:117], v[138:141], v[154:157], v[114:117]
	v_mfma_f32_16x16x32_bf16 v[110:113], v[130:133], v[162:165], v[110:113]
	v_mfma_f32_16x16x32_bf16 v[106:109], v[138:141], v[162:165], v[106:109]
	v_mfma_f32_16x16x32_bf16 v[102:105], v[130:133], v[170:173], v[102:105]
	v_mfma_f32_16x16x32_bf16 v[98:101], v[138:141], v[170:173], v[98:101]
	v_mfma_f32_16x16x32_bf16 v[126:129], v[134:137], v[150:153], v[126:129]
	v_mfma_f32_16x16x32_bf16 v[122:125], v[142:145], v[150:153], v[122:125]
	v_mfma_f32_16x16x32_bf16 v[118:121], v[134:137], v[158:161], v[118:121]
	v_mfma_f32_16x16x32_bf16 v[114:117], v[142:145], v[158:161], v[114:117]
	v_mfma_f32_16x16x32_bf16 v[110:113], v[134:137], v[166:169], v[110:113]
	v_mfma_f32_16x16x32_bf16 v[106:109], v[142:145], v[166:169], v[106:109]
	v_mfma_f32_16x16x32_bf16 v[102:105], v[134:137], v[174:177], v[102:105]
	v_mfma_f32_16x16x32_bf16 v[98:101], v[142:145], v[174:177], v[98:101]
	s_barrier
	s_setprio 0
	s_mov_b32 m0, s78
	v_or_b32_e32 v178, 0x1c000, v201
	v_add_u32_e32 v182, 0x1c400, v201
	v_add_u32_e32 v186, 0x1c800, v201
	v_add_u32_e32 v190, 0x1cc00, v201
	v_lshl_add_u64 v[216:217], v[216:217], 0, s[76:77]
	ds_read_b128 v[178:181], v178
	ds_read_b128 v[182:185], v182
	ds_read_b128 v[186:189], v186
	ds_read_b128 v[190:193], v190
	global_load_lds_dwordx4 v[216:217], off
	v_lshl_add_u64 v[216:217], v[218:219], 0, s[76:77]
	s_mov_b32 m0, s79
	s_nop 0
	global_load_lds_dwordx4 v[216:217], off
	s_setprio 1
	s_barrier
	s_waitcnt lgkmcnt(0)
	v_mfma_f32_16x16x32_bf16 v[94:97], v[178:181], v[146:149], v[94:97]
	v_mfma_f32_16x16x32_bf16 v[90:93], v[186:189], v[146:149], v[90:93]
	v_mfma_f32_16x16x32_bf16 v[86:89], v[178:181], v[154:157], v[86:89]
	v_mfma_f32_16x16x32_bf16 v[82:85], v[186:189], v[154:157], v[82:85]
	v_mfma_f32_16x16x32_bf16 v[78:81], v[178:181], v[162:165], v[78:81]
	v_mfma_f32_16x16x32_bf16 v[74:77], v[186:189], v[162:165], v[74:77]
	v_mfma_f32_16x16x32_bf16 v[70:73], v[178:181], v[170:173], v[70:73]
	v_mfma_f32_16x16x32_bf16 v[66:69], v[186:189], v[170:173], v[66:69]
	v_mfma_f32_16x16x32_bf16 v[94:97], v[182:185], v[150:153], v[94:97]
	v_mfma_f32_16x16x32_bf16 v[90:93], v[190:193], v[150:153], v[90:93]
	v_mfma_f32_16x16x32_bf16 v[86:89], v[182:185], v[158:161], v[86:89]
	v_mfma_f32_16x16x32_bf16 v[82:85], v[190:193], v[158:161], v[82:85]
	v_mfma_f32_16x16x32_bf16 v[78:81], v[182:185], v[166:169], v[78:81]
	v_mfma_f32_16x16x32_bf16 v[74:77], v[190:193], v[166:169], v[74:77]
	s_mov_b32 m0, s26
	v_mfma_f32_16x16x32_bf16 v[70:73], v[182:185], v[174:177], v[70:73]
	v_lshl_add_u64 v[216:217], v[220:221], 0, s[76:77]
	v_mfma_f32_16x16x32_bf16 v[66:69], v[190:193], v[174:177], v[66:69]
	s_barrier
	s_setprio 0
	ds_read_b128 v[146:149], v199 offset:49152
	ds_read_b128 v[150:153], v199 offset:50176
	ds_read_b128 v[154:157], v199 offset:51200
	ds_read_b128 v[158:161], v199 offset:52224
	ds_read_b128 v[162:165], v199 offset:53248
	ds_read_b128 v[166:169], v199 offset:54272
	ds_read_b128 v[170:173], v199 offset:55296
	ds_read_b128 v[174:177], v199 offset:56320
	global_load_lds_dwordx4 v[216:217], off
	v_lshl_add_u64 v[216:217], v[222:223], 0, s[76:77]
	s_mov_b32 m0, s4
	s_nop 0
	global_load_lds_dwordx4 v[216:217], off
	s_setprio 1
	s_barrier
	s_waitcnt lgkmcnt(0)
	v_mfma_f32_16x16x32_bf16 v[62:65], v[130:133], v[146:149], v[62:65]
	v_mfma_f32_16x16x32_bf16 v[58:61], v[138:141], v[146:149], v[58:61]
	v_mfma_f32_16x16x32_bf16 v[54:57], v[130:133], v[154:157], v[54:57]
	v_mfma_f32_16x16x32_bf16 v[50:53], v[138:141], v[154:157], v[50:53]
	v_mfma_f32_16x16x32_bf16 v[46:49], v[130:133], v[162:165], v[46:49]
	v_mfma_f32_16x16x32_bf16 v[42:45], v[138:141], v[162:165], v[42:45]
	v_mfma_f32_16x16x32_bf16 v[38:41], v[130:133], v[170:173], v[38:41]
	v_mfma_f32_16x16x32_bf16 v[34:37], v[138:141], v[170:173], v[34:37]
	v_mfma_f32_16x16x32_bf16 v[62:65], v[134:137], v[150:153], v[62:65]
	v_mfma_f32_16x16x32_bf16 v[58:61], v[142:145], v[150:153], v[58:61]
	v_mfma_f32_16x16x32_bf16 v[54:57], v[134:137], v[158:161], v[54:57]
	v_mfma_f32_16x16x32_bf16 v[50:53], v[142:145], v[158:161], v[50:53]
	v_mfma_f32_16x16x32_bf16 v[46:49], v[134:137], v[166:169], v[46:49]
	v_mfma_f32_16x16x32_bf16 v[42:45], v[142:145], v[166:169], v[42:45]
	v_mfma_f32_16x16x32_bf16 v[38:41], v[134:137], v[174:177], v[38:41]
	v_mfma_f32_16x16x32_bf16 v[34:37], v[142:145], v[174:177], v[34:37]
	s_barrier
	s_setprio 0
	s_add_u32 s10, s52, 0x40080
	s_addc_u32 s11, s53, 0
	s_mov_b32 m0, s5
	v_lshl_add_u64 v[130:131], s[10:11], 0, v[194:195]
	global_load_lds_dwordx4 v[130:131], off
	v_lshl_add_u64 v[130:131], s[10:11], 0, v[210:211]
	s_mov_b32 m0, s58
	s_nop 0
	global_load_lds_dwordx4 v[130:131], off
	s_waitcnt vmcnt(6)
	s_setprio 1
	s_barrier
	v_mfma_f32_16x16x32_bf16 v[30:33], v[178:181], v[146:149], v[30:33]
	v_mfma_f32_16x16x32_bf16 v[26:29], v[186:189], v[146:149], v[26:29]
	v_mfma_f32_16x16x32_bf16 v[22:25], v[178:181], v[154:157], v[22:25]
	v_mfma_f32_16x16x32_bf16 v[18:21], v[186:189], v[154:157], v[18:21]
	v_mfma_f32_16x16x32_bf16 v[14:17], v[178:181], v[162:165], v[14:17]
	v_mfma_f32_16x16x32_bf16 v[10:13], v[186:189], v[162:165], v[10:13]
	v_mfma_f32_16x16x32_bf16 v[6:9], v[178:181], v[170:173], v[6:9]
	v_mfma_f32_16x16x32_bf16 v[2:5], v[186:189], v[170:173], v[2:5]
	v_mfma_f32_16x16x32_bf16 v[30:33], v[182:185], v[150:153], v[30:33]
	v_mfma_f32_16x16x32_bf16 v[26:29], v[190:193], v[150:153], v[26:29]
	v_mfma_f32_16x16x32_bf16 v[22:25], v[182:185], v[158:161], v[22:25]
	v_mfma_f32_16x16x32_bf16 v[18:21], v[190:193], v[158:161], v[18:21]
	v_mfma_f32_16x16x32_bf16 v[14:17], v[182:185], v[166:169], v[14:17]
	v_mfma_f32_16x16x32_bf16 v[10:13], v[190:193], v[166:169], v[10:13]
	v_mfma_f32_16x16x32_bf16 v[6:9], v[182:185], v[174:177], v[6:9]
	v_mfma_f32_16x16x32_bf16 v[2:5], v[190:193], v[174:177], v[2:5]
	s_setprio 0
	s_add_i32 s29, s29, 2
	s_add_u32 s8, s8, 0x100
	s_addc_u32 s9, s9, 0
	s_add_u32 s7, s7, 0x100
	s_addc_u32 s28, s28, 0
	s_cmp_gt_u32 s29, 13
	s_barrier
	s_cbranch_scc0 .LBB0_368
	s_cmp_gt_i32 s95, 1
	s_cselect_b64 s[52:53], -1, 0
	s_mul_i32 s7, s6, 0x680000
	s_lshl_b32 s8, s95, 12
	s_lshl_b32 s9, s54, 9
	s_add_i32 s7, s7, s8
	s_add_i32 s7, s7, s9
	s_add_i32 s7, s7, 0x3800
	s_add_u32 s20, s50, s7
	s_addc_u32 s21, s51, 0
	s_lshl_b32 s7, s6, 20
	s_add_i32 s7, s7, s9
	s_add_u32 s10, s96, s7
	s_addc_u32 s11, s97, 0
	s_mov_b32 s86, 0xbfb8aa3b
	s_mov_b32 s87, 0xbfb8aa3b
	v_mul_u32_u24_e32 v253, 0x6800, v197
	v_lshlrev_b32_e32 v255, 12, v197
	v_lshl_add_u32 v253, v203, 1, v253
	v_lshl_add_u32 v255, v203, 1, v255
	v_add_u32_e32 v254, 0x1000, v253
	s_cmp_eq_u32 s95, 2
	s_cbranch_scc1 .Lem_br2
	global_load_dwordx4 v[130:133], v253, s[20:21]
	global_load_dwordx4 v[134:137], v254, s[20:21]
	global_load_dwordx4 v[138:141], v253, s[20:21] offset:256
	global_load_dwordx4 v[142:145], v254, s[20:21] offset:256
	s_add_u32 s28, s20, 0x68000
	s_addc_u32 s29, s21, 0
	global_load_dwordx4 v[146:149], v253, s[28:29]
	global_load_dwordx4 v[150:153], v254, s[28:29]
	global_load_dwordx4 v[154:157], v253, s[28:29] offset:256
	global_load_dwordx4 v[158:161], v254, s[28:29] offset:256
	s_add_u32 s28, s20, 0xd0000
	s_addc_u32 s29, s21, 0
	global_load_dwordx4 v[162:165], v253, s[28:29]
	global_load_dwordx4 v[166:169], v254, s[28:29]
	global_load_dwordx4 v[170:173], v253, s[28:29] offset:256
	global_load_dwordx4 v[174:177], v254, s[28:29] offset:256
	s_add_u32 s28, s20, 0x138000
	s_addc_u32 s29, s21, 0
	global_load_dwordx4 v[178:181], v253, s[28:29]
	global_load_dwordx4 v[182:185], v254, s[28:29]
	global_load_dwordx4 v[186:189], v253, s[28:29] offset:256
	global_load_dwordx4 v[190:193], v254, s[28:29] offset:256
	s_waitcnt vmcnt(12)
	v_lshlrev_b32_e32 v216, 16, v130
	v_and_b32_e32 v217, 0xffff0000, v130
	v_lshlrev_b32_e32 v218, 16, v131
	v_and_b32_e32 v219, 0xffff0000, v131
	v_lshlrev_b32_e32 v220, 16, v132
	v_and_b32_e32 v221, 0xffff0000, v132
	v_lshlrev_b32_e32 v222, 16, v133
	v_and_b32_e32 v223, 0xffff0000, v133
	v_pk_mul_f32 v[216:217], v[216:217], s[86:87] op_sel_hi:[1,0]
	v_pk_mul_f32 v[218:219], v[218:219], s[86:87] op_sel_hi:[1,0]
	v_pk_mul_f32 v[220:221], v[220:221], s[86:87] op_sel_hi:[1,0]
	v_pk_mul_f32 v[222:223], v[222:223], s[86:87] op_sel_hi:[1,0]
	v_exp_f32_e32 v216, v216
	v_exp_f32_e32 v217, v217
	v_exp_f32_e32 v218, v218
	v_exp_f32_e32 v219, v219
	v_exp_f32_e32 v220, v220
	v_exp_f32_e32 v221, v221
	v_exp_f32_e32 v222, v222
	v_exp_f32_e32 v223, v223
	v_pk_add_f32 v[216:217], v[216:217], 1.0 op_sel_hi:[1,0]
	v_pk_add_f32 v[218:219], v[218:219], 1.0 op_sel_hi:[1,0]
	v_pk_add_f32 v[220:221], v[220:221], 1.0 op_sel_hi:[1,0]
	v_pk_add_f32 v[222:223], v[222:223], 1.0 op_sel_hi:[1,0]
	v_rcp_f32_e32 v216, v216
	v_rcp_f32_e32 v217, v217
	v_rcp_f32_e32 v218, v218
	v_rcp_f32_e32 v219, v219
	v_rcp_f32_e32 v220, v220
	v_rcp_f32_e32 v221, v221
	v_rcp_f32_e32 v222, v222
	v_rcp_f32_e32 v223, v223
	v_lshlrev_b32_e32 v242, 16, v134
	v_and_b32_e32 v243, 0xffff0000, v134
	v_lshlrev_b32_e32 v244, 16, v135
	v_and_b32_e32 v245, 0xffff0000, v135
	v_lshlrev_b32_e32 v246, 16, v136
	v_and_b32_e32 v247, 0xffff0000, v136
	v_lshlrev_b32_e32 v248, 16, v137
	v_and_b32_e32 v249, 0xffff0000, v137
	v_pk_mul_f32 v[242:243], v[242:243], s[86:87] op_sel_hi:[1,0]
	v_pk_mul_f32 v[244:245], v[244:245], s[86:87] op_sel_hi:[1,0]
	v_pk_mul_f32 v[246:247], v[246:247], s[86:87] op_sel_hi:[1,0]
	v_pk_mul_f32 v[248:249], v[248:249], s[86:87] op_sel_hi:[1,0]
	v_exp_f32_e32 v242, v242
	v_exp_f32_e32 v243, v243
	v_exp_f32_e32 v244, v244
	v_exp_f32_e32 v245, v245
	v_exp_f32_e32 v246, v246
	v_exp_f32_e32 v247, v247
	v_exp_f32_e32 v248, v248
	v_exp_f32_e32 v249, v249
	v_pk_add_f32 v[242:243], v[242:243], 1.0 op_sel_hi:[1,0]
	v_pk_add_f32 v[244:245], v[244:245], 1.0 op_sel_hi:[1,0]
	v_pk_add_f32 v[246:247], v[246:247], 1.0 op_sel_hi:[1,0]
	v_pk_add_f32 v[248:249], v[248:249], 1.0 op_sel_hi:[1,0]
	v_pk_mul_f32 v[216:217], v[216:217], v[242:243]
	v_pk_mul_f32 v[218:219], v[218:219], v[244:245]
	v_pk_mul_f32 v[220:221], v[220:221], v[246:247]
	v_pk_mul_f32 v[222:223], v[222:223], v[248:249]
	v_pk_mul_f32 v[126:127], v[126:127], v[216:217]
	v_pk_mul_f32 v[128:129], v[128:129], v[218:219]
	v_pk_mul_f32 v[122:123], v[122:123], v[220:221]
	v_pk_mul_f32 v[124:125], v[124:125], v[222:223]
	v_lshlrev_b32_e32 v216, 16, v138
	v_and_b32_e32 v217, 0xffff0000, v138
	v_lshlrev_b32_e32 v218, 16, v139
	v_and_b32_e32 v219, 0xffff0000, v139
	v_lshlrev_b32_e32 v220, 16, v140
	v_and_b32_e32 v221, 0xffff0000, v140
	v_lshlrev_b32_e32 v222, 16, v141
	v_and_b32_e32 v223, 0xffff0000, v141
	v_pk_mul_f32 v[216:217], v[216:217], s[86:87] op_sel_hi:[1,0]
	v_pk_mul_f32 v[218:219], v[218:219], s[86:87] op_sel_hi:[1,0]
	v_pk_mul_f32 v[220:221], v[220:221], s[86:87] op_sel_hi:[1,0]
	v_pk_mul_f32 v[222:223], v[222:223], s[86:87] op_sel_hi:[1,0]
	v_exp_f32_e32 v216, v216
	v_exp_f32_e32 v217, v217
	v_exp_f32_e32 v218, v218
	v_exp_f32_e32 v219, v219
	v_exp_f32_e32 v220, v220
	v_exp_f32_e32 v221, v221
	v_exp_f32_e32 v222, v222
	v_exp_f32_e32 v223, v223
	v_pk_add_f32 v[216:217], v[216:217], 1.0 op_sel_hi:[1,0]
	v_pk_add_f32 v[218:219], v[218:219], 1.0 op_sel_hi:[1,0]
	v_pk_add_f32 v[220:221], v[220:221], 1.0 op_sel_hi:[1,0]
	v_pk_add_f32 v[222:223], v[222:223], 1.0 op_sel_hi:[1,0]
	v_rcp_f32_e32 v216, v216
	v_rcp_f32_e32 v217, v217
	v_rcp_f32_e32 v218, v218
	v_rcp_f32_e32 v219, v219
	v_rcp_f32_e32 v220, v220
	v_rcp_f32_e32 v221, v221
	v_rcp_f32_e32 v222, v222
	v_rcp_f32_e32 v223, v223
	v_lshlrev_b32_e32 v242, 16, v142
	v_and_b32_e32 v243, 0xffff0000, v142
	v_lshlrev_b32_e32 v244, 16, v143
	v_and_b32_e32 v245, 0xffff0000, v143
	v_lshlrev_b32_e32 v246, 16, v144
	v_and_b32_e32 v247, 0xffff0000, v144
	v_lshlrev_b32_e32 v248, 16, v145
	v_and_b32_e32 v249, 0xffff0000, v145
	v_pk_mul_f32 v[242:243], v[242:243], s[86:87] op_sel_hi:[1,0]
	v_pk_mul_f32 v[244:245], v[244:245], s[86:87] op_sel_hi:[1,0]
	v_pk_mul_f32 v[246:247], v[246:247], s[86:87] op_sel_hi:[1,0]
	v_pk_mul_f32 v[248:249], v[248:249], s[86:87] op_sel_hi:[1,0]
	v_exp_f32_e32 v242, v242
	v_exp_f32_e32 v243, v243
	v_exp_f32_e32 v244, v244
	v_exp_f32_e32 v245, v245
	v_exp_f32_e32 v246, v246
	v_exp_f32_e32 v247, v247
	v_exp_f32_e32 v248, v248
	v_exp_f32_e32 v249, v249
	v_pk_add_f32 v[242:243], v[242:243], 1.0 op_sel_hi:[1,0]
	v_pk_add_f32 v[244:245], v[244:245], 1.0 op_sel_hi:[1,0]
	v_pk_add_f32 v[246:247], v[246:247], 1.0 op_sel_hi:[1,0]
	v_pk_add_f32 v[248:249], v[248:249], 1.0 op_sel_hi:[1,0]
	v_pk_mul_f32 v[216:217], v[216:217], v[242:243]
	v_pk_mul_f32 v[218:219], v[218:219], v[244:245]
	v_pk_mul_f32 v[220:221], v[220:221], v[246:247]
	v_pk_mul_f32 v[222:223], v[222:223], v[248:249]
	v_pk_mul_f32 v[94:95], v[94:95], v[216:217]
	v_pk_mul_f32 v[96:97], v[96:97], v[218:219]
	v_pk_mul_f32 v[90:91], v[90:91], v[220:221]
	v_pk_mul_f32 v[92:93], v[92:93], v[222:223]
	s_add_u32 s28, s20, 0x340000
	s_addc_u32 s29, s21, 0
	global_load_dwordx4 v[130:133], v253, s[28:29]
	global_load_dwordx4 v[134:137], v254, s[28:29]
	global_load_dwordx4 v[138:141], v253, s[28:29] offset:256
	global_load_dwordx4 v[142:145], v254, s[28:29] offset:256
	s_waitcnt vmcnt(12)
	v_lshlrev_b32_e32 v216, 16, v146
	v_and_b32_e32 v217, 0xffff0000, v146
	v_lshlrev_b32_e32 v218, 16, v147
	v_and_b32_e32 v219, 0xffff0000, v147
	v_lshlrev_b32_e32 v220, 16, v148
	v_and_b32_e32 v221, 0xffff0000, v148
	v_lshlrev_b32_e32 v222, 16, v149
	v_and_b32_e32 v223, 0xffff0000, v149
	v_pk_mul_f32 v[216:217], v[216:217], s[86:87] op_sel_hi:[1,0]
	v_pk_mul_f32 v[218:219], v[218:219], s[86:87] op_sel_hi:[1,0]
	v_pk_mul_f32 v[220:221], v[220:221], s[86:87] op_sel_hi:[1,0]
	v_pk_mul_f32 v[222:223], v[222:223], s[86:87] op_sel_hi:[1,0]
	v_exp_f32_e32 v216, v216
	v_exp_f32_e32 v217, v217
	v_exp_f32_e32 v218, v218
	v_exp_f32_e32 v219, v219
	v_exp_f32_e32 v220, v220
	v_exp_f32_e32 v221, v221
	v_exp_f32_e32 v222, v222
	v_exp_f32_e32 v223, v223
	v_pk_add_f32 v[216:217], v[216:217], 1.0 op_sel_hi:[1,0]
	v_pk_add_f32 v[218:219], v[218:219], 1.0 op_sel_hi:[1,0]
	v_pk_add_f32 v[220:221], v[220:221], 1.0 op_sel_hi:[1,0]
	v_pk_add_f32 v[222:223], v[222:223], 1.0 op_sel_hi:[1,0]
	v_rcp_f32_e32 v216, v216
	v_rcp_f32_e32 v217, v217
	v_rcp_f32_e32 v218, v218
	v_rcp_f32_e32 v219, v219
	v_rcp_f32_e32 v220, v220
	v_rcp_f32_e32 v221, v221
	v_rcp_f32_e32 v222, v222
	v_rcp_f32_e32 v223, v223
	v_lshlrev_b32_e32 v242, 16, v150
	v_and_b32_e32 v243, 0xffff0000, v150
	v_lshlrev_b32_e32 v244, 16, v151
	v_and_b32_e32 v245, 0xffff0000, v151
	v_lshlrev_b32_e32 v246, 16, v152
	v_and_b32_e32 v247, 0xffff0000, v152
	v_lshlrev_b32_e32 v248, 16, v153
	v_and_b32_e32 v249, 0xffff0000, v153
	v_pk_mul_f32 v[242:243], v[242:243], s[86:87] op_sel_hi:[1,0]
	v_pk_mul_f32 v[244:245], v[244:245], s[86:87] op_sel_hi:[1,0]
	v_pk_mul_f32 v[246:247], v[246:247], s[86:87] op_sel_hi:[1,0]
	v_pk_mul_f32 v[248:249], v[248:249], s[86:87] op_sel_hi:[1,0]
	v_exp_f32_e32 v242, v242
	v_exp_f32_e32 v243, v243
	v_exp_f32_e32 v244, v244
	v_exp_f32_e32 v245, v245
	v_exp_f32_e32 v246, v246
	v_exp_f32_e32 v247, v247
	v_exp_f32_e32 v248, v248
	v_exp_f32_e32 v249, v249
	v_pk_add_f32 v[242:243], v[242:243], 1.0 op_sel_hi:[1,0]
	v_pk_add_f32 v[244:245], v[244:245], 1.0 op_sel_hi:[1,0]
	v_pk_add_f32 v[246:247], v[246:247], 1.0 op_sel_hi:[1,0]
	v_pk_add_f32 v[248:249], v[248:249], 1.0 op_sel_hi:[1,0]
	v_pk_mul_f32 v[216:217], v[216:217], v[242:243]
	v_pk_mul_f32 v[218:219], v[218:219], v[244:245]
	v_pk_mul_f32 v[220:221], v[220:221], v[246:247]
	v_pk_mul_f32 v[222:223], v[222:223], v[248:249]
	v_pk_mul_f32 v[118:119], v[118:119], v[216:217]
	v_pk_mul_f32 v[120:121], v[120:121], v[218:219]
	v_pk_mul_f32 v[114:115], v[114:115], v[220:221]
	v_pk_mul_f32 v[116:117], v[116:117], v[222:223]
	v_lshlrev_b32_e32 v216, 16, v154
	v_and_b32_e32 v217, 0xffff0000, v154
	v_lshlrev_b32_e32 v218, 16, v155
	v_and_b32_e32 v219, 0xffff0000, v155
	v_lshlrev_b32_e32 v220, 16, v156
	v_and_b32_e32 v221, 0xffff0000, v156
	v_lshlrev_b32_e32 v222, 16, v157
	v_and_b32_e32 v223, 0xffff0000, v157
	v_pk_mul_f32 v[216:217], v[216:217], s[86:87] op_sel_hi:[1,0]
	v_pk_mul_f32 v[218:219], v[218:219], s[86:87] op_sel_hi:[1,0]
	v_pk_mul_f32 v[220:221], v[220:221], s[86:87] op_sel_hi:[1,0]
	v_pk_mul_f32 v[222:223], v[222:223], s[86:87] op_sel_hi:[1,0]
	v_exp_f32_e32 v216, v216
	v_exp_f32_e32 v217, v217
	v_exp_f32_e32 v218, v218
	v_exp_f32_e32 v219, v219
	v_exp_f32_e32 v220, v220
	v_exp_f32_e32 v221, v221
	v_exp_f32_e32 v222, v222
	v_exp_f32_e32 v223, v223
	v_pk_add_f32 v[216:217], v[216:217], 1.0 op_sel_hi:[1,0]
	v_pk_add_f32 v[218:219], v[218:219], 1.0 op_sel_hi:[1,0]
	v_pk_add_f32 v[220:221], v[220:221], 1.0 op_sel_hi:[1,0]
	v_pk_add_f32 v[222:223], v[222:223], 1.0 op_sel_hi:[1,0]
	v_rcp_f32_e32 v216, v216
	v_rcp_f32_e32 v217, v217
	v_rcp_f32_e32 v218, v218
	v_rcp_f32_e32 v219, v219
	v_rcp_f32_e32 v220, v220
	v_rcp_f32_e32 v221, v221
	v_rcp_f32_e32 v222, v222
	v_rcp_f32_e32 v223, v223
	v_lshlrev_b32_e32 v242, 16, v158
	v_and_b32_e32 v243, 0xffff0000, v158
	v_lshlrev_b32_e32 v244, 16, v159
	v_and_b32_e32 v245, 0xffff0000, v159
	v_lshlrev_b32_e32 v246, 16, v160
	v_and_b32_e32 v247, 0xffff0000, v160
	v_lshlrev_b32_e32 v248, 16, v161
	v_and_b32_e32 v249, 0xffff0000, v161
	v_pk_mul_f32 v[242:243], v[242:243], s[86:87] op_sel_hi:[1,0]
	v_pk_mul_f32 v[244:245], v[244:245], s[86:87] op_sel_hi:[1,0]
	v_pk_mul_f32 v[246:247], v[246:247], s[86:87] op_sel_hi:[1,0]
	v_pk_mul_f32 v[248:249], v[248:249], s[86:87] op_sel_hi:[1,0]
	v_exp_f32_e32 v242, v242
	v_exp_f32_e32 v243, v243
	v_exp_f32_e32 v244, v244
	v_exp_f32_e32 v245, v245
	v_exp_f32_e32 v246, v246
	v_exp_f32_e32 v247, v247
	v_exp_f32_e32 v248, v248
	v_exp_f32_e32 v249, v249
	v_pk_add_f32 v[242:243], v[242:243], 1.0 op_sel_hi:[1,0]
	v_pk_add_f32 v[244:245], v[244:245], 1.0 op_sel_hi:[1,0]
	v_pk_add_f32 v[246:247], v[246:247], 1.0 op_sel_hi:[1,0]
	v_pk_add_f32 v[248:249], v[248:249], 1.0 op_sel_hi:[1,0]
	v_pk_mul_f32 v[216:217], v[216:217], v[242:243]
	v_pk_mul_f32 v[218:219], v[218:219], v[244:245]
	v_pk_mul_f32 v[220:221], v[220:221], v[246:247]
	v_pk_mul_f32 v[222:223], v[222:223], v[248:249]
	v_pk_mul_f32 v[86:87], v[86:87], v[216:217]
	v_pk_mul_f32 v[88:89], v[88:89], v[218:219]
	v_pk_mul_f32 v[82:83], v[82:83], v[220:221]
	v_pk_mul_f32 v[84:85], v[84:85], v[222:223]
	s_add_u32 s28, s20, 0x3a8000
	s_addc_u32 s29, s21, 0
	global_load_dwordx4 v[146:149], v253, s[28:29]
	global_load_dwordx4 v[150:153], v254, s[28:29]
	global_load_dwordx4 v[154:157], v253, s[28:29] offset:256
	global_load_dwordx4 v[158:161], v254, s[28:29] offset:256
	s_waitcnt vmcnt(12)
	v_lshlrev_b32_e32 v216, 16, v162
	v_and_b32_e32 v217, 0xffff0000, v162
	v_lshlrev_b32_e32 v218, 16, v163
	v_and_b32_e32 v219, 0xffff0000, v163
	v_lshlrev_b32_e32 v220, 16, v164
	v_and_b32_e32 v221, 0xffff0000, v164
	v_lshlrev_b32_e32 v222, 16, v165
	v_and_b32_e32 v223, 0xffff0000, v165
	v_pk_mul_f32 v[216:217], v[216:217], s[86:87] op_sel_hi:[1,0]
	v_pk_mul_f32 v[218:219], v[218:219], s[86:87] op_sel_hi:[1,0]
	v_pk_mul_f32 v[220:221], v[220:221], s[86:87] op_sel_hi:[1,0]
	v_pk_mul_f32 v[222:223], v[222:223], s[86:87] op_sel_hi:[1,0]
	v_exp_f32_e32 v216, v216
	v_exp_f32_e32 v217, v217
	v_exp_f32_e32 v218, v218
	v_exp_f32_e32 v219, v219
	v_exp_f32_e32 v220, v220
	v_exp_f32_e32 v221, v221
	v_exp_f32_e32 v222, v222
	v_exp_f32_e32 v223, v223
	v_pk_add_f32 v[216:217], v[216:217], 1.0 op_sel_hi:[1,0]
	v_pk_add_f32 v[218:219], v[218:219], 1.0 op_sel_hi:[1,0]
	v_pk_add_f32 v[220:221], v[220:221], 1.0 op_sel_hi:[1,0]
	v_pk_add_f32 v[222:223], v[222:223], 1.0 op_sel_hi:[1,0]
	v_rcp_f32_e32 v216, v216
	v_rcp_f32_e32 v217, v217
	v_rcp_f32_e32 v218, v218
	v_rcp_f32_e32 v219, v219
	v_rcp_f32_e32 v220, v220
	v_rcp_f32_e32 v221, v221
	v_rcp_f32_e32 v222, v222
	v_rcp_f32_e32 v223, v223
	v_lshlrev_b32_e32 v242, 16, v166
	v_and_b32_e32 v243, 0xffff0000, v166
	v_lshlrev_b32_e32 v244, 16, v167
	v_and_b32_e32 v245, 0xffff0000, v167
	v_lshlrev_b32_e32 v246, 16, v168
	v_and_b32_e32 v247, 0xffff0000, v168
	v_lshlrev_b32_e32 v248, 16, v169
	v_and_b32_e32 v249, 0xffff0000, v169
	v_pk_mul_f32 v[242:243], v[242:243], s[86:87] op_sel_hi:[1,0]
	v_pk_mul_f32 v[244:245], v[244:245], s[86:87] op_sel_hi:[1,0]
	v_pk_mul_f32 v[246:247], v[246:247], s[86:87] op_sel_hi:[1,0]
	v_pk_mul_f32 v[248:249], v[248:249], s[86:87] op_sel_hi:[1,0]
	v_exp_f32_e32 v242, v242
	v_exp_f32_e32 v243, v243
	v_exp_f32_e32 v244, v244
	v_exp_f32_e32 v245, v245
	v_exp_f32_e32 v246, v246
	v_exp_f32_e32 v247, v247
	v_exp_f32_e32 v248, v248
	v_exp_f32_e32 v249, v249
	v_pk_add_f32 v[242:243], v[242:243], 1.0 op_sel_hi:[1,0]
	v_pk_add_f32 v[244:245], v[244:245], 1.0 op_sel_hi:[1,0]
	v_pk_add_f32 v[246:247], v[246:247], 1.0 op_sel_hi:[1,0]
	v_pk_add_f32 v[248:249], v[248:249], 1.0 op_sel_hi:[1,0]
	v_pk_mul_f32 v[216:217], v[216:217], v[242:243]
	v_pk_mul_f32 v[218:219], v[218:219], v[244:245]
	v_pk_mul_f32 v[220:221], v[220:221], v[246:247]
	v_pk_mul_f32 v[222:223], v[222:223], v[248:249]
	v_pk_mul_f32 v[110:111], v[110:111], v[216:217]
	v_pk_mul_f32 v[112:113], v[112:113], v[218:219]
	v_pk_mul_f32 v[106:107], v[106:107], v[220:221]
	v_pk_mul_f32 v[108:109], v[108:109], v[222:223]
	v_lshlrev_b32_e32 v216, 16, v170
	v_and_b32_e32 v217, 0xffff0000, v170
	v_lshlrev_b32_e32 v218, 16, v171
	v_and_b32_e32 v219, 0xffff0000, v171
	v_lshlrev_b32_e32 v220, 16, v172
	v_and_b32_e32 v221, 0xffff0000, v172
	v_lshlrev_b32_e32 v222, 16, v173
	v_and_b32_e32 v223, 0xffff0000, v173
	v_pk_mul_f32 v[216:217], v[216:217], s[86:87] op_sel_hi:[1,0]
	v_pk_mul_f32 v[218:219], v[218:219], s[86:87] op_sel_hi:[1,0]
	v_pk_mul_f32 v[220:221], v[220:221], s[86:87] op_sel_hi:[1,0]
	v_pk_mul_f32 v[222:223], v[222:223], s[86:87] op_sel_hi:[1,0]
	v_exp_f32_e32 v216, v216
	v_exp_f32_e32 v217, v217
	v_exp_f32_e32 v218, v218
	v_exp_f32_e32 v219, v219
	v_exp_f32_e32 v220, v220
	v_exp_f32_e32 v221, v221
	v_exp_f32_e32 v222, v222
	v_exp_f32_e32 v223, v223
	v_pk_add_f32 v[216:217], v[216:217], 1.0 op_sel_hi:[1,0]
	v_pk_add_f32 v[218:219], v[218:219], 1.0 op_sel_hi:[1,0]
	v_pk_add_f32 v[220:221], v[220:221], 1.0 op_sel_hi:[1,0]
	v_pk_add_f32 v[222:223], v[222:223], 1.0 op_sel_hi:[1,0]
	v_rcp_f32_e32 v216, v216
	v_rcp_f32_e32 v217, v217
	v_rcp_f32_e32 v218, v218
	v_rcp_f32_e32 v219, v219
	v_rcp_f32_e32 v220, v220
	v_rcp_f32_e32 v221, v221
	v_rcp_f32_e32 v222, v222
	v_rcp_f32_e32 v223, v223
	v_lshlrev_b32_e32 v242, 16, v174
	v_and_b32_e32 v243, 0xffff0000, v174
	v_lshlrev_b32_e32 v244, 16, v175
	v_and_b32_e32 v245, 0xffff0000, v175
	v_lshlrev_b32_e32 v246, 16, v176
	v_and_b32_e32 v247, 0xffff0000, v176
	v_lshlrev_b32_e32 v248, 16, v177
	v_and_b32_e32 v249, 0xffff0000, v177
	v_pk_mul_f32 v[242:243], v[242:243], s[86:87] op_sel_hi:[1,0]
	v_pk_mul_f32 v[244:245], v[244:245], s[86:87] op_sel_hi:[1,0]
	v_pk_mul_f32 v[246:247], v[246:247], s[86:87] op_sel_hi:[1,0]
	v_pk_mul_f32 v[248:249], v[248:249], s[86:87] op_sel_hi:[1,0]
	v_exp_f32_e32 v242, v242
	v_exp_f32_e32 v243, v243
	v_exp_f32_e32 v244, v244
	v_exp_f32_e32 v245, v245
	v_exp_f32_e32 v246, v246
	v_exp_f32_e32 v247, v247
	v_exp_f32_e32 v248, v248
	v_exp_f32_e32 v249, v249
	v_pk_add_f32 v[242:243], v[242:243], 1.0 op_sel_hi:[1,0]
	v_pk_add_f32 v[244:245], v[244:245], 1.0 op_sel_hi:[1,0]
	v_pk_add_f32 v[246:247], v[246:247], 1.0 op_sel_hi:[1,0]
	v_pk_add_f32 v[248:249], v[248:249], 1.0 op_sel_hi:[1,0]
	v_pk_mul_f32 v[216:217], v[216:217], v[242:243]
	v_pk_mul_f32 v[218:219], v[218:219], v[244:245]
	v_pk_mul_f32 v[220:221], v[220:221], v[246:247]
	v_pk_mul_f32 v[222:223], v[222:223], v[248:249]
	v_pk_mul_f32 v[78:79], v[78:79], v[216:217]
	v_pk_mul_f32 v[80:81], v[80:81], v[218:219]
	v_pk_mul_f32 v[74:75], v[74:75], v[220:221]
	v_pk_mul_f32 v[76:77], v[76:77], v[222:223]
	s_add_u32 s28, s20, 0x410000
	s_addc_u32 s29, s21, 0
	global_load_dwordx4 v[162:165], v253, s[28:29]
	global_load_dwordx4 v[166:169], v254, s[28:29]
	global_load_dwordx4 v[170:173], v253, s[28:29] offset:256
	global_load_dwordx4 v[174:177], v254, s[28:29] offset:256
	s_waitcnt vmcnt(12)
	v_lshlrev_b32_e32 v216, 16, v178
	v_and_b32_e32 v217, 0xffff0000, v178
	v_lshlrev_b32_e32 v218, 16, v179
	v_and_b32_e32 v219, 0xffff0000, v179
	v_lshlrev_b32_e32 v220, 16, v180
	v_and_b32_e32 v221, 0xffff0000, v180
	v_lshlrev_b32_e32 v222, 16, v181
	v_and_b32_e32 v223, 0xffff0000, v181
	v_pk_mul_f32 v[216:217], v[216:217], s[86:87] op_sel_hi:[1,0]
	v_pk_mul_f32 v[218:219], v[218:219], s[86:87] op_sel_hi:[1,0]
	v_pk_mul_f32 v[220:221], v[220:221], s[86:87] op_sel_hi:[1,0]
	v_pk_mul_f32 v[222:223], v[222:223], s[86:87] op_sel_hi:[1,0]
	v_exp_f32_e32 v216, v216
	v_exp_f32_e32 v217, v217
	v_exp_f32_e32 v218, v218
	v_exp_f32_e32 v219, v219
	v_exp_f32_e32 v220, v220
	v_exp_f32_e32 v221, v221
	v_exp_f32_e32 v222, v222
	v_exp_f32_e32 v223, v223
	v_pk_add_f32 v[216:217], v[216:217], 1.0 op_sel_hi:[1,0]
	v_pk_add_f32 v[218:219], v[218:219], 1.0 op_sel_hi:[1,0]
	v_pk_add_f32 v[220:221], v[220:221], 1.0 op_sel_hi:[1,0]
	v_pk_add_f32 v[222:223], v[222:223], 1.0 op_sel_hi:[1,0]
	v_rcp_f32_e32 v216, v216
	v_rcp_f32_e32 v217, v217
	v_rcp_f32_e32 v218, v218
	v_rcp_f32_e32 v219, v219
	v_rcp_f32_e32 v220, v220
	v_rcp_f32_e32 v221, v221
	v_rcp_f32_e32 v222, v222
	v_rcp_f32_e32 v223, v223
	v_lshlrev_b32_e32 v242, 16, v182
	v_and_b32_e32 v243, 0xffff0000, v182
	v_lshlrev_b32_e32 v244, 16, v183
	v_and_b32_e32 v245, 0xffff0000, v183
	v_lshlrev_b32_e32 v246, 16, v184
	v_and_b32_e32 v247, 0xffff0000, v184
	v_lshlrev_b32_e32 v248, 16, v185
	v_and_b32_e32 v249, 0xffff0000, v185
	v_pk_mul_f32 v[242:243], v[242:243], s[86:87] op_sel_hi:[1,0]
	v_pk_mul_f32 v[244:245], v[244:245], s[86:87] op_sel_hi:[1,0]
	v_pk_mul_f32 v[246:247], v[246:247], s[86:87] op_sel_hi:[1,0]
	v_pk_mul_f32 v[248:249], v[248:249], s[86:87] op_sel_hi:[1,0]
	v_exp_f32_e32 v242, v242
	v_exp_f32_e32 v243, v243
	v_exp_f32_e32 v244, v244
	v_exp_f32_e32 v245, v245
	v_exp_f32_e32 v246, v246
	v_exp_f32_e32 v247, v247
	v_exp_f32_e32 v248, v248
	v_exp_f32_e32 v249, v249
	v_pk_add_f32 v[242:243], v[242:243], 1.0 op_sel_hi:[1,0]
	v_pk_add_f32 v[244:245], v[244:245], 1.0 op_sel_hi:[1,0]
	v_pk_add_f32 v[246:247], v[246:247], 1.0 op_sel_hi:[1,0]
	v_pk_add_f32 v[248:249], v[248:249], 1.0 op_sel_hi:[1,0]
	v_pk_mul_f32 v[216:217], v[216:217], v[242:243]
	v_pk_mul_f32 v[218:219], v[218:219], v[244:245]
	v_pk_mul_f32 v[220:221], v[220:221], v[246:247]
	v_pk_mul_f32 v[222:223], v[222:223], v[248:249]
	v_pk_mul_f32 v[102:103], v[102:103], v[216:217]
	v_pk_mul_f32 v[104:105], v[104:105], v[218:219]
	v_pk_mul_f32 v[98:99], v[98:99], v[220:221]
	v_pk_mul_f32 v[100:101], v[100:101], v[222:223]
	v_lshlrev_b32_e32 v216, 16, v186
	v_and_b32_e32 v217, 0xffff0000, v186
	v_lshlrev_b32_e32 v218, 16, v187
	v_and_b32_e32 v219, 0xffff0000, v187
	v_lshlrev_b32_e32 v220, 16, v188
	v_and_b32_e32 v221, 0xffff0000, v188
	v_lshlrev_b32_e32 v222, 16, v189
	v_and_b32_e32 v223, 0xffff0000, v189
	v_pk_mul_f32 v[216:217], v[216:217], s[86:87] op_sel_hi:[1,0]
	v_pk_mul_f32 v[218:219], v[218:219], s[86:87] op_sel_hi:[1,0]
	v_pk_mul_f32 v[220:221], v[220:221], s[86:87] op_sel_hi:[1,0]
	v_pk_mul_f32 v[222:223], v[222:223], s[86:87] op_sel_hi:[1,0]
	v_exp_f32_e32 v216, v216
	v_exp_f32_e32 v217, v217
	v_exp_f32_e32 v218, v218
	v_exp_f32_e32 v219, v219
	v_exp_f32_e32 v220, v220
	v_exp_f32_e32 v221, v221
	v_exp_f32_e32 v222, v222
	v_exp_f32_e32 v223, v223
	v_pk_add_f32 v[216:217], v[216:217], 1.0 op_sel_hi:[1,0]
	v_pk_add_f32 v[218:219], v[218:219], 1.0 op_sel_hi:[1,0]
	v_pk_add_f32 v[220:221], v[220:221], 1.0 op_sel_hi:[1,0]
	v_pk_add_f32 v[222:223], v[222:223], 1.0 op_sel_hi:[1,0]
	v_rcp_f32_e32 v216, v216
	v_rcp_f32_e32 v217, v217
	v_rcp_f32_e32 v218, v218
	v_rcp_f32_e32 v219, v219
	v_rcp_f32_e32 v220, v220
	v_rcp_f32_e32 v221, v221
	v_rcp_f32_e32 v222, v222
	v_rcp_f32_e32 v223, v223
	v_lshlrev_b32_e32 v242, 16, v190
	v_and_b32_e32 v243, 0xffff0000, v190
	v_lshlrev_b32_e32 v244, 16, v191
	v_and_b32_e32 v245, 0xffff0000, v191
	v_lshlrev_b32_e32 v246, 16, v192
	v_and_b32_e32 v247, 0xffff0000, v192
	v_lshlrev_b32_e32 v248, 16, v193
	v_and_b32_e32 v249, 0xffff0000, v193
	v_pk_mul_f32 v[242:243], v[242:243], s[86:87] op_sel_hi:[1,0]
	v_pk_mul_f32 v[244:245], v[244:245], s[86:87] op_sel_hi:[1,0]
	v_pk_mul_f32 v[246:247], v[246:247], s[86:87] op_sel_hi:[1,0]
	v_pk_mul_f32 v[248:249], v[248:249], s[86:87] op_sel_hi:[1,0]
	v_exp_f32_e32 v242, v242
	v_exp_f32_e32 v243, v243
	v_exp_f32_e32 v244, v244
	v_exp_f32_e32 v245, v245
	v_exp_f32_e32 v246, v246
	v_exp_f32_e32 v247, v247
	v_exp_f32_e32 v248, v248
	v_exp_f32_e32 v249, v249
	v_pk_add_f32 v[242:243], v[242:243], 1.0 op_sel_hi:[1,0]
	v_pk_add_f32 v[244:245], v[244:245], 1.0 op_sel_hi:[1,0]
	v_pk_add_f32 v[246:247], v[246:247], 1.0 op_sel_hi:[1,0]
	v_pk_add_f32 v[248:249], v[248:249], 1.0 op_sel_hi:[1,0]
	v_pk_mul_f32 v[216:217], v[216:217], v[242:243]
	v_pk_mul_f32 v[218:219], v[218:219], v[244:245]
	v_pk_mul_f32 v[220:221], v[220:221], v[246:247]
	v_pk_mul_f32 v[222:223], v[222:223], v[248:249]
	v_pk_mul_f32 v[70:71], v[70:71], v[216:217]
	v_pk_mul_f32 v[72:73], v[72:73], v[218:219]
	v_pk_mul_f32 v[66:67], v[66:67], v[220:221]
	v_pk_mul_f32 v[68:69], v[68:69], v[222:223]
	s_add_u32 s28, s20, 0x478000
	s_addc_u32 s29, s21, 0
	global_load_dwordx4 v[178:181], v253, s[28:29]
	global_load_dwordx4 v[182:185], v254, s[28:29]
	global_load_dwordx4 v[186:189], v253, s[28:29] offset:256
	global_load_dwordx4 v[190:193], v254, s[28:29] offset:256
	s_waitcnt vmcnt(12)
	v_lshlrev_b32_e32 v216, 16, v130
	v_and_b32_e32 v217, 0xffff0000, v130
	v_lshlrev_b32_e32 v218, 16, v131
	v_and_b32_e32 v219, 0xffff0000, v131
	v_lshlrev_b32_e32 v220, 16, v132
	v_and_b32_e32 v221, 0xffff0000, v132
	v_lshlrev_b32_e32 v222, 16, v133
	v_and_b32_e32 v223, 0xffff0000, v133
	v_pk_mul_f32 v[216:217], v[216:217], s[86:87] op_sel_hi:[1,0]
	v_pk_mul_f32 v[218:219], v[218:219], s[86:87] op_sel_hi:[1,0]
	v_pk_mul_f32 v[220:221], v[220:221], s[86:87] op_sel_hi:[1,0]
	v_pk_mul_f32 v[222:223], v[222:223], s[86:87] op_sel_hi:[1,0]
	v_exp_f32_e32 v216, v216
	v_exp_f32_e32 v217, v217
	v_exp_f32_e32 v218, v218
	v_exp_f32_e32 v219, v219
	v_exp_f32_e32 v220, v220
	v_exp_f32_e32 v221, v221
	v_exp_f32_e32 v222, v222
	v_exp_f32_e32 v223, v223
	v_pk_add_f32 v[216:217], v[216:217], 1.0 op_sel_hi:[1,0]
	v_pk_add_f32 v[218:219], v[218:219], 1.0 op_sel_hi:[1,0]
	v_pk_add_f32 v[220:221], v[220:221], 1.0 op_sel_hi:[1,0]
	v_pk_add_f32 v[222:223], v[222:223], 1.0 op_sel_hi:[1,0]
	v_rcp_f32_e32 v216, v216
	v_rcp_f32_e32 v217, v217
	v_rcp_f32_e32 v218, v218
	v_rcp_f32_e32 v219, v219
	v_rcp_f32_e32 v220, v220
	v_rcp_f32_e32 v221, v221
	v_rcp_f32_e32 v222, v222
	v_rcp_f32_e32 v223, v223
	v_lshlrev_b32_e32 v242, 16, v134
	v_and_b32_e32 v243, 0xffff0000, v134
	v_lshlrev_b32_e32 v244, 16, v135
	v_and_b32_e32 v245, 0xffff0000, v135
	v_lshlrev_b32_e32 v246, 16, v136
	v_and_b32_e32 v247, 0xffff0000, v136
	v_lshlrev_b32_e32 v248, 16, v137
	v_and_b32_e32 v249, 0xffff0000, v137
	v_pk_mul_f32 v[242:243], v[242:243], s[86:87] op_sel_hi:[1,0]
	v_pk_mul_f32 v[244:245], v[244:245], s[86:87] op_sel_hi:[1,0]
	v_pk_mul_f32 v[246:247], v[246:247], s[86:87] op_sel_hi:[1,0]
	v_pk_mul_f32 v[248:249], v[248:249], s[86:87] op_sel_hi:[1,0]
	v_exp_f32_e32 v242, v242
	v_exp_f32_e32 v243, v243
	v_exp_f32_e32 v244, v244
	v_exp_f32_e32 v245, v245
	v_exp_f32_e32 v246, v246
	v_exp_f32_e32 v247, v247
	v_exp_f32_e32 v248, v248
	v_exp_f32_e32 v249, v249
	v_pk_add_f32 v[242:243], v[242:243], 1.0 op_sel_hi:[1,0]
	v_pk_add_f32 v[244:245], v[244:245], 1.0 op_sel_hi:[1,0]
	v_pk_add_f32 v[246:247], v[246:247], 1.0 op_sel_hi:[1,0]
	v_pk_add_f32 v[248:249], v[248:249], 1.0 op_sel_hi:[1,0]
	v_pk_mul_f32 v[216:217], v[216:217], v[242:243]
	v_pk_mul_f32 v[218:219], v[218:219], v[244:245]
	v_pk_mul_f32 v[220:221], v[220:221], v[246:247]
	v_pk_mul_f32 v[222:223], v[222:223], v[248:249]
	v_pk_mul_f32 v[62:63], v[62:63], v[216:217]
	v_pk_mul_f32 v[64:65], v[64:65], v[218:219]
	v_pk_mul_f32 v[58:59], v[58:59], v[220:221]
	v_pk_mul_f32 v[60:61], v[60:61], v[222:223]
	v_lshlrev_b32_e32 v216, 16, v138
	v_and_b32_e32 v217, 0xffff0000, v138
	v_lshlrev_b32_e32 v218, 16, v139
	v_and_b32_e32 v219, 0xffff0000, v139
	v_lshlrev_b32_e32 v220, 16, v140
	v_and_b32_e32 v221, 0xffff0000, v140
	v_lshlrev_b32_e32 v222, 16, v141
	v_and_b32_e32 v223, 0xffff0000, v141
	v_pk_mul_f32 v[216:217], v[216:217], s[86:87] op_sel_hi:[1,0]
	v_pk_mul_f32 v[218:219], v[218:219], s[86:87] op_sel_hi:[1,0]
	v_pk_mul_f32 v[220:221], v[220:221], s[86:87] op_sel_hi:[1,0]
	v_pk_mul_f32 v[222:223], v[222:223], s[86:87] op_sel_hi:[1,0]
	v_exp_f32_e32 v216, v216
	v_exp_f32_e32 v217, v217
	v_exp_f32_e32 v218, v218
	v_exp_f32_e32 v219, v219
	v_exp_f32_e32 v220, v220
	v_exp_f32_e32 v221, v221
	v_exp_f32_e32 v222, v222
	v_exp_f32_e32 v223, v223
	v_pk_add_f32 v[216:217], v[216:217], 1.0 op_sel_hi:[1,0]
	v_pk_add_f32 v[218:219], v[218:219], 1.0 op_sel_hi:[1,0]
	v_pk_add_f32 v[220:221], v[220:221], 1.0 op_sel_hi:[1,0]
	v_pk_add_f32 v[222:223], v[222:223], 1.0 op_sel_hi:[1,0]
	v_rcp_f32_e32 v216, v216
	v_rcp_f32_e32 v217, v217
	v_rcp_f32_e32 v218, v218
	v_rcp_f32_e32 v219, v219
	v_rcp_f32_e32 v220, v220
	v_rcp_f32_e32 v221, v221
	v_rcp_f32_e32 v222, v222
	v_rcp_f32_e32 v223, v223
	v_lshlrev_b32_e32 v242, 16, v142
	v_and_b32_e32 v243, 0xffff0000, v142
	v_lshlrev_b32_e32 v244, 16, v143
	v_and_b32_e32 v245, 0xffff0000, v143
	v_lshlrev_b32_e32 v246, 16, v144
	v_and_b32_e32 v247, 0xffff0000, v144
	v_lshlrev_b32_e32 v248, 16, v145
	v_and_b32_e32 v249, 0xffff0000, v145
	v_pk_mul_f32 v[242:243], v[242:243], s[86:87] op_sel_hi:[1,0]
	v_pk_mul_f32 v[244:245], v[244:245], s[86:87] op_sel_hi:[1,0]
	v_pk_mul_f32 v[246:247], v[246:247], s[86:87] op_sel_hi:[1,0]
	v_pk_mul_f32 v[248:249], v[248:249], s[86:87] op_sel_hi:[1,0]
	v_exp_f32_e32 v242, v242
	v_exp_f32_e32 v243, v243
	v_exp_f32_e32 v244, v244
	v_exp_f32_e32 v245, v245
	v_exp_f32_e32 v246, v246
	v_exp_f32_e32 v247, v247
	v_exp_f32_e32 v248, v248
	v_exp_f32_e32 v249, v249
	v_pk_add_f32 v[242:243], v[242:243], 1.0 op_sel_hi:[1,0]
	v_pk_add_f32 v[244:245], v[244:245], 1.0 op_sel_hi:[1,0]
	v_pk_add_f32 v[246:247], v[246:247], 1.0 op_sel_hi:[1,0]
	v_pk_add_f32 v[248:249], v[248:249], 1.0 op_sel_hi:[1,0]
	v_pk_mul_f32 v[216:217], v[216:217], v[242:243]
	v_pk_mul_f32 v[218:219], v[218:219], v[244:245]
	v_pk_mul_f32 v[220:221], v[220:221], v[246:247]
	v_pk_mul_f32 v[222:223], v[222:223], v[248:249]
	v_pk_mul_f32 v[30:31], v[30:31], v[216:217]
	v_pk_mul_f32 v[32:33], v[32:33], v[218:219]
	v_pk_mul_f32 v[26:27], v[26:27], v[220:221]
	v_pk_mul_f32 v[28:29], v[28:29], v[222:223]
	s_waitcnt vmcnt(8)
	v_lshlrev_b32_e32 v216, 16, v146
	v_and_b32_e32 v217, 0xffff0000, v146
	v_lshlrev_b32_e32 v218, 16, v147
	v_and_b32_e32 v219, 0xffff0000, v147
	v_lshlrev_b32_e32 v220, 16, v148
	v_and_b32_e32 v221, 0xffff0000, v148
	v_lshlrev_b32_e32 v222, 16, v149
	v_and_b32_e32 v223, 0xffff0000, v149
	v_pk_mul_f32 v[216:217], v[216:217], s[86:87] op_sel_hi:[1,0]
	v_pk_mul_f32 v[218:219], v[218:219], s[86:87] op_sel_hi:[1,0]
	v_pk_mul_f32 v[220:221], v[220:221], s[86:87] op_sel_hi:[1,0]
	v_pk_mul_f32 v[222:223], v[222:223], s[86:87] op_sel_hi:[1,0]
	v_exp_f32_e32 v216, v216
	v_exp_f32_e32 v217, v217
	v_exp_f32_e32 v218, v218
	v_exp_f32_e32 v219, v219
	v_exp_f32_e32 v220, v220
	v_exp_f32_e32 v221, v221
	v_exp_f32_e32 v222, v222
	v_exp_f32_e32 v223, v223
	v_pk_add_f32 v[216:217], v[216:217], 1.0 op_sel_hi:[1,0]
	v_pk_add_f32 v[218:219], v[218:219], 1.0 op_sel_hi:[1,0]
	v_pk_add_f32 v[220:221], v[220:221], 1.0 op_sel_hi:[1,0]
	v_pk_add_f32 v[222:223], v[222:223], 1.0 op_sel_hi:[1,0]
	v_rcp_f32_e32 v216, v216
	v_rcp_f32_e32 v217, v217
	v_rcp_f32_e32 v218, v218
	v_rcp_f32_e32 v219, v219
	v_rcp_f32_e32 v220, v220
	v_rcp_f32_e32 v221, v221
	v_rcp_f32_e32 v222, v222
	v_rcp_f32_e32 v223, v223
	v_lshlrev_b32_e32 v242, 16, v150
	v_and_b32_e32 v243, 0xffff0000, v150
	v_lshlrev_b32_e32 v244, 16, v151
	v_and_b32_e32 v245, 0xffff0000, v151
	v_lshlrev_b32_e32 v246, 16, v152
	v_and_b32_e32 v247, 0xffff0000, v152
	v_lshlrev_b32_e32 v248, 16, v153
	v_and_b32_e32 v249, 0xffff0000, v153
	v_pk_mul_f32 v[242:243], v[242:243], s[86:87] op_sel_hi:[1,0]
	v_pk_mul_f32 v[244:245], v[244:245], s[86:87] op_sel_hi:[1,0]
	v_pk_mul_f32 v[246:247], v[246:247], s[86:87] op_sel_hi:[1,0]
	v_pk_mul_f32 v[248:249], v[248:249], s[86:87] op_sel_hi:[1,0]
	v_exp_f32_e32 v242, v242
	v_exp_f32_e32 v243, v243
	v_exp_f32_e32 v244, v244
	v_exp_f32_e32 v245, v245
	v_exp_f32_e32 v246, v246
	v_exp_f32_e32 v247, v247
	v_exp_f32_e32 v248, v248
	v_exp_f32_e32 v249, v249
	v_pk_add_f32 v[242:243], v[242:243], 1.0 op_sel_hi:[1,0]
	v_pk_add_f32 v[244:245], v[244:245], 1.0 op_sel_hi:[1,0]
	v_pk_add_f32 v[246:247], v[246:247], 1.0 op_sel_hi:[1,0]
	v_pk_add_f32 v[248:249], v[248:249], 1.0 op_sel_hi:[1,0]
	v_pk_mul_f32 v[216:217], v[216:217], v[242:243]
	v_pk_mul_f32 v[218:219], v[218:219], v[244:245]
	v_pk_mul_f32 v[220:221], v[220:221], v[246:247]
	v_pk_mul_f32 v[222:223], v[222:223], v[248:249]
	v_pk_mul_f32 v[54:55], v[54:55], v[216:217]
	v_pk_mul_f32 v[56:57], v[56:57], v[218:219]
	v_pk_mul_f32 v[50:51], v[50:51], v[220:221]
	v_pk_mul_f32 v[52:53], v[52:53], v[222:223]
	v_lshlrev_b32_e32 v216, 16, v154
	v_and_b32_e32 v217, 0xffff0000, v154
	v_lshlrev_b32_e32 v218, 16, v155
	v_and_b32_e32 v219, 0xffff0000, v155
	v_lshlrev_b32_e32 v220, 16, v156
	v_and_b32_e32 v221, 0xffff0000, v156
	v_lshlrev_b32_e32 v222, 16, v157
	v_and_b32_e32 v223, 0xffff0000, v157
	v_pk_mul_f32 v[216:217], v[216:217], s[86:87] op_sel_hi:[1,0]
	v_pk_mul_f32 v[218:219], v[218:219], s[86:87] op_sel_hi:[1,0]
	v_pk_mul_f32 v[220:221], v[220:221], s[86:87] op_sel_hi:[1,0]
	v_pk_mul_f32 v[222:223], v[222:223], s[86:87] op_sel_hi:[1,0]
	v_exp_f32_e32 v216, v216
	v_exp_f32_e32 v217, v217
	v_exp_f32_e32 v218, v218
	v_exp_f32_e32 v219, v219
	v_exp_f32_e32 v220, v220
	v_exp_f32_e32 v221, v221
	v_exp_f32_e32 v222, v222
	v_exp_f32_e32 v223, v223
	v_pk_add_f32 v[216:217], v[216:217], 1.0 op_sel_hi:[1,0]
	v_pk_add_f32 v[218:219], v[218:219], 1.0 op_sel_hi:[1,0]
	v_pk_add_f32 v[220:221], v[220:221], 1.0 op_sel_hi:[1,0]
	v_pk_add_f32 v[222:223], v[222:223], 1.0 op_sel_hi:[1,0]
	v_rcp_f32_e32 v216, v216
	v_rcp_f32_e32 v217, v217
	v_rcp_f32_e32 v218, v218
	v_rcp_f32_e32 v219, v219
	v_rcp_f32_e32 v220, v220
	v_rcp_f32_e32 v221, v221
	v_rcp_f32_e32 v222, v222
	v_rcp_f32_e32 v223, v223
	v_lshlrev_b32_e32 v242, 16, v158
	v_and_b32_e32 v243, 0xffff0000, v158
	v_lshlrev_b32_e32 v244, 16, v159
	v_and_b32_e32 v245, 0xffff0000, v159
	v_lshlrev_b32_e32 v246, 16, v160
	v_and_b32_e32 v247, 0xffff0000, v160
	v_lshlrev_b32_e32 v248, 16, v161
	v_and_b32_e32 v249, 0xffff0000, v161
	v_pk_mul_f32 v[242:243], v[242:243], s[86:87] op_sel_hi:[1,0]
	v_pk_mul_f32 v[244:245], v[244:245], s[86:87] op_sel_hi:[1,0]
	v_pk_mul_f32 v[246:247], v[246:247], s[86:87] op_sel_hi:[1,0]
	v_pk_mul_f32 v[248:249], v[248:249], s[86:87] op_sel_hi:[1,0]
	v_exp_f32_e32 v242, v242
	v_exp_f32_e32 v243, v243
	v_exp_f32_e32 v244, v244
	v_exp_f32_e32 v245, v245
	v_exp_f32_e32 v246, v246
	v_exp_f32_e32 v247, v247
	v_exp_f32_e32 v248, v248
	v_exp_f32_e32 v249, v249
	v_pk_add_f32 v[242:243], v[242:243], 1.0 op_sel_hi:[1,0]
	v_pk_add_f32 v[244:245], v[244:245], 1.0 op_sel_hi:[1,0]
	v_pk_add_f32 v[246:247], v[246:247], 1.0 op_sel_hi:[1,0]
	v_pk_add_f32 v[248:249], v[248:249], 1.0 op_sel_hi:[1,0]
	v_pk_mul_f32 v[216:217], v[216:217], v[242:243]
	v_pk_mul_f32 v[218:219], v[218:219], v[244:245]
	v_pk_mul_f32 v[220:221], v[220:221], v[246:247]
	v_pk_mul_f32 v[222:223], v[222:223], v[248:249]
	v_pk_mul_f32 v[22:23], v[22:23], v[216:217]
	v_pk_mul_f32 v[24:25], v[24:25], v[218:219]
	v_pk_mul_f32 v[18:19], v[18:19], v[220:221]
	v_pk_mul_f32 v[20:21], v[20:21], v[222:223]
	s_waitcnt vmcnt(4)
	v_lshlrev_b32_e32 v216, 16, v162
	v_and_b32_e32 v217, 0xffff0000, v162
	v_lshlrev_b32_e32 v218, 16, v163
	v_and_b32_e32 v219, 0xffff0000, v163
	v_lshlrev_b32_e32 v220, 16, v164
	v_and_b32_e32 v221, 0xffff0000, v164
	v_lshlrev_b32_e32 v222, 16, v165
	v_and_b32_e32 v223, 0xffff0000, v165
	v_pk_mul_f32 v[216:217], v[216:217], s[86:87] op_sel_hi:[1,0]
	v_pk_mul_f32 v[218:219], v[218:219], s[86:87] op_sel_hi:[1,0]
	v_pk_mul_f32 v[220:221], v[220:221], s[86:87] op_sel_hi:[1,0]
	v_pk_mul_f32 v[222:223], v[222:223], s[86:87] op_sel_hi:[1,0]
	v_exp_f32_e32 v216, v216
	v_exp_f32_e32 v217, v217
	v_exp_f32_e32 v218, v218
	v_exp_f32_e32 v219, v219
	v_exp_f32_e32 v220, v220
	v_exp_f32_e32 v221, v221
	v_exp_f32_e32 v222, v222
	v_exp_f32_e32 v223, v223
	v_pk_add_f32 v[216:217], v[216:217], 1.0 op_sel_hi:[1,0]
	v_pk_add_f32 v[218:219], v[218:219], 1.0 op_sel_hi:[1,0]
	v_pk_add_f32 v[220:221], v[220:221], 1.0 op_sel_hi:[1,0]
	v_pk_add_f32 v[222:223], v[222:223], 1.0 op_sel_hi:[1,0]
	v_rcp_f32_e32 v216, v216
	v_rcp_f32_e32 v217, v217
	v_rcp_f32_e32 v218, v218
	v_rcp_f32_e32 v219, v219
	v_rcp_f32_e32 v220, v220
	v_rcp_f32_e32 v221, v221
	v_rcp_f32_e32 v222, v222
	v_rcp_f32_e32 v223, v223
	v_lshlrev_b32_e32 v242, 16, v166
	v_and_b32_e32 v243, 0xffff0000, v166
	v_lshlrev_b32_e32 v244, 16, v167
	v_and_b32_e32 v245, 0xffff0000, v167
	v_lshlrev_b32_e32 v246, 16, v168
	v_and_b32_e32 v247, 0xffff0000, v168
	v_lshlrev_b32_e32 v248, 16, v169
	v_and_b32_e32 v249, 0xffff0000, v169
	v_pk_mul_f32 v[242:243], v[242:243], s[86:87] op_sel_hi:[1,0]
	v_pk_mul_f32 v[244:245], v[244:245], s[86:87] op_sel_hi:[1,0]
	v_pk_mul_f32 v[246:247], v[246:247], s[86:87] op_sel_hi:[1,0]
	v_pk_mul_f32 v[248:249], v[248:249], s[86:87] op_sel_hi:[1,0]
	v_exp_f32_e32 v242, v242
	v_exp_f32_e32 v243, v243
	v_exp_f32_e32 v244, v244
	v_exp_f32_e32 v245, v245
	v_exp_f32_e32 v246, v246
	v_exp_f32_e32 v247, v247
	v_exp_f32_e32 v248, v248
	v_exp_f32_e32 v249, v249
	v_pk_add_f32 v[242:243], v[242:243], 1.0 op_sel_hi:[1,0]
	v_pk_add_f32 v[244:245], v[244:245], 1.0 op_sel_hi:[1,0]
	v_pk_add_f32 v[246:247], v[246:247], 1.0 op_sel_hi:[1,0]
	v_pk_add_f32 v[248:249], v[248:249], 1.0 op_sel_hi:[1,0]
	v_pk_mul_f32 v[216:217], v[216:217], v[242:243]
	v_pk_mul_f32 v[218:219], v[218:219], v[244:245]
	v_pk_mul_f32 v[220:221], v[220:221], v[246:247]
	v_pk_mul_f32 v[222:223], v[222:223], v[248:249]
	v_pk_mul_f32 v[46:47], v[46:47], v[216:217]
	v_pk_mul_f32 v[48:49], v[48:49], v[218:219]
	v_pk_mul_f32 v[42:43], v[42:43], v[220:221]
	v_pk_mul_f32 v[44:45], v[44:45], v[222:223]
	v_lshlrev_b32_e32 v216, 16, v170
	v_and_b32_e32 v217, 0xffff0000, v170
	v_lshlrev_b32_e32 v218, 16, v171
	v_and_b32_e32 v219, 0xffff0000, v171
	v_lshlrev_b32_e32 v220, 16, v172
	v_and_b32_e32 v221, 0xffff0000, v172
	v_lshlrev_b32_e32 v222, 16, v173
	v_and_b32_e32 v223, 0xffff0000, v173
	v_pk_mul_f32 v[216:217], v[216:217], s[86:87] op_sel_hi:[1,0]
	v_pk_mul_f32 v[218:219], v[218:219], s[86:87] op_sel_hi:[1,0]
	v_pk_mul_f32 v[220:221], v[220:221], s[86:87] op_sel_hi:[1,0]
	v_pk_mul_f32 v[222:223], v[222:223], s[86:87] op_sel_hi:[1,0]
	v_exp_f32_e32 v216, v216
	v_exp_f32_e32 v217, v217
	v_exp_f32_e32 v218, v218
	v_exp_f32_e32 v219, v219
	v_exp_f32_e32 v220, v220
	v_exp_f32_e32 v221, v221
	v_exp_f32_e32 v222, v222
	v_exp_f32_e32 v223, v223
	v_pk_add_f32 v[216:217], v[216:217], 1.0 op_sel_hi:[1,0]
	v_pk_add_f32 v[218:219], v[218:219], 1.0 op_sel_hi:[1,0]
	v_pk_add_f32 v[220:221], v[220:221], 1.0 op_sel_hi:[1,0]
	v_pk_add_f32 v[222:223], v[222:223], 1.0 op_sel_hi:[1,0]
	v_rcp_f32_e32 v216, v216
	v_rcp_f32_e32 v217, v217
	v_rcp_f32_e32 v218, v218
	v_rcp_f32_e32 v219, v219
	v_rcp_f32_e32 v220, v220
	v_rcp_f32_e32 v221, v221
	v_rcp_f32_e32 v222, v222
	v_rcp_f32_e32 v223, v223
	v_lshlrev_b32_e32 v242, 16, v174
	v_and_b32_e32 v243, 0xffff0000, v174
	v_lshlrev_b32_e32 v244, 16, v175
	v_and_b32_e32 v245, 0xffff0000, v175
	v_lshlrev_b32_e32 v246, 16, v176
	v_and_b32_e32 v247, 0xffff0000, v176
	v_lshlrev_b32_e32 v248, 16, v177
	v_and_b32_e32 v249, 0xffff0000, v177
	v_pk_mul_f32 v[242:243], v[242:243], s[86:87] op_sel_hi:[1,0]
	v_pk_mul_f32 v[244:245], v[244:245], s[86:87] op_sel_hi:[1,0]
	v_pk_mul_f32 v[246:247], v[246:247], s[86:87] op_sel_hi:[1,0]
	v_pk_mul_f32 v[248:249], v[248:249], s[86:87] op_sel_hi:[1,0]
	v_exp_f32_e32 v242, v242
	v_exp_f32_e32 v243, v243
	v_exp_f32_e32 v244, v244
	v_exp_f32_e32 v245, v245
	v_exp_f32_e32 v246, v246
	v_exp_f32_e32 v247, v247
	v_exp_f32_e32 v248, v248
	v_exp_f32_e32 v249, v249
	v_pk_add_f32 v[242:243], v[242:243], 1.0 op_sel_hi:[1,0]
	v_pk_add_f32 v[244:245], v[244:245], 1.0 op_sel_hi:[1,0]
	v_pk_add_f32 v[246:247], v[246:247], 1.0 op_sel_hi:[1,0]
	v_pk_add_f32 v[248:249], v[248:249], 1.0 op_sel_hi:[1,0]
	v_pk_mul_f32 v[216:217], v[216:217], v[242:243]
	v_pk_mul_f32 v[218:219], v[218:219], v[244:245]
	v_pk_mul_f32 v[220:221], v[220:221], v[246:247]
	v_pk_mul_f32 v[222:223], v[222:223], v[248:249]
	v_pk_mul_f32 v[14:15], v[14:15], v[216:217]
	v_pk_mul_f32 v[16:17], v[16:17], v[218:219]
	v_pk_mul_f32 v[10:11], v[10:11], v[220:221]
	v_pk_mul_f32 v[12:13], v[12:13], v[222:223]
	s_waitcnt vmcnt(0)
	v_lshlrev_b32_e32 v216, 16, v178
	v_and_b32_e32 v217, 0xffff0000, v178
	v_lshlrev_b32_e32 v218, 16, v179
	v_and_b32_e32 v219, 0xffff0000, v179
	v_lshlrev_b32_e32 v220, 16, v180
	v_and_b32_e32 v221, 0xffff0000, v180
	v_lshlrev_b32_e32 v222, 16, v181
	v_and_b32_e32 v223, 0xffff0000, v181
	v_pk_mul_f32 v[216:217], v[216:217], s[86:87] op_sel_hi:[1,0]
	v_pk_mul_f32 v[218:219], v[218:219], s[86:87] op_sel_hi:[1,0]
	v_pk_mul_f32 v[220:221], v[220:221], s[86:87] op_sel_hi:[1,0]
	v_pk_mul_f32 v[222:223], v[222:223], s[86:87] op_sel_hi:[1,0]
	v_exp_f32_e32 v216, v216
	v_exp_f32_e32 v217, v217
	v_exp_f32_e32 v218, v218
	v_exp_f32_e32 v219, v219
	v_exp_f32_e32 v220, v220
	v_exp_f32_e32 v221, v221
	v_exp_f32_e32 v222, v222
	v_exp_f32_e32 v223, v223
	v_pk_add_f32 v[216:217], v[216:217], 1.0 op_sel_hi:[1,0]
	v_pk_add_f32 v[218:219], v[218:219], 1.0 op_sel_hi:[1,0]
	v_pk_add_f32 v[220:221], v[220:221], 1.0 op_sel_hi:[1,0]
	v_pk_add_f32 v[222:223], v[222:223], 1.0 op_sel_hi:[1,0]
	v_rcp_f32_e32 v216, v216
	v_rcp_f32_e32 v217, v217
	v_rcp_f32_e32 v218, v218
	v_rcp_f32_e32 v219, v219
	v_rcp_f32_e32 v220, v220
	v_rcp_f32_e32 v221, v221
	v_rcp_f32_e32 v222, v222
	v_rcp_f32_e32 v223, v223
	v_lshlrev_b32_e32 v242, 16, v182
	v_and_b32_e32 v243, 0xffff0000, v182
	v_lshlrev_b32_e32 v244, 16, v183
	v_and_b32_e32 v245, 0xffff0000, v183
	v_lshlrev_b32_e32 v246, 16, v184
	v_and_b32_e32 v247, 0xffff0000, v184
	v_lshlrev_b32_e32 v248, 16, v185
	v_and_b32_e32 v249, 0xffff0000, v185
	v_pk_mul_f32 v[242:243], v[242:243], s[86:87] op_sel_hi:[1,0]
	v_pk_mul_f32 v[244:245], v[244:245], s[86:87] op_sel_hi:[1,0]
	v_pk_mul_f32 v[246:247], v[246:247], s[86:87] op_sel_hi:[1,0]
	v_pk_mul_f32 v[248:249], v[248:249], s[86:87] op_sel_hi:[1,0]
	v_exp_f32_e32 v242, v242
	v_exp_f32_e32 v243, v243
	v_exp_f32_e32 v244, v244
	v_exp_f32_e32 v245, v245
	v_exp_f32_e32 v246, v246
	v_exp_f32_e32 v247, v247
	v_exp_f32_e32 v248, v248
	v_exp_f32_e32 v249, v249
	v_pk_add_f32 v[242:243], v[242:243], 1.0 op_sel_hi:[1,0]
	v_pk_add_f32 v[244:245], v[244:245], 1.0 op_sel_hi:[1,0]
	v_pk_add_f32 v[246:247], v[246:247], 1.0 op_sel_hi:[1,0]
	v_pk_add_f32 v[248:249], v[248:249], 1.0 op_sel_hi:[1,0]
	v_pk_mul_f32 v[216:217], v[216:217], v[242:243]
	v_pk_mul_f32 v[218:219], v[218:219], v[244:245]
	v_pk_mul_f32 v[220:221], v[220:221], v[246:247]
	v_pk_mul_f32 v[222:223], v[222:223], v[248:249]
	v_pk_mul_f32 v[38:39], v[38:39], v[216:217]
	v_pk_mul_f32 v[40:41], v[40:41], v[218:219]
	v_pk_mul_f32 v[34:35], v[34:35], v[220:221]
	v_pk_mul_f32 v[36:37], v[36:37], v[222:223]
	v_lshlrev_b32_e32 v216, 16, v186
	v_and_b32_e32 v217, 0xffff0000, v186
	v_lshlrev_b32_e32 v218, 16, v187
	v_and_b32_e32 v219, 0xffff0000, v187
	v_lshlrev_b32_e32 v220, 16, v188
	v_and_b32_e32 v221, 0xffff0000, v188
	v_lshlrev_b32_e32 v222, 16, v189
	v_and_b32_e32 v223, 0xffff0000, v189
	v_pk_mul_f32 v[216:217], v[216:217], s[86:87] op_sel_hi:[1,0]
	v_pk_mul_f32 v[218:219], v[218:219], s[86:87] op_sel_hi:[1,0]
	v_pk_mul_f32 v[220:221], v[220:221], s[86:87] op_sel_hi:[1,0]
	v_pk_mul_f32 v[222:223], v[222:223], s[86:87] op_sel_hi:[1,0]
	v_exp_f32_e32 v216, v216
	v_exp_f32_e32 v217, v217
	v_exp_f32_e32 v218, v218
	v_exp_f32_e32 v219, v219
	v_exp_f32_e32 v220, v220
	v_exp_f32_e32 v221, v221
	v_exp_f32_e32 v222, v222
	v_exp_f32_e32 v223, v223
	v_pk_add_f32 v[216:217], v[216:217], 1.0 op_sel_hi:[1,0]
	v_pk_add_f32 v[218:219], v[218:219], 1.0 op_sel_hi:[1,0]
	v_pk_add_f32 v[220:221], v[220:221], 1.0 op_sel_hi:[1,0]
	v_pk_add_f32 v[222:223], v[222:223], 1.0 op_sel_hi:[1,0]
	v_rcp_f32_e32 v216, v216
	v_rcp_f32_e32 v217, v217
	v_rcp_f32_e32 v218, v218
	v_rcp_f32_e32 v219, v219
	v_rcp_f32_e32 v220, v220
	v_rcp_f32_e32 v221, v221
	v_rcp_f32_e32 v222, v222
	v_rcp_f32_e32 v223, v223
	v_lshlrev_b32_e32 v242, 16, v190
	v_and_b32_e32 v243, 0xffff0000, v190
	v_lshlrev_b32_e32 v244, 16, v191
	v_and_b32_e32 v245, 0xffff0000, v191
	v_lshlrev_b32_e32 v246, 16, v192
	v_and_b32_e32 v247, 0xffff0000, v192
	v_lshlrev_b32_e32 v248, 16, v193
	v_and_b32_e32 v249, 0xffff0000, v193
	v_pk_mul_f32 v[242:243], v[242:243], s[86:87] op_sel_hi:[1,0]
	v_pk_mul_f32 v[244:245], v[244:245], s[86:87] op_sel_hi:[1,0]
	v_pk_mul_f32 v[246:247], v[246:247], s[86:87] op_sel_hi:[1,0]
	v_pk_mul_f32 v[248:249], v[248:249], s[86:87] op_sel_hi:[1,0]
	v_exp_f32_e32 v242, v242
	v_exp_f32_e32 v243, v243
	v_exp_f32_e32 v244, v244
	v_exp_f32_e32 v245, v245
	v_exp_f32_e32 v246, v246
	v_exp_f32_e32 v247, v247
	v_exp_f32_e32 v248, v248
	v_exp_f32_e32 v249, v249
	v_pk_add_f32 v[242:243], v[242:243], 1.0 op_sel_hi:[1,0]
	v_pk_add_f32 v[244:245], v[244:245], 1.0 op_sel_hi:[1,0]
	v_pk_add_f32 v[246:247], v[246:247], 1.0 op_sel_hi:[1,0]
	v_pk_add_f32 v[248:249], v[248:249], 1.0 op_sel_hi:[1,0]
	v_pk_mul_f32 v[216:217], v[216:217], v[242:243]
	v_pk_mul_f32 v[218:219], v[218:219], v[244:245]
	v_pk_mul_f32 v[220:221], v[220:221], v[246:247]
	v_pk_mul_f32 v[222:223], v[222:223], v[248:249]
	v_pk_mul_f32 v[6:7], v[6:7], v[216:217]
	v_pk_mul_f32 v[8:9], v[8:9], v[218:219]
	v_pk_mul_f32 v[2:3], v[2:3], v[220:221]
	v_pk_mul_f32 v[4:5], v[4:5], v[222:223]
	s_branch .Lem_done

.LBB0_504:
	v_or_b32_e32 v130, 0x10000, v163
	v_add_u32_e32 v134, 0x10400, v163
	v_add_u32_e32 v150, 0x10800, v163
	v_add_u32_e32 v154, 0x10c00, v163
	ds_read_b128 v[130:133], v130
	ds_read_b128 v[134:137], v134
	ds_read_b128 v[150:153], v150
	ds_read_b128 v[154:157], v154
	s_add_u32 s10, s52, 0xfff80080
	s_addc_u32 s11, s53, -1
	s_cmp_eq_u32 s29, 28
	s_cselect_b32 s11, s9, s11
	s_cselect_b32 s10, s8, s10
	s_cselect_b32 s55, s35, s7
	s_cselect_b32 s54, s34, s5
	v_lshl_add_u64 v[206:207], s[52:53], 0, v[146:147]
	s_add_i32 m0, s42, 0xc000
	ds_read_b128 v[158:161], v162
	ds_read_b128 v[166:169], v162 offset:1024
	ds_read_b128 v[170:173], v162 offset:2048
	ds_read_b128 v[174:177], v162 offset:3072
	ds_read_b128 v[178:181], v162 offset:4096
	ds_read_b128 v[182:185], v162 offset:5120
	ds_read_b128 v[186:189], v162 offset:6144
	ds_read_b128 v[190:193], v162 offset:7168
	global_load_lds_dwordx4 v[206:207], off
	v_lshl_add_u64 v[206:207], s[52:53], 0, v[148:149]
	s_add_i32 m0, s42, 0xe000
	s_nop 0
	global_load_lds_dwordx4 v[206:207], off
	s_waitcnt lgkmcnt(8)
	s_setprio 1
	s_barrier
	s_waitcnt lgkmcnt(0)
	v_mfma_f32_16x16x32_bf16 v[126:129], v[130:133], v[158:161], v[126:129]
	v_mfma_f32_16x16x32_bf16 v[122:125], v[150:153], v[158:161], v[122:125]
	v_mfma_f32_16x16x32_bf16 v[118:121], v[130:133], v[170:173], v[118:121]
	v_mfma_f32_16x16x32_bf16 v[114:117], v[150:153], v[170:173], v[114:117]
	v_mfma_f32_16x16x32_bf16 v[110:113], v[130:133], v[178:181], v[110:113]
	v_mfma_f32_16x16x32_bf16 v[106:109], v[150:153], v[178:181], v[106:109]
	v_mfma_f32_16x16x32_bf16 v[102:105], v[130:133], v[186:189], v[102:105]
	v_mfma_f32_16x16x32_bf16 v[98:101], v[150:153], v[186:189], v[98:101]
	v_mfma_f32_16x16x32_bf16 v[126:129], v[134:137], v[166:169], v[126:129]
	v_mfma_f32_16x16x32_bf16 v[122:125], v[154:157], v[166:169], v[122:125]
	v_mfma_f32_16x16x32_bf16 v[118:121], v[134:137], v[174:177], v[118:121]
	v_mfma_f32_16x16x32_bf16 v[114:117], v[154:157], v[174:177], v[114:117]
	v_mfma_f32_16x16x32_bf16 v[110:113], v[134:137], v[182:185], v[110:113]
	v_mfma_f32_16x16x32_bf16 v[106:109], v[154:157], v[182:185], v[106:109]
	v_mfma_f32_16x16x32_bf16 v[102:105], v[134:137], v[190:193], v[102:105]
	v_mfma_f32_16x16x32_bf16 v[98:101], v[154:157], v[190:193], v[98:101]
	s_barrier
	s_setprio 0
	v_or_b32_e32 v165, 0x14000, v163
	s_mov_b32 m0, s41
	v_add_u32_e32 v197, 0x14400, v163
	ds_read_b128 v[206:209], v165
	ds_read_b128 v[210:213], v197
	v_add_u32_e32 v165, 0x14800, v163
	v_lshl_add_u64 v[222:223], s[54:55], 0, v[194:195]
	v_add_u32_e32 v197, 0x14c00, v163
	ds_read_b128 v[214:217], v165
	ds_read_b128 v[218:221], v197
	global_load_lds_dwordx4 v[222:223], off
	v_lshl_add_u64 v[224:225], s[54:55], 0, v[138:139]
	s_mov_b32 m0, s57
	s_nop 0
	global_load_lds_dwordx4 v[224:225], off
	s_setprio 1
	s_barrier
	s_waitcnt lgkmcnt(0)
	v_mfma_f32_16x16x32_bf16 v[62:65], v[206:209], v[158:161], v[62:65]
	v_mfma_f32_16x16x32_bf16 v[58:61], v[214:217], v[158:161], v[58:61]
	v_mfma_f32_16x16x32_bf16 v[54:57], v[206:209], v[170:173], v[54:57]
	v_mfma_f32_16x16x32_bf16 v[46:49], v[214:217], v[170:173], v[46:49]
	v_mfma_f32_16x16x32_bf16 v[50:53], v[206:209], v[178:181], v[50:53]
	v_mfma_f32_16x16x32_bf16 v[42:45], v[214:217], v[178:181], v[42:45]
	v_mfma_f32_16x16x32_bf16 v[38:41], v[206:209], v[186:189], v[38:41]
	v_mfma_f32_16x16x32_bf16 v[34:37], v[214:217], v[186:189], v[34:37]
	v_mfma_f32_16x16x32_bf16 v[62:65], v[210:213], v[166:169], v[62:65]
	v_mfma_f32_16x16x32_bf16 v[58:61], v[218:221], v[166:169], v[58:61]
	v_mfma_f32_16x16x32_bf16 v[54:57], v[210:213], v[174:177], v[54:57]
	v_mfma_f32_16x16x32_bf16 v[46:49], v[218:221], v[174:177], v[46:49]
	v_mfma_f32_16x16x32_bf16 v[50:53], v[210:213], v[182:185], v[50:53]
	v_mfma_f32_16x16x32_bf16 v[42:45], v[218:221], v[182:185], v[42:45]
	s_mov_b32 m0, s42
	v_mfma_f32_16x16x32_bf16 v[38:41], v[210:213], v[190:193], v[38:41]
	v_lshl_add_u64 v[226:227], s[10:11], 0, v[142:143]
	v_mfma_f32_16x16x32_bf16 v[34:37], v[218:221], v[190:193], v[34:37]
	s_barrier
	s_setprio 0
	ds_read_b128 v[158:161], v162 offset:16384
	ds_read_b128 v[166:169], v162 offset:17408
	ds_read_b128 v[170:173], v162 offset:18432
	ds_read_b128 v[174:177], v162 offset:19456
	ds_read_b128 v[178:181], v162 offset:20480
	ds_read_b128 v[182:185], v162 offset:21504
	ds_read_b128 v[186:189], v162 offset:22528
	ds_read_b128 v[190:193], v162 offset:23552
	global_load_lds_dwordx4 v[226:227], off
	v_lshl_add_u64 v[228:229], s[10:11], 0, v[140:141]
	s_mov_b32 m0, s58
	s_nop 0
	global_load_lds_dwordx4 v[228:229], off
	s_setprio 1
	s_barrier
	s_waitcnt lgkmcnt(0)
	v_mfma_f32_16x16x32_bf16 v[94:97], v[130:133], v[158:161], v[94:97]
	v_mfma_f32_16x16x32_bf16 v[90:93], v[150:153], v[158:161], v[90:93]
	v_mfma_f32_16x16x32_bf16 v[86:89], v[130:133], v[170:173], v[86:89]
	v_mfma_f32_16x16x32_bf16 v[82:85], v[150:153], v[170:173], v[82:85]
	v_mfma_f32_16x16x32_bf16 v[78:81], v[130:133], v[178:181], v[78:81]
	v_mfma_f32_16x16x32_bf16 v[74:77], v[150:153], v[178:181], v[74:77]
	v_mfma_f32_16x16x32_bf16 v[70:73], v[130:133], v[186:189], v[70:73]
	v_mfma_f32_16x16x32_bf16 v[66:69], v[150:153], v[186:189], v[66:69]
	v_mfma_f32_16x16x32_bf16 v[94:97], v[134:137], v[166:169], v[94:97]
	v_mfma_f32_16x16x32_bf16 v[90:93], v[154:157], v[166:169], v[90:93]
	v_mfma_f32_16x16x32_bf16 v[86:89], v[134:137], v[174:177], v[86:89]
	v_mfma_f32_16x16x32_bf16 v[82:85], v[154:157], v[174:177], v[82:85]
	v_mfma_f32_16x16x32_bf16 v[78:81], v[134:137], v[182:185], v[78:81]
	v_mfma_f32_16x16x32_bf16 v[74:77], v[154:157], v[182:185], v[74:77]
	v_mfma_f32_16x16x32_bf16 v[70:73], v[134:137], v[190:193], v[70:73]
	v_mfma_f32_16x16x32_bf16 v[66:69], v[154:157], v[190:193], v[66:69]
	s_barrier
	s_setprio 0
	s_add_u32 s86, s54, 0x80000
	s_addc_u32 s87, s55, 0
	s_mov_b32 m0, s59
	v_lshl_add_u64 v[130:131], s[86:87], 0, v[194:195]
	global_load_lds_dwordx4 v[130:131], off
	v_lshl_add_u64 v[130:131], s[86:87], 0, v[138:139]
	s_mov_b32 m0, s60
	s_nop 0
	global_load_lds_dwordx4 v[130:131], off
	s_waitcnt vmcnt(6)
	s_setprio 1
	s_barrier
	v_mfma_f32_16x16x32_bf16 v[30:33], v[206:209], v[158:161], v[30:33]
	v_mfma_f32_16x16x32_bf16 v[18:21], v[214:217], v[158:161], v[18:21]
	v_mfma_f32_16x16x32_bf16 v[26:29], v[206:209], v[170:173], v[26:29]
	v_mfma_f32_16x16x32_bf16 v[14:17], v[214:217], v[170:173], v[14:17]
	v_mfma_f32_16x16x32_bf16 v[22:25], v[206:209], v[178:181], v[22:25]
	v_mfma_f32_16x16x32_bf16 v[6:9], v[214:217], v[178:181], v[6:9]
	v_mfma_f32_16x16x32_bf16 v[10:13], v[206:209], v[186:189], v[10:13]
	v_mfma_f32_16x16x32_bf16 v[2:5], v[214:217], v[186:189], v[2:5]
	v_mfma_f32_16x16x32_bf16 v[30:33], v[210:213], v[166:169], v[30:33]
	v_mfma_f32_16x16x32_bf16 v[18:21], v[218:221], v[166:169], v[18:21]
	v_mfma_f32_16x16x32_bf16 v[26:29], v[210:213], v[174:177], v[26:29]
	v_mfma_f32_16x16x32_bf16 v[14:17], v[218:221], v[174:177], v[14:17]
	v_or_b32_e32 v130, 0x18000, v163
	v_mfma_f32_16x16x32_bf16 v[22:25], v[210:213], v[182:185], v[22:25]
	v_add_u32_e32 v134, 0x18400, v163
	v_mfma_f32_16x16x32_bf16 v[6:9], v[218:221], v[182:185], v[6:9]
	v_add_u32_e32 v150, 0x18800, v163
	v_mfma_f32_16x16x32_bf16 v[10:13], v[210:213], v[190:193], v[10:13]
	v_add_u32_e32 v154, 0x18c00, v163
	v_mfma_f32_16x16x32_bf16 v[2:5], v[218:221], v[190:193], v[2:5]
	s_barrier
	s_setprio 0
	ds_read_b128 v[130:133], v130
	ds_read_b128 v[134:137], v134
	ds_read_b128 v[150:153], v150
	ds_read_b128 v[154:157], v154
	s_add_u32 s10, s10, 0x80000
	s_addc_u32 s11, s11, 0
	s_mov_b32 m0, s61
	v_lshl_add_u64 v[206:207], s[10:11], 0, v[142:143]
	ds_read_b128 v[158:161], v162 offset:32768
	ds_read_b128 v[166:169], v162 offset:33792
	ds_read_b128 v[170:173], v162 offset:34816
	ds_read_b128 v[174:177], v162 offset:35840
	ds_read_b128 v[178:181], v162 offset:36864
	ds_read_b128 v[182:185], v162 offset:37888
	ds_read_b128 v[186:189], v162 offset:38912
	ds_read_b128 v[190:193], v162 offset:39936
	global_load_lds_dwordx4 v[206:207], off
	v_lshl_add_u64 v[206:207], s[10:11], 0, v[140:141]
	s_mov_b32 m0, s62
	s_nop 0
	global_load_lds_dwordx4 v[206:207], off
	s_waitcnt lgkmcnt(8)
	s_setprio 1
	s_barrier
	s_waitcnt lgkmcnt(0)
	v_mfma_f32_16x16x32_bf16 v[126:129], v[130:133], v[158:161], v[126:129]
	v_mfma_f32_16x16x32_bf16 v[122:125], v[150:153], v[158:161], v[122:125]
	v_mfma_f32_16x16x32_bf16 v[118:121], v[130:133], v[170:173], v[118:121]
	v_mfma_f32_16x16x32_bf16 v[114:117], v[150:153], v[170:173], v[114:117]
	v_mfma_f32_16x16x32_bf16 v[110:113], v[130:133], v[178:181], v[110:113]
	v_mfma_f32_16x16x32_bf16 v[106:109], v[150:153], v[178:181], v[106:109]
	v_mfma_f32_16x16x32_bf16 v[102:105], v[130:133], v[186:189], v[102:105]
	v_mfma_f32_16x16x32_bf16 v[98:101], v[150:153], v[186:189], v[98:101]
	v_mfma_f32_16x16x32_bf16 v[126:129], v[134:137], v[166:169], v[126:129]
	v_mfma_f32_16x16x32_bf16 v[122:125], v[154:157], v[166:169], v[122:125]
	v_mfma_f32_16x16x32_bf16 v[118:121], v[134:137], v[174:177], v[118:121]
	v_mfma_f32_16x16x32_bf16 v[114:117], v[154:157], v[174:177], v[114:117]
	v_mfma_f32_16x16x32_bf16 v[110:113], v[134:137], v[182:185], v[110:113]
	v_mfma_f32_16x16x32_bf16 v[106:109], v[154:157], v[182:185], v[106:109]
	v_mfma_f32_16x16x32_bf16 v[102:105], v[134:137], v[190:193], v[102:105]
	v_mfma_f32_16x16x32_bf16 v[98:101], v[154:157], v[190:193], v[98:101]
	s_barrier
	s_setprio 0
	v_or_b32_e32 v165, 0x1c000, v163
	s_mov_b32 m0, s70
	v_add_u32_e32 v197, 0x1c400, v163
	ds_read_b128 v[206:209], v165
	ds_read_b128 v[210:213], v197
	v_add_u32_e32 v165, 0x1c800, v163
	v_lshl_add_u64 v[222:223], v[222:223], 0, s[76:77]
	v_add_u32_e32 v197, 0x1cc00, v163
	ds_read_b128 v[214:217], v165
	ds_read_b128 v[218:221], v197
	global_load_lds_dwordx4 v[222:223], off
	v_lshl_add_u64 v[222:223], v[224:225], 0, s[76:77]
	s_mov_b32 m0, s71
	s_nop 0
	global_load_lds_dwordx4 v[222:223], off
	s_setprio 1
	s_barrier
	s_waitcnt lgkmcnt(0)
	v_mfma_f32_16x16x32_bf16 v[62:65], v[206:209], v[158:161], v[62:65]
	v_mfma_f32_16x16x32_bf16 v[58:61], v[214:217], v[158:161], v[58:61]
	v_mfma_f32_16x16x32_bf16 v[54:57], v[206:209], v[170:173], v[54:57]
	v_mfma_f32_16x16x32_bf16 v[46:49], v[214:217], v[170:173], v[46:49]
	v_mfma_f32_16x16x32_bf16 v[50:53], v[206:209], v[178:181], v[50:53]
	v_mfma_f32_16x16x32_bf16 v[42:45], v[214:217], v[178:181], v[42:45]
	v_mfma_f32_16x16x32_bf16 v[38:41], v[206:209], v[186:189], v[38:41]
	v_mfma_f32_16x16x32_bf16 v[34:37], v[214:217], v[186:189], v[34:37]
	v_mfma_f32_16x16x32_bf16 v[62:65], v[210:213], v[166:169], v[62:65]
	v_mfma_f32_16x16x32_bf16 v[58:61], v[218:221], v[166:169], v[58:61]
	v_mfma_f32_16x16x32_bf16 v[54:57], v[210:213], v[174:177], v[54:57]
	v_mfma_f32_16x16x32_bf16 v[46:49], v[218:221], v[174:177], v[46:49]
	v_mfma_f32_16x16x32_bf16 v[50:53], v[210:213], v[182:185], v[50:53]
	v_mfma_f32_16x16x32_bf16 v[42:45], v[218:221], v[182:185], v[42:45]
	s_mov_b32 m0, s78
	v_mfma_f32_16x16x32_bf16 v[38:41], v[210:213], v[190:193], v[38:41]
	v_lshl_add_u64 v[222:223], v[226:227], 0, s[76:77]
	v_mfma_f32_16x16x32_bf16 v[34:37], v[218:221], v[190:193], v[34:37]
	s_barrier
	s_setprio 0
	ds_read_b128 v[158:161], v162 offset:49152
	ds_read_b128 v[166:169], v162 offset:50176
	ds_read_b128 v[170:173], v162 offset:51200
	ds_read_b128 v[174:177], v162 offset:52224
	ds_read_b128 v[178:181], v162 offset:53248
	ds_read_b128 v[182:185], v162 offset:54272
	ds_read_b128 v[186:189], v162 offset:55296
	ds_read_b128 v[190:193], v162 offset:56320
	global_load_lds_dwordx4 v[222:223], off
	v_lshl_add_u64 v[222:223], v[228:229], 0, s[76:77]
	s_mov_b32 m0, s79
	s_nop 0
	global_load_lds_dwordx4 v[222:223], off
	s_setprio 1
	s_barrier
	s_waitcnt lgkmcnt(0)
	v_mfma_f32_16x16x32_bf16 v[94:97], v[130:133], v[158:161], v[94:97]
	v_mfma_f32_16x16x32_bf16 v[90:93], v[150:153], v[158:161], v[90:93]
	v_mfma_f32_16x16x32_bf16 v[86:89], v[130:133], v[170:173], v[86:89]
	v_mfma_f32_16x16x32_bf16 v[82:85], v[150:153], v[170:173], v[82:85]
	v_mfma_f32_16x16x32_bf16 v[78:81], v[130:133], v[178:181], v[78:81]
	v_mfma_f32_16x16x32_bf16 v[74:77], v[150:153], v[178:181], v[74:77]
	v_mfma_f32_16x16x32_bf16 v[70:73], v[130:133], v[186:189], v[70:73]
	v_mfma_f32_16x16x32_bf16 v[66:69], v[150:153], v[186:189], v[66:69]
	v_mfma_f32_16x16x32_bf16 v[94:97], v[134:137], v[166:169], v[94:97]
	v_mfma_f32_16x16x32_bf16 v[90:93], v[154:157], v[166:169], v[90:93]
	v_mfma_f32_16x16x32_bf16 v[86:89], v[134:137], v[174:177], v[86:89]
	v_mfma_f32_16x16x32_bf16 v[82:85], v[154:157], v[174:177], v[82:85]
	v_mfma_f32_16x16x32_bf16 v[78:81], v[134:137], v[182:185], v[78:81]
	v_mfma_f32_16x16x32_bf16 v[74:77], v[154:157], v[182:185], v[74:77]
	v_mfma_f32_16x16x32_bf16 v[70:73], v[134:137], v[190:193], v[70:73]
	v_mfma_f32_16x16x32_bf16 v[66:69], v[154:157], v[190:193], v[66:69]
	s_barrier
	s_setprio 0
	s_add_u32 s10, s54, 0x80080
	s_addc_u32 s11, s55, 0
	s_mov_b32 m0, s80
	v_lshl_add_u64 v[130:131], s[10:11], 0, v[194:195]
	global_load_lds_dwordx4 v[130:131], off
	v_lshl_add_u64 v[130:131], s[10:11], 0, v[138:139]
	s_mov_b32 m0, s81
	s_nop 0
	global_load_lds_dwordx4 v[130:131], off
	s_waitcnt vmcnt(6)
	s_setprio 1
	s_barrier
	v_mfma_f32_16x16x32_bf16 v[30:33], v[206:209], v[158:161], v[30:33]
	v_mfma_f32_16x16x32_bf16 v[18:21], v[214:217], v[158:161], v[18:21]
	v_mfma_f32_16x16x32_bf16 v[26:29], v[206:209], v[170:173], v[26:29]
	v_mfma_f32_16x16x32_bf16 v[14:17], v[214:217], v[170:173], v[14:17]
	v_mfma_f32_16x16x32_bf16 v[22:25], v[206:209], v[178:181], v[22:25]
	v_mfma_f32_16x16x32_bf16 v[6:9], v[214:217], v[178:181], v[6:9]
	v_mfma_f32_16x16x32_bf16 v[10:13], v[206:209], v[186:189], v[10:13]
	v_mfma_f32_16x16x32_bf16 v[2:5], v[214:217], v[186:189], v[2:5]
	v_mfma_f32_16x16x32_bf16 v[30:33], v[210:213], v[166:169], v[30:33]
	v_mfma_f32_16x16x32_bf16 v[18:21], v[218:221], v[166:169], v[18:21]
	v_mfma_f32_16x16x32_bf16 v[26:29], v[210:213], v[174:177], v[26:29]
	v_mfma_f32_16x16x32_bf16 v[14:17], v[218:221], v[174:177], v[14:17]
	v_mfma_f32_16x16x32_bf16 v[22:25], v[210:213], v[182:185], v[22:25]
	v_mfma_f32_16x16x32_bf16 v[6:9], v[218:221], v[182:185], v[6:9]
	v_mfma_f32_16x16x32_bf16 v[10:13], v[210:213], v[190:193], v[10:13]
	v_mfma_f32_16x16x32_bf16 v[2:5], v[218:221], v[190:193], v[2:5]
	s_setprio 0
	s_add_i32 s29, s29, 2
	s_add_u32 s52, s52, 0x100
	s_addc_u32 s53, s53, 0
	s_add_u32 s5, s5, 0x100
	s_addc_u32 s7, s7, 0
	s_cmp_gt_u32 s29, 29
	s_barrier
	s_cbranch_scc0 .LBB0_504
	v_readlane_b32 s10, v250, 21
	s_cmp_gt_i32 s40, 63
	v_readlane_b32 s11, v250, 22
	s_mov_b64 s[20:21], s[48:49]
	s_cselect_b32 s11, s21, s11
	s_cselect_b32 s10, s20, s10
	v_readlane_b32 s20, v252, 0
	v_readlane_b32 s26, v252, 6
	v_readlane_b32 s27, v252, 7
	s_cselect_b32 s53, s3, s27
	s_cselect_b32 s52, s2, s26
	s_sub_i32 s5, s40, 64
	s_cmp_gt_i32 s40, 63
	s_cselect_b32 s54, s5, s40
	s_lshr_b32 s5, s40, 3
	s_cmp_gt_i32 s40, 63
	s_mulk_i32 s5, 0x1800
	v_lshl_or_b32 v130, s28, 8, v164
	s_cselect_b32 s28, 0xc000, s5
	s_ashr_i32 s29, s28, 31
	s_lshl_b64 s[28:29], s[28:29], 2
	s_add_u32 s28, s63, s28
	v_ashrrev_i32_e32 v131, 31, v130
	s_addc_u32 s29, s67, s29
	v_lshlrev_b64 v[130:131], 2, v[130:131]
	v_lshl_add_u64 v[132:133], s[28:29], 0, v[130:131]
	s_mov_b64 s[28:29], 0x6484000
	s_ashr_i32 s55, s54, 31
	v_lshl_add_u64 v[154:155], v[132:133], 0, s[28:29]
	s_lshl_b64 s[28:29], s[54:55], 19
	v_lshl_add_u64 v[134:135], s[28:29], 0, v[144:145]
	v_lshlrev_b64 v[134:135], 2, v[134:135]
	v_lshl_add_u64 v[136:137], s[10:11], 0, v[134:135]
	v_lshl_add_u64 v[134:135], s[52:53], 0, v[134:135]
	s_mov_b32 s5, 0x6484000
	v_lshl_add_u64 v[150:151], v[136:137], 0, v[130:131]
	v_lshl_add_u64 v[152:153], v[134:135], 0, v[130:131]
	v_add_co_u32_e32 v130, vcc, s5, v132
	s_mov_b64 s[10:11], 0x20000
	s_nop 0
	v_addc_co_u32_e32 v131, vcc, 0, v133, vcc
	v_add_co_u32_e32 v156, vcc, s13, v150
	global_load_dwordx4 v[134:137], v[130:131], off
	s_nop 0
	global_load_dwordx4 v[130:133], v[154:155], off offset:16
	global_load_dwordx4 v[166:169], v[150:151], off offset:16
	global_load_dwordx4 v[170:173], v[150:151], off
	v_lshl_add_u64 v[158:159], v[150:151], 0, s[10:11]
	v_addc_co_u32_e32 v157, vcc, 0, v151, vcc
	s_mov_b32 s5, 0x40000
	global_load_dwordx4 v[174:177], v[156:157], off
	global_load_dwordx4 v[178:181], v[158:159], off offset:16
	s_mov_b64 s[10:11], 0x40000
	v_add_co_u32_e32 v158, vcc, s5, v150
	v_lshl_add_u64 v[160:161], v[150:151], 0, s[10:11]
	s_nop 0
	v_addc_co_u32_e32 v159, vcc, 0, v151, vcc
	s_mov_b32 s7, 0x60000
	global_load_dwordx4 v[182:185], v[158:159], off
	global_load_dwordx4 v[186:189], v[160:161], off offset:16
	s_mov_b64 s[10:11], 0x60000
	v_add_co_u32_e32 v160, vcc, s7, v150
	v_lshl_add_u64 v[206:207], v[150:151], 0, s[10:11]
	s_nop 0
	v_addc_co_u32_e32 v161, vcc, 0, v151, vcc
	global_load_dwordx4 v[190:193], v[160:161], off
	s_nop 0
	global_load_dwordx4 v[206:209], v[206:207], off offset:16
	v_readlane_b32 s21, v252, 1
	v_readlane_b32 s22, v252, 2
	v_readlane_b32 s23, v252, 3
	v_readlane_b32 s24, v252, 4
	v_readlane_b32 s25, v252, 5
	s_waitcnt vmcnt(0)
	v_pk_fma_f32 v[124:125], v[124:125], v[132:133], v[168:169]
	v_pk_fma_f32 v[122:123], v[122:123], v[130:131], v[166:167]
	global_store_dwordx4 v[152:153], v[122:125], off offset:16
	v_pk_fma_f32 v[128:129], v[128:129], v[136:137], v[172:173]
	v_pk_fma_f32 v[126:127], v[126:127], v[134:135], v[170:171]
	v_pk_fma_f32 v[122:123], v[120:121], v[136:137], v[176:177]
	v_pk_fma_f32 v[120:121], v[118:119], v[134:135], v[174:175]
	v_add_co_u32_e32 v118, vcc, s13, v152
	v_pk_fma_f32 v[116:117], v[116:117], v[132:133], v[180:181]
	s_nop 0
	v_addc_co_u32_e32 v119, vcc, 0, v153, vcc
	v_pk_fma_f32 v[114:115], v[114:115], v[130:131], v[178:179]
	global_store_dwordx4 v[118:119], v[114:117], off offset:16
	v_pk_fma_f32 v[108:109], v[108:109], v[132:133], v[188:189]
	v_pk_fma_f32 v[106:107], v[106:107], v[130:131], v[186:187]
	v_pk_fma_f32 v[114:115], v[112:113], v[136:137], v[184:185]
	v_pk_fma_f32 v[112:113], v[110:111], v[134:135], v[182:183]
	v_add_co_u32_e32 v110, vcc, s5, v152
	global_store_dwordx4 v[152:153], v[126:129], off
	s_nop 0
	v_addc_co_u32_e32 v111, vcc, 0, v153, vcc
	global_store_dwordx4 v[110:111], v[106:109], off offset:16
	v_pk_fma_f32 v[100:101], v[100:101], v[132:133], v[208:209]
	v_pk_fma_f32 v[98:99], v[98:99], v[130:131], v[206:207]
	v_pk_fma_f32 v[106:107], v[104:105], v[136:137], v[192:193]
	v_pk_fma_f32 v[104:105], v[102:103], v[134:135], v[190:191]
	v_add_co_u32_e32 v102, vcc, s7, v152
	global_store_dwordx4 v[118:119], v[120:123], off
	s_nop 0
	v_addc_co_u32_e32 v103, vcc, 0, v153, vcc
	global_store_dwordx4 v[110:111], v[112:115], off
	global_store_dwordx4 v[102:103], v[104:107], off
	global_store_dwordx4 v[102:103], v[98:101], off offset:16
	s_mov_b32 s5, 0x100000
	s_mov_b64 s[10:11], 0x100000
	v_add_co_u32_e32 v98, vcc, s5, v150
	v_lshl_add_u64 v[100:101], v[150:151], 0, s[10:11]
	s_nop 0
	v_addc_co_u32_e32 v99, vcc, 0, v151, vcc
	global_load_dwordx4 v[112:115], v[98:99], off
	global_load_dwordx4 v[120:123], v[100:101], off offset:16
	s_mov_b64 s[10:11], 0x120000
	v_add_co_u32_e32 v100, vcc, s45, v150
	v_lshl_add_u64 v[104:105], v[150:151], 0, s[10:11]
	s_nop 0
	v_addc_co_u32_e32 v101, vcc, 0, v151, vcc
	s_mov_b64 s[10:11], 0x140000
	s_mov_b32 s7, 0x140000
	global_load_dwordx4 v[124:127], v[100:101], off
	global_load_dwordx4 v[166:169], v[104:105], off offset:16
	v_lshl_add_u64 v[106:107], v[150:151], 0, s[10:11]
	v_add_co_u32_e32 v104, vcc, s7, v150
	s_mov_b64 s[10:11], 0x160000
	s_nop 0
	v_addc_co_u32_e32 v105, vcc, 0, v151, vcc
	v_lshl_add_u64 v[108:109], v[150:151], 0, s[10:11]
	s_mov_b32 s10, 0x160000
	global_load_dwordx4 v[170:173], v[104:105], off
	global_load_dwordx4 v[174:177], v[106:107], off offset:16
	v_add_co_u32_e32 v106, vcc, s10, v150
	s_waitcnt vmcnt(0)
	v_pk_fma_f32 v[112:113], v[94:95], v[134:135], v[112:113]
	v_addc_co_u32_e32 v107, vcc, 0, v151, vcc
	global_load_dwordx4 v[178:181], v[106:107], off
	global_load_dwordx4 v[182:185], v[108:109], off offset:16
	v_add_co_u32_e32 v94, vcc, s5, v152
	v_pk_fma_f32 v[92:93], v[92:93], v[132:133], v[122:123]
	s_nop 0
	v_addc_co_u32_e32 v95, vcc, 0, v153, vcc
	v_pk_fma_f32 v[90:91], v[90:91], v[130:131], v[120:121]
	global_store_dwordx4 v[94:95], v[90:93], off offset:16
	v_pk_fma_f32 v[84:85], v[84:85], v[132:133], v[168:169]
	v_pk_fma_f32 v[82:83], v[82:83], v[130:131], v[166:167]
	v_pk_fma_f32 v[90:91], v[88:89], v[136:137], v[126:127]
	v_pk_fma_f32 v[88:89], v[86:87], v[134:135], v[124:125]
	v_add_co_u32_e32 v86, vcc, s45, v152
	v_pk_fma_f32 v[114:115], v[96:97], v[136:137], v[114:115]
	s_nop 0
	v_addc_co_u32_e32 v87, vcc, 0, v153, vcc
	global_store_dwordx4 v[86:87], v[82:85], off offset:16
	v_pk_fma_f32 v[76:77], v[76:77], v[132:133], v[176:177]
	v_pk_fma_f32 v[74:75], v[74:75], v[130:131], v[174:175]
	v_pk_fma_f32 v[82:83], v[80:81], v[136:137], v[172:173]
	v_pk_fma_f32 v[80:81], v[78:79], v[134:135], v[170:171]
	v_add_co_u32_e32 v78, vcc, s7, v152
	global_store_dwordx4 v[94:95], v[112:115], off
	s_nop 0
	v_addc_co_u32_e32 v79, vcc, 0, v153, vcc
	global_store_dwordx4 v[78:79], v[74:77], off offset:16
	global_store_dwordx4 v[86:87], v[88:91], off
	global_store_dwordx4 v[78:79], v[80:83], off
	v_add_co_u32_e32 v74, vcc, s10, v152
	s_waitcnt vmcnt(0)
	v_pk_fma_f32 v[72:73], v[72:73], v[136:137], v[180:181]
	v_pk_fma_f32 v[70:71], v[70:71], v[134:135], v[178:179]
	v_addc_co_u32_e32 v75, vcc, 0, v153, vcc
	v_pk_fma_f32 v[68:69], v[68:69], v[132:133], v[184:185]
	v_pk_fma_f32 v[66:67], v[66:67], v[130:131], v[182:183]
	global_store_dwordx4 v[74:75], v[70:73], off
	global_store_dwordx4 v[74:75], v[66:69], off offset:16
	s_mov_b64 s[10:11], 0x20200
	v_lshl_add_u64 v[76:77], v[150:151], 0, s[10:11]
	s_mov_b64 s[10:11], 0x40200
	global_load_dwordx4 v[80:83], v[150:151], off offset:512
	global_load_dwordx4 v[70:73], v[154:155], off offset:512
	global_load_dwordx4 v[66:69], v[154:155], off offset:528
	global_load_dwordx4 v[88:91], v[150:151], off offset:528
	global_load_dwordx4 v[112:115], v[156:157], off offset:512
	global_load_dwordx4 v[120:123], v[158:159], off offset:512
	global_load_dwordx4 v[124:127], v[76:77], off offset:16
	v_lshl_add_u64 v[76:77], v[150:151], 0, s[10:11]
	s_mov_b64 s[10:11], 0x60200
	global_load_dwordx4 v[128:131], v[76:77], off offset:16
	global_load_dwordx4 v[132:135], v[160:161], off offset:512
	v_lshl_add_u64 v[76:77], v[150:151], 0, s[10:11]
	global_load_dwordx4 v[154:157], v[76:77], off offset:16
	s_waitcnt vmcnt(0)
	v_pk_fma_f32 v[64:65], v[64:65], v[72:73], v[82:83]
	v_pk_fma_f32 v[62:63], v[62:63], v[70:71], v[80:81]
	v_pk_fma_f32 v[60:61], v[60:61], v[68:69], v[90:91]
	v_pk_fma_f32 v[58:59], v[58:59], v[66:67], v[88:89]
	v_pk_fma_f32 v[52:53], v[52:53], v[72:73], v[122:123]
	v_pk_fma_f32 v[50:51], v[50:51], v[70:71], v[120:121]
	v_pk_fma_f32 v[48:49], v[48:49], v[68:69], v[126:127]
	v_pk_fma_f32 v[46:47], v[46:47], v[66:67], v[124:125]
	v_pk_fma_f32 v[56:57], v[56:57], v[72:73], v[114:115]
	v_pk_fma_f32 v[54:55], v[54:55], v[70:71], v[112:113]
	global_store_dwordx4 v[152:153], v[62:65], off offset:512
	global_store_dwordx4 v[152:153], v[58:61], off offset:528
	global_store_dwordx4 v[118:119], v[54:57], off offset:512
	global_store_dwordx4 v[110:111], v[50:53], off offset:512
	v_pk_fma_f32 v[44:45], v[44:45], v[68:69], v[130:131]
	v_pk_fma_f32 v[42:43], v[42:43], v[66:67], v[128:129]
	v_pk_fma_f32 v[40:41], v[40:41], v[72:73], v[134:135]
	v_pk_fma_f32 v[38:39], v[38:39], v[70:71], v[132:133]
	v_pk_fma_f32 v[36:37], v[36:37], v[68:69], v[156:157]
	v_pk_fma_f32 v[34:35], v[34:35], v[66:67], v[154:155]
	global_store_dwordx4 v[118:119], v[46:49], off offset:528
	global_store_dwordx4 v[110:111], v[42:45], off offset:528
	global_store_dwordx4 v[102:103], v[38:41], off offset:512
	global_store_dwordx4 v[102:103], v[34:37], off offset:528
	s_mov_b64 s[10:11], 0x100200
	v_lshl_add_u64 v[50:51], v[150:151], 0, s[10:11]
	s_mov_b64 s[10:11], 0x120200
	v_lshl_add_u64 v[54:55], v[150:151], 0, s[10:11]
	s_mov_b64 s[10:11], 0x140200
	v_lshl_add_u64 v[58:59], v[150:151], 0, s[10:11]
	s_mov_b64 s[10:11], 0x160200
	global_load_dwordx4 v[34:37], v[98:99], off offset:512
	global_load_dwordx4 v[38:41], v[100:101], off offset:512
	global_load_dwordx4 v[42:45], v[104:105], off offset:512
	global_load_dwordx4 v[46:49], v[106:107], off offset:512
	v_lshl_add_u64 v[62:63], v[150:151], 0, s[10:11]
	global_load_dwordx4 v[50:53], v[50:51], off offset:16
	s_waitcnt vmcnt(0)
	v_pk_fma_f32 v[32:33], v[32:33], v[72:73], v[36:37]
	global_load_dwordx4 v[54:57], v[54:55], off offset:16
	v_pk_fma_f32 v[30:31], v[30:31], v[70:71], v[34:35]
	global_load_dwordx4 v[58:61], v[58:59], off offset:16
	v_pk_fma_f32 v[28:29], v[28:29], v[72:73], v[40:41]
	global_load_dwordx4 v[62:65], v[62:63], off offset:16
	v_pk_fma_f32 v[26:27], v[26:27], v[70:71], v[38:39]
	v_pk_fma_f32 v[24:25], v[24:25], v[72:73], v[44:45]
	v_pk_fma_f32 v[22:23], v[22:23], v[70:71], v[42:43]
	v_pk_fma_f32 v[12:13], v[12:13], v[72:73], v[48:49]
	v_pk_fma_f32 v[10:11], v[10:11], v[70:71], v[46:47]
	v_pk_fma_f32 v[20:21], v[20:21], v[68:69], v[52:53]
	v_pk_fma_f32 v[18:19], v[18:19], v[66:67], v[50:51]
	global_store_dwordx4 v[94:95], v[30:33], off offset:512
	global_store_dwordx4 v[86:87], v[26:29], off offset:512
	global_store_dwordx4 v[78:79], v[22:25], off offset:512
	global_store_dwordx4 v[74:75], v[10:13], off offset:512
	s_waitcnt vmcnt(0)
	v_pk_fma_f32 v[16:17], v[16:17], v[68:69], v[56:57]
	v_pk_fma_f32 v[14:15], v[14:15], v[66:67], v[54:55]
	v_pk_fma_f32 v[8:9], v[8:9], v[68:69], v[60:61]
	v_pk_fma_f32 v[6:7], v[6:7], v[66:67], v[58:59]
	v_pk_fma_f32 v[4:5], v[4:5], v[68:69], v[64:65]
	v_pk_fma_f32 v[2:3], v[2:3], v[66:67], v[62:63]
	global_store_dwordx4 v[94:95], v[18:21], off offset:528
	global_store_dwordx4 v[86:87], v[14:17], off offset:528
	global_store_dwordx4 v[78:79], v[6:9], off offset:528
	global_store_dwordx4 v[74:75], v[2:5], off offset:528
	s_and_b64 vcc, exec, s[0:1]
	s_mov_b32 s40, s6
	s_mov_b32 s28, s4
	s_mov_b64 s[54:55], s[34:35]
	s_mov_b64 s[52:53], s[8:9]
	s_cbranch_vccz .LBB0_501
	s_waitcnt vmcnt(0)
	v_readlane_b32 s28, v250, 12
	v_readlane_b32 s26, v250, 15
	s_cmpk_gt_u32 s12, 0xff
	v_readlane_b32 s29, v250, 13
	v_readlane_b32 s27, v250, 16
	s_mov_b32 s70, 0x800000
	v_readlane_b32 s79, v250, 18
	s_cbranch_scc1 .LBB0_508
	s_barrier
